# nt cache policy on further read-once / last-use loads: residual tiles in GEMM epilogues, gate tiles, partial slabs, final-norm rows, K/V cache
# speedup vs baseline: 1.0599x; 1.0024x over previous
.LBB0_446:
	v_mov_b32_e32 v128, v155
	v_mov_b32_e32 v129, v156
	s_add_i32 s12, s88, s66
	v_add_u32_e32 v128, s12, v128
	v_mov_b64_e32 v[132:133], s[8:9]
	v_mad_i64_i32 v[132:133], s[40:41], v128, s70, v[132:133]
	s_lshl_b32 s12, s87, 1
	s_and_b32 s40, s12, 0xffffff00
	v_lshl_add_u32 v130, v129, 3, s67
	s_ashr_i32 s41, s40, 31
	v_lshl_add_u64 v[132:133], s[40:41], 1, v[132:133]
	v_ashrrev_i32_e32 v131, 31, v130
	v_lshl_add_u64 v[132:133], v[130:131], 1, v[132:133]
	v_add_co_u32_e32 v134, vcc, s65, v132
	v_ashrrev_i32_e32 v129, 31, v128
	s_nop 0
	v_addc_co_u32_e32 v135, vcc, 0, v133, vcc
	flat_load_dwordx4 v[134:137], v[134:135] offset:2304 nt
	v_add_u32_e32 v130, s87, v130
	v_lshlrev_b64 v[138:139], 12, v[128:129]
	v_ashrrev_i32_e32 v131, 31, v130
	v_lshl_add_u64 v[138:139], s[10:11], 0, v[138:139]
	v_lshlrev_b64 v[130:131], 1, v[130:131]
	v_lshl_add_u64 v[138:139], v[138:139], 0, v[130:131]
	v_lshl_add_u64 v[152:153], v[132:133], 0, s[44:45]
	s_waitcnt vmcnt(0) lgkmcnt(0)
	global_load_dwordx4 v[232:235], v[152:153], off offset:512 nt
	v_add_co_u32_e32 v198, vcc, s71, v132
	s_nop 1
	v_addc_co_u32_e32 v199, vcc, 0, v133, vcc
	global_load_dwordx4 v[236:239], v[198:199], off offset:2304 nt
	v_add_co_u32_e32 v198, vcc, s71, v132
	s_nop 1
	v_addc_co_u32_e32 v199, vcc, 0, v133, vcc
	global_load_dwordx4 v[240:243], v[198:199], off offset:2816 nt
	v_add_co_u32_e32 v198, vcc, s72, v132
	s_nop 1
	v_addc_co_u32_e32 v199, vcc, 0, v133, vcc
	global_load_dwordx4 v[244:247], v[198:199], off offset:2304 nt
	v_add_co_u32_e32 v198, vcc, s72, v132
	s_nop 1
	v_addc_co_u32_e32 v199, vcc, 0, v133, vcc
	global_load_dwordx4 v[248:251], v[198:199], off offset:2816 nt
	v_add_co_u32_e32 v198, vcc, s73, v132
	s_nop 1
	v_addc_co_u32_e32 v199, vcc, 0, v133, vcc
	global_load_dwordx4 v[252:255], v[198:199], off offset:2304 nt
	v_add_co_u32_e32 v198, vcc, s73, v132
	s_nop 1
	v_addc_co_u32_e32 v199, vcc, 0, v133, vcc
	global_load_dwordx4 v[228:231], v[198:199], off offset:2816 nt
	v_lshlrev_b32_e32 v161, 16, v137
	v_and_b32_e32 v137, 0xffff0000, v137
	v_lshlrev_b32_e32 v129, 16, v134
	v_and_b32_e32 v134, 0xffff0000, v134
	v_lshlrev_b32_e32 v159, 16, v135
	v_and_b32_e32 v135, 0xffff0000, v135
	v_lshlrev_b32_e32 v160, 16, v136
	v_and_b32_e32 v136, 0xffff0000, v136
	v_mul_f32_e32 v123, v123, v137
	v_mul_f32_e32 v124, v124, v129
	v_mul_f32_e32 v125, v125, v134
	v_mul_f32_e32 v126, v126, v159
	v_mul_f32_e32 v127, v127, v135
	v_mul_f32_e32 v129, v120, v160
	v_mul_f32_e32 v134, v121, v136
	v_mul_f32_e32 v135, v122, v161
	v_cvt_pk_bf16_f32 v120, v124, v125
	v_cvt_pk_bf16_f32 v121, v126, v127
	v_cvt_pk_bf16_f32 v122, v129, v134
	v_cvt_pk_bf16_f32 v123, v135, v123
	flat_store_dwordx4 v[138:139], v[120:123]
	v_add_co_u32_e32 v124, vcc, s71, v132
	s_waitcnt vmcnt(7) lgkmcnt(0)
	s_nop 1
	v_mov_b32_e32 v120, v232
	v_mov_b32_e32 v121, v233
	v_mov_b32_e32 v122, v234
	v_mov_b32_e32 v123, v235
	v_lshlrev_b32_e32 v134, 16, v123
	v_and_b32_e32 v123, 0xffff0000, v123
	v_lshlrev_b32_e32 v126, 16, v120
	v_and_b32_e32 v120, 0xffff0000, v120
	v_lshlrev_b32_e32 v127, 16, v121
	v_and_b32_e32 v121, 0xffff0000, v121
	v_lshlrev_b32_e32 v129, 16, v122
	v_and_b32_e32 v122, 0xffff0000, v122
	v_mul_f32_e32 v115, v115, v123
	v_addc_co_u32_e32 v125, vcc, 0, v133, vcc
	v_add_co_u32_e32 v198, vcc, s74, v132
	s_nop 1
	v_addc_co_u32_e32 v199, vcc, 0, v133, vcc
	global_load_dwordx4 v[232:235], v[198:199], off offset:2304 nt
	v_mul_f32_e32 v116, v116, v126
	v_mul_f32_e32 v117, v117, v120
	v_mul_f32_e32 v118, v118, v127
	v_mul_f32_e32 v119, v119, v121
	v_mul_f32_e32 v120, v112, v129
	v_mul_f32_e32 v121, v113, v122
	v_mul_f32_e32 v122, v114, v134
	v_cvt_pk_bf16_f32 v112, v116, v117
	v_cvt_pk_bf16_f32 v113, v118, v119
	v_cvt_pk_bf16_f32 v114, v120, v121
	v_cvt_pk_bf16_f32 v115, v122, v115
	flat_store_dwordx4 v[138:139], v[112:115] offset:256
	v_add_u32_e32 v116, 16, v128
	v_ashrrev_i32_e32 v117, 31, v116
	v_lshlrev_b64 v[116:117], 12, v[116:117]
	v_lshl_add_u64 v[116:117], s[10:11], 0, v[116:117]
	v_lshl_add_u64 v[116:117], v[116:117], 0, v[130:131]
	s_waitcnt vmcnt(8) lgkmcnt(0)
	s_nop 1
	v_mov_b32_e32 v112, v236
	v_mov_b32_e32 v113, v237
	v_mov_b32_e32 v114, v238
	v_mov_b32_e32 v115, v239
	v_add_co_u32_e32 v198, vcc, s74, v132
	s_nop 1
	v_addc_co_u32_e32 v199, vcc, 0, v133, vcc
	global_load_dwordx4 v[236:239], v[198:199], off offset:2816 nt
	v_lshlrev_b32_e32 v121, 16, v115
	v_and_b32_e32 v115, 0xffff0000, v115
	v_lshlrev_b32_e32 v118, 16, v112
	v_and_b32_e32 v112, 0xffff0000, v112
	v_lshlrev_b32_e32 v119, 16, v113
	v_and_b32_e32 v113, 0xffff0000, v113
	v_lshlrev_b32_e32 v120, 16, v114
	v_and_b32_e32 v114, 0xffff0000, v114
	v_mul_f32_e32 v107, v107, v115
	v_mul_f32_e32 v108, v108, v118
	v_mul_f32_e32 v109, v109, v112
	v_mul_f32_e32 v110, v110, v119
	v_mul_f32_e32 v111, v111, v113
	v_mul_f32_e32 v112, v104, v120
	v_mul_f32_e32 v113, v105, v114
	v_mul_f32_e32 v114, v106, v121
	v_cvt_pk_bf16_f32 v104, v108, v109
	v_cvt_pk_bf16_f32 v105, v110, v111
	v_cvt_pk_bf16_f32 v106, v112, v113
	v_cvt_pk_bf16_f32 v107, v114, v107
	flat_store_dwordx4 v[116:117], v[104:107]
	v_add_co_u32_e32 v108, vcc, s72, v132
	s_waitcnt vmcnt(9) lgkmcnt(0)
	s_nop 1
	v_mov_b32_e32 v104, v240
	v_mov_b32_e32 v105, v241
	v_mov_b32_e32 v106, v242
	v_mov_b32_e32 v107, v243
	v_lshlrev_b32_e32 v113, 16, v107
	v_and_b32_e32 v107, 0xffff0000, v107
	v_lshlrev_b32_e32 v110, 16, v104
	v_and_b32_e32 v104, 0xffff0000, v104
	v_lshlrev_b32_e32 v111, 16, v105
	v_and_b32_e32 v105, 0xffff0000, v105
	v_lshlrev_b32_e32 v112, 16, v106
	v_and_b32_e32 v106, 0xffff0000, v106
	v_mul_f32_e32 v99, v99, v107
	v_addc_co_u32_e32 v109, vcc, 0, v133, vcc
	v_add_co_u32_e32 v198, vcc, s75, v132
	s_nop 1
	v_addc_co_u32_e32 v199, vcc, 0, v133, vcc
	global_load_dwordx4 v[240:243], v[198:199], off offset:2304 nt
	v_mul_f32_e32 v100, v100, v110
	v_mul_f32_e32 v101, v101, v104
	v_mul_f32_e32 v102, v102, v111
	v_mul_f32_e32 v103, v103, v105
	v_mul_f32_e32 v104, v96, v112
	v_mul_f32_e32 v105, v97, v106
	v_mul_f32_e32 v106, v98, v113
	v_cvt_pk_bf16_f32 v96, v100, v101
	v_cvt_pk_bf16_f32 v97, v102, v103
	v_cvt_pk_bf16_f32 v98, v104, v105
	v_cvt_pk_bf16_f32 v99, v106, v99
	flat_store_dwordx4 v[116:117], v[96:99] offset:256
	v_add_u32_e32 v100, 32, v128
	v_ashrrev_i32_e32 v101, 31, v100
	v_lshlrev_b64 v[100:101], 12, v[100:101]
	v_lshl_add_u64 v[100:101], s[10:11], 0, v[100:101]
	v_lshl_add_u64 v[100:101], v[100:101], 0, v[130:131]
	s_waitcnt vmcnt(10) lgkmcnt(0)
	s_nop 1
	v_mov_b32_e32 v96, v244
	v_mov_b32_e32 v97, v245
	v_mov_b32_e32 v98, v246
	v_mov_b32_e32 v99, v247
	v_add_co_u32_e32 v198, vcc, s75, v132
	s_nop 1
	v_addc_co_u32_e32 v199, vcc, 0, v133, vcc
	global_load_dwordx4 v[244:247], v[198:199], off offset:2816 nt
	v_lshlrev_b32_e32 v105, 16, v99
	v_and_b32_e32 v99, 0xffff0000, v99
	v_lshlrev_b32_e32 v102, 16, v96
	v_and_b32_e32 v96, 0xffff0000, v96
	v_lshlrev_b32_e32 v103, 16, v97
	v_and_b32_e32 v97, 0xffff0000, v97
	v_lshlrev_b32_e32 v104, 16, v98
	v_and_b32_e32 v98, 0xffff0000, v98
	v_mul_f32_e32 v91, v91, v99
	v_mul_f32_e32 v92, v92, v102
	v_mul_f32_e32 v93, v93, v96
	v_mul_f32_e32 v94, v94, v103
	v_mul_f32_e32 v95, v95, v97
	v_mul_f32_e32 v96, v88, v104
	v_mul_f32_e32 v97, v89, v98
	v_mul_f32_e32 v98, v90, v105
	v_cvt_pk_bf16_f32 v88, v92, v93
	v_cvt_pk_bf16_f32 v89, v94, v95
	v_cvt_pk_bf16_f32 v90, v96, v97
	v_cvt_pk_bf16_f32 v91, v98, v91
	flat_store_dwordx4 v[100:101], v[88:91]
	v_add_co_u32_e32 v92, vcc, s73, v132
	s_waitcnt vmcnt(11) lgkmcnt(0)
	s_nop 1
	v_mov_b32_e32 v88, v248
	v_mov_b32_e32 v89, v249
	v_mov_b32_e32 v90, v250
	v_mov_b32_e32 v91, v251
	v_lshlrev_b32_e32 v97, 16, v91
	v_and_b32_e32 v91, 0xffff0000, v91
	v_lshlrev_b32_e32 v94, 16, v88
	v_and_b32_e32 v88, 0xffff0000, v88
	v_lshlrev_b32_e32 v95, 16, v89
	v_and_b32_e32 v89, 0xffff0000, v89
	v_lshlrev_b32_e32 v96, 16, v90
	v_and_b32_e32 v90, 0xffff0000, v90
	v_mul_f32_e32 v83, v83, v91
	v_addc_co_u32_e32 v93, vcc, 0, v133, vcc
	v_add_co_u32_e32 v198, vcc, s76, v132
	s_nop 1
	v_addc_co_u32_e32 v199, vcc, 0, v133, vcc
	global_load_dwordx4 v[248:251], v[198:199], off offset:2304 nt
	v_mul_f32_e32 v84, v84, v94
	v_mul_f32_e32 v85, v85, v88
	v_mul_f32_e32 v86, v86, v95
	v_mul_f32_e32 v87, v87, v89
	v_mul_f32_e32 v88, v80, v96
	v_mul_f32_e32 v89, v81, v90
	v_mul_f32_e32 v90, v82, v97
	v_cvt_pk_bf16_f32 v80, v84, v85
	v_cvt_pk_bf16_f32 v81, v86, v87
	v_cvt_pk_bf16_f32 v82, v88, v89
	v_cvt_pk_bf16_f32 v83, v90, v83
	flat_store_dwordx4 v[100:101], v[80:83] offset:256
	v_add_u32_e32 v84, 48, v128
	v_ashrrev_i32_e32 v85, 31, v84
	v_lshlrev_b64 v[84:85], 12, v[84:85]
	v_lshl_add_u64 v[84:85], s[10:11], 0, v[84:85]
	v_lshl_add_u64 v[84:85], v[84:85], 0, v[130:131]
	s_waitcnt vmcnt(12) lgkmcnt(0)
	s_nop 1
	v_mov_b32_e32 v80, v252
	v_mov_b32_e32 v81, v253
	v_mov_b32_e32 v82, v254
	v_mov_b32_e32 v83, v255
	v_add_co_u32_e32 v198, vcc, s76, v132
	s_nop 1
	v_addc_co_u32_e32 v199, vcc, 0, v133, vcc
	global_load_dwordx4 v[252:255], v[198:199], off offset:2816 nt
	v_lshlrev_b32_e32 v89, 16, v83
	v_and_b32_e32 v83, 0xffff0000, v83
	v_lshlrev_b32_e32 v86, 16, v80
	v_and_b32_e32 v80, 0xffff0000, v80
	v_lshlrev_b32_e32 v87, 16, v81
	v_and_b32_e32 v81, 0xffff0000, v81
	v_lshlrev_b32_e32 v88, 16, v82
	v_and_b32_e32 v82, 0xffff0000, v82
	v_mul_f32_e32 v75, v75, v83
	v_mul_f32_e32 v76, v76, v86
	v_mul_f32_e32 v77, v77, v80
	v_mul_f32_e32 v78, v78, v87
	v_mul_f32_e32 v79, v79, v81
	v_mul_f32_e32 v80, v72, v88
	v_mul_f32_e32 v81, v73, v82
	v_mul_f32_e32 v82, v74, v89
	v_cvt_pk_bf16_f32 v72, v76, v77
	v_cvt_pk_bf16_f32 v73, v78, v79
	v_cvt_pk_bf16_f32 v74, v80, v81
	v_cvt_pk_bf16_f32 v75, v82, v75
	flat_store_dwordx4 v[84:85], v[72:75]
	v_add_co_u32_e32 v76, vcc, s74, v132
	s_waitcnt vmcnt(13) lgkmcnt(0)
	s_nop 1
	v_mov_b32_e32 v72, v228
	v_mov_b32_e32 v73, v229
	v_mov_b32_e32 v74, v230
	v_mov_b32_e32 v75, v231
	v_lshlrev_b32_e32 v81, 16, v75
	v_and_b32_e32 v75, 0xffff0000, v75
	v_lshlrev_b32_e32 v78, 16, v72
	v_and_b32_e32 v72, 0xffff0000, v72
	v_lshlrev_b32_e32 v79, 16, v73
	v_and_b32_e32 v73, 0xffff0000, v73
	v_lshlrev_b32_e32 v80, 16, v74
	v_and_b32_e32 v74, 0xffff0000, v74
	v_mul_f32_e32 v67, v67, v75
	v_addc_co_u32_e32 v77, vcc, 0, v133, vcc
	v_add_co_u32_e32 v198, vcc, s79, v132
	s_nop 1
	v_addc_co_u32_e32 v199, vcc, 0, v133, vcc
	global_load_dwordx4 v[228:231], v[198:199], off offset:2304 nt
	v_mul_f32_e32 v68, v68, v78
	v_mul_f32_e32 v69, v69, v72
	v_mul_f32_e32 v70, v70, v79
	v_mul_f32_e32 v71, v71, v73
	v_mul_f32_e32 v72, v64, v80
	v_mul_f32_e32 v73, v65, v74
	v_mul_f32_e32 v74, v66, v81
	v_cvt_pk_bf16_f32 v64, v68, v69
	v_cvt_pk_bf16_f32 v65, v70, v71
	v_cvt_pk_bf16_f32 v66, v72, v73
	v_cvt_pk_bf16_f32 v67, v74, v67
	flat_store_dwordx4 v[84:85], v[64:67] offset:256
	v_add_u32_e32 v68, 0x80, v128
	v_ashrrev_i32_e32 v69, 31, v68
	v_lshlrev_b64 v[68:69], 12, v[68:69]
	v_lshl_add_u64 v[68:69], s[10:11], 0, v[68:69]
	v_lshl_add_u64 v[68:69], v[68:69], 0, v[130:131]
	s_waitcnt vmcnt(13) lgkmcnt(0)
	s_nop 1
	v_mov_b32_e32 v64, v232
	v_mov_b32_e32 v65, v233
	v_mov_b32_e32 v66, v234
	v_mov_b32_e32 v67, v235
	v_add_co_u32_e32 v198, vcc, s79, v132
	s_nop 1
	v_addc_co_u32_e32 v199, vcc, 0, v133, vcc
	global_load_dwordx4 v[232:235], v[198:199], off offset:2816 nt
	v_lshlrev_b32_e32 v73, 16, v67
	v_and_b32_e32 v67, 0xffff0000, v67
	v_lshlrev_b32_e32 v70, 16, v64
	v_and_b32_e32 v64, 0xffff0000, v64
	v_lshlrev_b32_e32 v71, 16, v65
	v_and_b32_e32 v65, 0xffff0000, v65
	v_lshlrev_b32_e32 v72, 16, v66
	v_and_b32_e32 v66, 0xffff0000, v66
	v_mul_f32_e32 v59, v59, v67
	v_mul_f32_e32 v60, v60, v70
	v_mul_f32_e32 v61, v61, v64
	v_mul_f32_e32 v62, v62, v71
	v_mul_f32_e32 v63, v63, v65
	v_mul_f32_e32 v64, v56, v72
	v_mul_f32_e32 v65, v57, v66
	v_mul_f32_e32 v66, v58, v73
	v_cvt_pk_bf16_f32 v56, v60, v61
	v_cvt_pk_bf16_f32 v57, v62, v63
	v_cvt_pk_bf16_f32 v58, v64, v65
	v_cvt_pk_bf16_f32 v59, v66, v59
	flat_store_dwordx4 v[68:69], v[56:59]
	v_add_co_u32_e32 v60, vcc, s75, v132
	s_waitcnt vmcnt(13) lgkmcnt(0)
	s_nop 1
	v_mov_b32_e32 v56, v236
	v_mov_b32_e32 v57, v237
	v_mov_b32_e32 v58, v238
	v_mov_b32_e32 v59, v239
	v_lshlrev_b32_e32 v65, 16, v59
	v_and_b32_e32 v59, 0xffff0000, v59
	v_lshlrev_b32_e32 v62, 16, v56
	v_and_b32_e32 v56, 0xffff0000, v56
	v_lshlrev_b32_e32 v63, 16, v57
	v_and_b32_e32 v57, 0xffff0000, v57
	v_lshlrev_b32_e32 v64, 16, v58
	v_and_b32_e32 v58, 0xffff0000, v58
	v_mul_f32_e32 v51, v51, v59
	v_addc_co_u32_e32 v61, vcc, 0, v133, vcc
	v_mul_f32_e32 v52, v52, v62
	v_mul_f32_e32 v53, v53, v56
	v_mul_f32_e32 v54, v54, v63
	v_mul_f32_e32 v55, v55, v57
	v_mul_f32_e32 v56, v48, v64
	v_mul_f32_e32 v57, v49, v58
	v_mul_f32_e32 v58, v50, v65
	v_cvt_pk_bf16_f32 v48, v52, v53
	v_cvt_pk_bf16_f32 v49, v54, v55
	v_cvt_pk_bf16_f32 v50, v56, v57
	v_cvt_pk_bf16_f32 v51, v58, v51
	flat_store_dwordx4 v[68:69], v[48:51] offset:256
	v_add_u32_e32 v52, 0x90, v128
	v_ashrrev_i32_e32 v53, 31, v52
	v_lshlrev_b64 v[52:53], 12, v[52:53]
	v_lshl_add_u64 v[52:53], s[10:11], 0, v[52:53]
	v_lshl_add_u64 v[52:53], v[52:53], 0, v[130:131]
	s_waitcnt vmcnt(12) lgkmcnt(0)
	s_nop 1
	v_mov_b32_e32 v48, v240
	v_mov_b32_e32 v49, v241
	v_mov_b32_e32 v50, v242
	v_mov_b32_e32 v51, v243
	v_lshlrev_b32_e32 v57, 16, v51
	v_and_b32_e32 v51, 0xffff0000, v51
	v_lshlrev_b32_e32 v54, 16, v48
	v_and_b32_e32 v48, 0xffff0000, v48
	v_lshlrev_b32_e32 v55, 16, v49
	v_and_b32_e32 v49, 0xffff0000, v49
	v_lshlrev_b32_e32 v56, 16, v50
	v_and_b32_e32 v50, 0xffff0000, v50
	v_mul_f32_e32 v43, v43, v51
	v_mul_f32_e32 v44, v44, v54
	v_mul_f32_e32 v45, v45, v48
	v_mul_f32_e32 v46, v46, v55
	v_mul_f32_e32 v47, v47, v49
	v_mul_f32_e32 v48, v40, v56
	v_mul_f32_e32 v49, v41, v50
	v_mul_f32_e32 v50, v42, v57
	v_cvt_pk_bf16_f32 v40, v44, v45
	v_cvt_pk_bf16_f32 v41, v46, v47
	v_cvt_pk_bf16_f32 v42, v48, v49
	v_cvt_pk_bf16_f32 v43, v50, v43
	flat_store_dwordx4 v[52:53], v[40:43]
	v_add_co_u32_e32 v44, vcc, s76, v132
	s_waitcnt vmcnt(11) lgkmcnt(0)
	s_nop 1
	v_mov_b32_e32 v40, v244
	v_mov_b32_e32 v41, v245
	v_mov_b32_e32 v42, v246
	v_mov_b32_e32 v43, v247
	v_lshlrev_b32_e32 v49, 16, v43
	v_and_b32_e32 v43, 0xffff0000, v43
	v_lshlrev_b32_e32 v46, 16, v40
	v_and_b32_e32 v40, 0xffff0000, v40
	v_lshlrev_b32_e32 v47, 16, v41
	v_and_b32_e32 v41, 0xffff0000, v41
	v_lshlrev_b32_e32 v48, 16, v42
	v_and_b32_e32 v42, 0xffff0000, v42
	v_mul_f32_e32 v35, v35, v43
	v_addc_co_u32_e32 v45, vcc, 0, v133, vcc
	v_mul_f32_e32 v36, v36, v46
	v_mul_f32_e32 v37, v37, v40
	v_mul_f32_e32 v38, v38, v47
	v_mul_f32_e32 v39, v39, v41
	v_mul_f32_e32 v40, v32, v48
	v_mul_f32_e32 v41, v33, v42
	v_mul_f32_e32 v42, v34, v49
	v_cvt_pk_bf16_f32 v32, v36, v37
	v_cvt_pk_bf16_f32 v33, v38, v39
	v_cvt_pk_bf16_f32 v34, v40, v41
	v_cvt_pk_bf16_f32 v35, v42, v35
	flat_store_dwordx4 v[52:53], v[32:35] offset:256
	v_add_u32_e32 v36, 0xa0, v128
	v_ashrrev_i32_e32 v37, 31, v36
	v_lshlrev_b64 v[36:37], 12, v[36:37]
	v_lshl_add_u64 v[36:37], s[10:11], 0, v[36:37]
	v_lshl_add_u64 v[36:37], v[36:37], 0, v[130:131]
	s_waitcnt vmcnt(10) lgkmcnt(0)
	s_nop 1
	v_mov_b32_e32 v32, v248
	v_mov_b32_e32 v33, v249
	v_mov_b32_e32 v34, v250
	v_mov_b32_e32 v35, v251
	v_lshlrev_b32_e32 v41, 16, v35
	v_and_b32_e32 v35, 0xffff0000, v35
	v_lshlrev_b32_e32 v38, 16, v32
	v_and_b32_e32 v32, 0xffff0000, v32
	v_lshlrev_b32_e32 v39, 16, v33
	v_and_b32_e32 v33, 0xffff0000, v33
	v_lshlrev_b32_e32 v40, 16, v34
	v_and_b32_e32 v34, 0xffff0000, v34
	v_mul_f32_e32 v27, v27, v35
	v_mul_f32_e32 v28, v28, v38
	v_mul_f32_e32 v29, v29, v32
	v_mul_f32_e32 v30, v30, v39
	v_mul_f32_e32 v31, v31, v33
	v_mul_f32_e32 v32, v24, v40
	v_mul_f32_e32 v33, v25, v34
	v_mul_f32_e32 v34, v26, v41
	v_cvt_pk_bf16_f32 v24, v28, v29
	v_cvt_pk_bf16_f32 v25, v30, v31
	v_cvt_pk_bf16_f32 v26, v32, v33
	v_cvt_pk_bf16_f32 v27, v34, v27
	flat_store_dwordx4 v[36:37], v[24:27]
	v_add_co_u32_e32 v28, vcc, s79, v132
	s_waitcnt vmcnt(9) lgkmcnt(0)
	s_nop 1
	v_mov_b32_e32 v24, v252
	v_mov_b32_e32 v25, v253
	v_mov_b32_e32 v26, v254
	v_mov_b32_e32 v27, v255
	v_lshlrev_b32_e32 v33, 16, v27
	v_and_b32_e32 v27, 0xffff0000, v27
	v_lshlrev_b32_e32 v30, 16, v24
	v_and_b32_e32 v24, 0xffff0000, v24
	v_lshlrev_b32_e32 v31, 16, v25
	v_and_b32_e32 v25, 0xffff0000, v25
	v_lshlrev_b32_e32 v32, 16, v26
	v_and_b32_e32 v26, 0xffff0000, v26
	v_mul_f32_e32 v19, v19, v27
	v_addc_co_u32_e32 v29, vcc, 0, v133, vcc
	v_mul_f32_e32 v20, v20, v30
	v_mul_f32_e32 v21, v21, v24
	v_mul_f32_e32 v22, v22, v31
	v_mul_f32_e32 v23, v23, v25
	v_mul_f32_e32 v24, v16, v32
	v_mul_f32_e32 v25, v17, v26
	v_mul_f32_e32 v26, v18, v33
	v_cvt_pk_bf16_f32 v16, v20, v21
	v_cvt_pk_bf16_f32 v17, v22, v23
	v_cvt_pk_bf16_f32 v18, v24, v25
	v_cvt_pk_bf16_f32 v19, v26, v19
	flat_store_dwordx4 v[36:37], v[16:19] offset:256
	v_add_u32_e32 v20, 0xb0, v128
	v_ashrrev_i32_e32 v21, 31, v20
	v_lshlrev_b64 v[20:21], 12, v[20:21]
	v_lshl_add_u64 v[20:21], s[10:11], 0, v[20:21]
	v_lshl_add_u64 v[20:21], v[20:21], 0, v[130:131]
	s_andn2_b64 vcc, exec, s[50:51]
	s_mov_b64 s[50:51], -1
	s_waitcnt vmcnt(8) lgkmcnt(0)
	s_nop 1
	v_mov_b32_e32 v16, v228
	v_mov_b32_e32 v17, v229
	v_mov_b32_e32 v18, v230
	v_mov_b32_e32 v19, v231
	v_lshlrev_b32_e32 v25, 16, v19
	v_and_b32_e32 v19, 0xffff0000, v19
	v_lshlrev_b32_e32 v22, 16, v16
	v_and_b32_e32 v16, 0xffff0000, v16
	v_lshlrev_b32_e32 v23, 16, v17
	v_and_b32_e32 v17, 0xffff0000, v17
	v_lshlrev_b32_e32 v24, 16, v18
	v_and_b32_e32 v18, 0xffff0000, v18
	v_mul_f32_e32 v11, v11, v19
	v_mul_f32_e32 v12, v12, v22
	v_mul_f32_e32 v13, v13, v16
	v_mul_f32_e32 v14, v14, v23
	v_mul_f32_e32 v15, v15, v17
	v_mul_f32_e32 v16, v8, v24
	v_mul_f32_e32 v17, v9, v18
	v_mul_f32_e32 v18, v10, v25
	v_cvt_pk_bf16_f32 v8, v12, v13
	v_cvt_pk_bf16_f32 v9, v14, v15
	v_cvt_pk_bf16_f32 v10, v16, v17
	v_cvt_pk_bf16_f32 v11, v18, v11
	flat_store_dwordx4 v[20:21], v[8:11]
	s_waitcnt vmcnt(7) lgkmcnt(0)
	s_nop 1
	v_mov_b32_e32 v8, v232
	v_mov_b32_e32 v9, v233
	v_mov_b32_e32 v10, v234
	v_mov_b32_e32 v11, v235
	v_lshlrev_b32_e32 v15, 16, v11
	v_and_b32_e32 v11, 0xffff0000, v11
	v_lshlrev_b32_e32 v12, 16, v8
	v_and_b32_e32 v8, 0xffff0000, v8
	v_lshlrev_b32_e32 v13, 16, v9
	v_and_b32_e32 v9, 0xffff0000, v9
	v_lshlrev_b32_e32 v14, 16, v10
	v_and_b32_e32 v10, 0xffff0000, v10
	v_mul_f32_e32 v3, v3, v11
	v_mul_f32_e32 v4, v4, v12
	v_mul_f32_e32 v5, v5, v8
	v_mul_f32_e32 v6, v6, v13
	v_mul_f32_e32 v7, v7, v9
	v_mul_f32_e32 v8, v0, v14
	v_mul_f32_e32 v9, v1, v10
	v_mul_f32_e32 v10, v2, v15
	v_cvt_pk_bf16_f32 v0, v4, v5
	v_cvt_pk_bf16_f32 v1, v6, v7
	v_cvt_pk_bf16_f32 v2, v8, v9
	v_cvt_pk_bf16_f32 v3, v10, v3
	flat_store_dwordx4 v[20:21], v[0:3] offset:256
	s_cbranch_vccnz .LBB0_436
	s_andn2_b64 vcc, exec, s[6:7]
	s_cbranch_vccnz .LBB0_435
	s_barrier
	s_branch .LBB0_435

.LBB0_566:
	s_add_i32 s8, s58, 0xffffe000
	s_ashr_i32 s59, s58, 31
	s_cmpk_lt_i32 s58, 0x2000
	s_cselect_b32 s13, s59, 0
	s_cselect_b32 s12, s58, s8
	s_waitcnt lgkmcnt(0)
	s_cselect_b32 s8, s5, s7
	s_cselect_b32 s41, s4, s6
	s_lshl_b64 s[12:13], s[12:13], 13
	v_lshl_add_u32 v148, v166, 3, s84
	s_add_u32 s60, s41, s12
	v_ashrrev_i32_e32 v149, 31, v148
	v_lshlrev_b64 v[156:157], 11, v[156:157]
	s_addc_u32 s61, s8, s13
	v_lshl_add_u64 v[156:157], v[156:157], 0, v[148:149]
	s_ashr_i32 s51, s50, 31
	v_lshl_add_u64 v[156:157], v[156:157], 0, s[50:51]
	v_lshl_add_u64 v[174:175], v[156:157], 2, s[60:61]
	global_load_dwordx4 v[166:169], v[174:175], off nt
	global_load_dwordx4 v[170:173], v[174:175], off offset:16 nt
	s_lshl_b64 s[12:13], s[58:59], 12
	s_add_u32 s58, s75, s12
	s_addc_u32 s59, s76, s13
	v_lshl_add_u64 v[156:157], v[156:157], 1, s[58:59]
	v_ashrrev_i32_e32 v155, 31, v154
	v_lshlrev_b64 v[154:155], 11, v[154:155]
	v_lshl_add_u64 v[154:155], v[154:155], 0, v[148:149]
	v_lshl_add_u64 v[154:155], v[154:155], 0, s[50:51]
	v_ashrrev_i32_e32 v153, 31, v152
	v_ashrrev_i32_e32 v151, 31, v150
	v_ashrrev_i32_e32 v147, 31, v146
	v_ashrrev_i32_e32 v145, 31, v144
	v_ashrrev_i32_e32 v143, 31, v142
	v_ashrrev_i32_e32 v141, 31, v140
	global_load_dwordx4 v[184:187], v[174:175], off offset:512 nt
	global_load_dwordx4 v[188:191], v[174:175], off offset:528 nt
	v_lshl_add_u64 v[208:209], v[154:155], 2, s[60:61]
	global_load_dwordx4 v[192:195], v[208:209], off nt
	global_load_dwordx4 v[196:199], v[208:209], off offset:16 nt
	v_lshl_add_u64 v[208:209], v[154:155], 2, s[60:61]
	global_load_dwordx4 v[200:203], v[208:209], off offset:512 nt
	global_load_dwordx4 v[204:207], v[208:209], off offset:528 nt
	s_waitcnt vmcnt(6)
	v_lshlrev_b64 v[208:209], 11, v[152:153]
	v_lshl_add_u64 v[210:211], v[208:209], 0, v[148:149]
	v_lshl_add_u64 v[212:213], v[210:211], 0, s[50:51]
	v_lshl_add_u64 v[214:215], v[212:213], 2, s[60:61]
	global_load_dwordx4 v[176:179], v[214:215], off nt
	global_load_dwordx4 v[180:183], v[214:215], off offset:16 nt
	v_pk_add_f32 v[124:125], v[124:125], v[166:167]
	v_pk_add_f32 v[166:167], v[122:123], v[172:173]
	v_pk_add_f32 v[122:123], v[120:121], v[170:171]
	v_pk_add_f32 v[126:127], v[126:127], v[168:169]
	v_cvt_pk_bf16_f32 v120, v124, v125
	s_nop 0
	v_cvt_pk_bf16_f32 v121, v126, v127
	v_cvt_pk_bf16_f32 v122, v122, v123
	v_cvt_pk_bf16_f32 v123, v166, v167
	flat_store_dwordx4 v[156:157], v[120:123]
	s_nop 0
	v_lshl_add_u64 v[166:167], v[154:155], 2, s[60:61]
	s_waitcnt vmcnt(7)
	s_nop 1
	v_mov_b32_e32 v120, v184
	v_mov_b32_e32 v121, v185
	v_mov_b32_e32 v122, v186
	v_mov_b32_e32 v123, v187
	v_mov_b32_e32 v124, v188
	v_mov_b32_e32 v125, v189
	v_mov_b32_e32 v126, v190
	v_mov_b32_e32 v127, v191
	v_lshlrev_b64 v[208:209], 11, v[152:153]
	v_lshl_add_u64 v[210:211], v[208:209], 0, v[148:149]
	v_lshl_add_u64 v[212:213], v[210:211], 0, s[50:51]
	v_lshl_add_u64 v[214:215], v[212:213], 2, s[60:61]
	global_load_dwordx4 v[184:187], v[214:215], off offset:512 nt
	global_load_dwordx4 v[188:191], v[214:215], off offset:528 nt
	v_pk_add_f32 v[116:117], v[116:117], v[120:121]
	v_pk_add_f32 v[120:121], v[114:115], v[126:127]
	v_pk_add_f32 v[114:115], v[112:113], v[124:125]
	v_pk_add_f32 v[118:119], v[118:119], v[122:123]
	v_cvt_pk_bf16_f32 v112, v116, v117
	s_nop 0
	v_cvt_pk_bf16_f32 v113, v118, v119
	v_cvt_pk_bf16_f32 v114, v114, v115
	v_cvt_pk_bf16_f32 v115, v120, v121
	flat_store_dwordx4 v[156:157], v[112:115] offset:256
	s_nop 0
	v_lshl_add_u64 v[120:121], v[154:155], 1, s[58:59]
	s_waitcnt vmcnt(8)
	s_nop 1
	v_mov_b32_e32 v112, v192
	v_mov_b32_e32 v113, v193
	v_mov_b32_e32 v114, v194
	v_mov_b32_e32 v115, v195
	v_mov_b32_e32 v116, v196
	v_mov_b32_e32 v117, v197
	v_mov_b32_e32 v118, v198
	v_mov_b32_e32 v119, v199
	v_lshlrev_b64 v[208:209], 11, v[150:151]
	v_lshl_add_u64 v[210:211], v[208:209], 0, v[148:149]
	v_lshl_add_u64 v[212:213], v[210:211], 0, s[50:51]
	v_lshl_add_u64 v[214:215], v[212:213], 2, s[60:61]
	global_load_dwordx4 v[192:195], v[214:215], off nt
	global_load_dwordx4 v[196:199], v[214:215], off offset:16 nt
	v_pk_add_f32 v[108:109], v[108:109], v[112:113]
	v_pk_add_f32 v[112:113], v[106:107], v[118:119]
	v_pk_add_f32 v[106:107], v[104:105], v[116:117]
	v_pk_add_f32 v[110:111], v[110:111], v[114:115]
	v_cvt_pk_bf16_f32 v104, v108, v109
	s_nop 0
	v_cvt_pk_bf16_f32 v105, v110, v111
	v_cvt_pk_bf16_f32 v106, v106, v107
	v_cvt_pk_bf16_f32 v107, v112, v113
	flat_store_dwordx4 v[120:121], v[104:107]
	s_nop 0
	v_lshlrev_b64 v[112:113], 11, v[152:153]
	v_lshl_add_u64 v[112:113], v[112:113], 0, v[148:149]
	v_lshl_add_u64 v[112:113], v[112:113], 0, s[50:51]
	v_lshl_add_u64 v[114:115], v[112:113], 2, s[60:61]
	s_waitcnt vmcnt(9)
	s_nop 1
	v_mov_b32_e32 v104, v200
	v_mov_b32_e32 v105, v201
	v_mov_b32_e32 v106, v202
	v_mov_b32_e32 v107, v203
	v_mov_b32_e32 v108, v204
	v_mov_b32_e32 v109, v205
	v_mov_b32_e32 v110, v206
	v_mov_b32_e32 v111, v207
	v_lshlrev_b64 v[208:209], 11, v[150:151]
	v_lshl_add_u64 v[210:211], v[208:209], 0, v[148:149]
	v_lshl_add_u64 v[212:213], v[210:211], 0, s[50:51]
	v_lshl_add_u64 v[214:215], v[212:213], 2, s[60:61]
	global_load_dwordx4 v[200:203], v[214:215], off offset:512 nt
	global_load_dwordx4 v[204:207], v[214:215], off offset:528 nt
	v_pk_add_f32 v[100:101], v[100:101], v[104:105]
	v_pk_add_f32 v[104:105], v[98:99], v[110:111]
	v_pk_add_f32 v[98:99], v[96:97], v[108:109]
	v_pk_add_f32 v[102:103], v[102:103], v[106:107]
	v_cvt_pk_bf16_f32 v96, v100, v101
	s_nop 0
	v_cvt_pk_bf16_f32 v97, v102, v103
	v_cvt_pk_bf16_f32 v98, v98, v99
	v_cvt_pk_bf16_f32 v99, v104, v105
	flat_store_dwordx4 v[120:121], v[96:99] offset:256
	s_nop 0
	v_lshl_add_u64 v[104:105], v[112:113], 1, s[58:59]
	s_waitcnt vmcnt(10)
	s_nop 1
	v_mov_b32_e32 v96, v176
	v_mov_b32_e32 v97, v177
	v_mov_b32_e32 v98, v178
	v_mov_b32_e32 v99, v179
	v_mov_b32_e32 v100, v180
	v_mov_b32_e32 v101, v181
	v_mov_b32_e32 v102, v182
	v_mov_b32_e32 v103, v183
	v_lshlrev_b64 v[208:209], 11, v[146:147]
	v_lshl_add_u64 v[210:211], v[208:209], 0, v[148:149]
	v_lshl_add_u64 v[212:213], v[210:211], 0, s[50:51]
	v_lshl_add_u64 v[214:215], v[212:213], 2, s[60:61]
	global_load_dwordx4 v[176:179], v[214:215], off nt
	global_load_dwordx4 v[180:183], v[214:215], off offset:16 nt
	v_pk_add_f32 v[92:93], v[92:93], v[96:97]
	v_pk_add_f32 v[96:97], v[90:91], v[102:103]
	v_pk_add_f32 v[90:91], v[88:89], v[100:101]
	v_pk_add_f32 v[94:95], v[94:95], v[98:99]
	v_cvt_pk_bf16_f32 v88, v92, v93
	s_nop 0
	v_cvt_pk_bf16_f32 v89, v94, v95
	v_cvt_pk_bf16_f32 v90, v90, v91
	v_cvt_pk_bf16_f32 v91, v96, v97
	flat_store_dwordx4 v[104:105], v[88:91]
	s_nop 0
	v_lshlrev_b64 v[96:97], 11, v[150:151]
	v_lshl_add_u64 v[96:97], v[96:97], 0, v[148:149]
	v_lshl_add_u64 v[96:97], v[96:97], 0, s[50:51]
	v_lshl_add_u64 v[98:99], v[96:97], 2, s[60:61]
	s_waitcnt vmcnt(10)
	s_nop 1
	v_mov_b32_e32 v88, v184
	v_mov_b32_e32 v89, v185
	v_mov_b32_e32 v90, v186
	v_mov_b32_e32 v91, v187
	v_mov_b32_e32 v92, v188
	v_mov_b32_e32 v93, v189
	v_mov_b32_e32 v94, v190
	v_mov_b32_e32 v95, v191
	v_lshlrev_b64 v[208:209], 11, v[146:147]
	v_lshl_add_u64 v[210:211], v[208:209], 0, v[148:149]
	v_lshl_add_u64 v[212:213], v[210:211], 0, s[50:51]
	v_lshl_add_u64 v[214:215], v[212:213], 2, s[60:61]
	global_load_dwordx4 v[184:187], v[214:215], off offset:512 nt
	global_load_dwordx4 v[188:191], v[214:215], off offset:528 nt
	v_pk_add_f32 v[84:85], v[84:85], v[88:89]
	v_pk_add_f32 v[88:89], v[82:83], v[94:95]
	v_pk_add_f32 v[82:83], v[80:81], v[92:93]
	v_pk_add_f32 v[86:87], v[86:87], v[90:91]
	v_cvt_pk_bf16_f32 v80, v84, v85
	s_nop 0
	v_cvt_pk_bf16_f32 v81, v86, v87
	v_cvt_pk_bf16_f32 v82, v82, v83
	v_cvt_pk_bf16_f32 v83, v88, v89
	flat_store_dwordx4 v[104:105], v[80:83] offset:256
	s_nop 0
	v_lshl_add_u64 v[88:89], v[96:97], 1, s[58:59]
	s_waitcnt vmcnt(10)
	s_nop 1
	v_mov_b32_e32 v80, v192
	v_mov_b32_e32 v81, v193
	v_mov_b32_e32 v82, v194
	v_mov_b32_e32 v83, v195
	v_mov_b32_e32 v84, v196
	v_mov_b32_e32 v85, v197
	v_mov_b32_e32 v86, v198
	v_mov_b32_e32 v87, v199
	v_lshlrev_b64 v[208:209], 11, v[144:145]
	v_lshl_add_u64 v[210:211], v[208:209], 0, v[148:149]
	v_lshl_add_u64 v[212:213], v[210:211], 0, s[50:51]
	v_lshl_add_u64 v[214:215], v[212:213], 2, s[60:61]
	global_load_dwordx4 v[192:195], v[214:215], off nt
	global_load_dwordx4 v[196:199], v[214:215], off offset:16 nt
	v_pk_add_f32 v[76:77], v[76:77], v[80:81]
	v_pk_add_f32 v[80:81], v[74:75], v[86:87]
	v_pk_add_f32 v[74:75], v[72:73], v[84:85]
	v_pk_add_f32 v[78:79], v[78:79], v[82:83]
	v_cvt_pk_bf16_f32 v72, v76, v77
	s_nop 0
	v_cvt_pk_bf16_f32 v73, v78, v79
	v_cvt_pk_bf16_f32 v74, v74, v75
	v_cvt_pk_bf16_f32 v75, v80, v81
	flat_store_dwordx4 v[88:89], v[72:75]
	s_nop 0
	v_lshlrev_b64 v[80:81], 11, v[146:147]
	v_lshl_add_u64 v[80:81], v[80:81], 0, v[148:149]
	v_lshl_add_u64 v[80:81], v[80:81], 0, s[50:51]
	v_lshl_add_u64 v[82:83], v[80:81], 2, s[60:61]
	s_waitcnt vmcnt(10)
	s_nop 1
	v_mov_b32_e32 v72, v200
	v_mov_b32_e32 v73, v201
	v_mov_b32_e32 v74, v202
	v_mov_b32_e32 v75, v203
	v_mov_b32_e32 v76, v204
	v_mov_b32_e32 v77, v205
	v_mov_b32_e32 v78, v206
	v_mov_b32_e32 v79, v207
	v_lshlrev_b64 v[208:209], 11, v[144:145]
	v_lshl_add_u64 v[210:211], v[208:209], 0, v[148:149]
	v_lshl_add_u64 v[212:213], v[210:211], 0, s[50:51]
	v_lshl_add_u64 v[214:215], v[212:213], 2, s[60:61]
	global_load_dwordx4 v[200:203], v[214:215], off offset:512 nt
	global_load_dwordx4 v[204:207], v[214:215], off offset:528 nt
	v_pk_add_f32 v[68:69], v[68:69], v[72:73]
	v_pk_add_f32 v[72:73], v[66:67], v[78:79]
	v_pk_add_f32 v[66:67], v[64:65], v[76:77]
	v_pk_add_f32 v[70:71], v[70:71], v[74:75]
	v_cvt_pk_bf16_f32 v64, v68, v69
	s_nop 0
	v_cvt_pk_bf16_f32 v65, v70, v71
	v_cvt_pk_bf16_f32 v66, v66, v67
	v_cvt_pk_bf16_f32 v67, v72, v73
	flat_store_dwordx4 v[88:89], v[64:67] offset:256
	s_nop 0
	v_lshl_add_u64 v[72:73], v[80:81], 1, s[58:59]
	s_waitcnt vmcnt(10)
	s_nop 1
	v_mov_b32_e32 v64, v176
	v_mov_b32_e32 v65, v177
	v_mov_b32_e32 v66, v178
	v_mov_b32_e32 v67, v179
	v_mov_b32_e32 v68, v180
	v_mov_b32_e32 v69, v181
	v_mov_b32_e32 v70, v182
	v_mov_b32_e32 v71, v183
	v_lshlrev_b64 v[208:209], 11, v[142:143]
	v_lshl_add_u64 v[210:211], v[208:209], 0, v[148:149]
	v_lshl_add_u64 v[212:213], v[210:211], 0, s[50:51]
	v_lshl_add_u64 v[214:215], v[212:213], 2, s[60:61]
	global_load_dwordx4 v[176:179], v[214:215], off nt
	global_load_dwordx4 v[180:183], v[214:215], off offset:16 nt
	v_pk_add_f32 v[60:61], v[60:61], v[64:65]
	v_pk_add_f32 v[64:65], v[58:59], v[70:71]
	v_pk_add_f32 v[58:59], v[56:57], v[68:69]
	v_pk_add_f32 v[62:63], v[62:63], v[66:67]
	v_cvt_pk_bf16_f32 v56, v60, v61
	s_nop 0
	v_cvt_pk_bf16_f32 v57, v62, v63
	v_cvt_pk_bf16_f32 v58, v58, v59
	v_cvt_pk_bf16_f32 v59, v64, v65
	flat_store_dwordx4 v[72:73], v[56:59]
	s_nop 0
	v_lshlrev_b64 v[64:65], 11, v[144:145]
	v_lshl_add_u64 v[64:65], v[64:65], 0, v[148:149]
	v_lshl_add_u64 v[64:65], v[64:65], 0, s[50:51]
	v_lshl_add_u64 v[66:67], v[64:65], 2, s[60:61]
	s_waitcnt vmcnt(10)
	s_nop 1
	v_mov_b32_e32 v56, v184
	v_mov_b32_e32 v57, v185
	v_mov_b32_e32 v58, v186
	v_mov_b32_e32 v59, v187
	v_mov_b32_e32 v60, v188
	v_mov_b32_e32 v61, v189
	v_mov_b32_e32 v62, v190
	v_mov_b32_e32 v63, v191
	v_lshlrev_b64 v[208:209], 11, v[142:143]
	v_lshl_add_u64 v[210:211], v[208:209], 0, v[148:149]
	v_lshl_add_u64 v[212:213], v[210:211], 0, s[50:51]
	v_lshl_add_u64 v[214:215], v[212:213], 2, s[60:61]
	global_load_dwordx4 v[184:187], v[214:215], off offset:512 nt
	global_load_dwordx4 v[188:191], v[214:215], off offset:528 nt
	v_pk_add_f32 v[52:53], v[52:53], v[56:57]
	v_pk_add_f32 v[56:57], v[50:51], v[62:63]
	v_pk_add_f32 v[50:51], v[48:49], v[60:61]
	v_pk_add_f32 v[54:55], v[54:55], v[58:59]
	v_cvt_pk_bf16_f32 v48, v52, v53
	s_nop 0
	v_cvt_pk_bf16_f32 v49, v54, v55
	v_cvt_pk_bf16_f32 v50, v50, v51
	v_cvt_pk_bf16_f32 v51, v56, v57
	flat_store_dwordx4 v[72:73], v[48:51] offset:256
	s_nop 0
	v_lshl_add_u64 v[56:57], v[64:65], 1, s[58:59]
	s_waitcnt vmcnt(10)
	s_nop 1
	v_mov_b32_e32 v48, v192
	v_mov_b32_e32 v49, v193
	v_mov_b32_e32 v50, v194
	v_mov_b32_e32 v51, v195
	v_mov_b32_e32 v52, v196
	v_mov_b32_e32 v53, v197
	v_mov_b32_e32 v54, v198
	v_mov_b32_e32 v55, v199
	v_lshlrev_b64 v[208:209], 11, v[140:141]
	v_lshl_add_u64 v[210:211], v[208:209], 0, v[148:149]
	v_lshl_add_u64 v[212:213], v[210:211], 0, s[50:51]
	v_lshl_add_u64 v[214:215], v[212:213], 2, s[60:61]
	global_load_dwordx4 v[192:195], v[214:215], off nt
	global_load_dwordx4 v[196:199], v[214:215], off offset:16 nt
	v_pk_add_f32 v[44:45], v[44:45], v[48:49]
	v_pk_add_f32 v[48:49], v[42:43], v[54:55]
	v_pk_add_f32 v[42:43], v[40:41], v[52:53]
	v_pk_add_f32 v[46:47], v[46:47], v[50:51]
	v_cvt_pk_bf16_f32 v40, v44, v45
	s_nop 0
	v_cvt_pk_bf16_f32 v41, v46, v47
	v_cvt_pk_bf16_f32 v42, v42, v43
	v_cvt_pk_bf16_f32 v43, v48, v49
	flat_store_dwordx4 v[56:57], v[40:43]
	s_nop 0
	v_lshlrev_b64 v[48:49], 11, v[142:143]
	v_lshl_add_u64 v[48:49], v[48:49], 0, v[148:149]
	v_lshl_add_u64 v[48:49], v[48:49], 0, s[50:51]
	v_lshl_add_u64 v[50:51], v[48:49], 2, s[60:61]
	s_waitcnt vmcnt(10)
	s_nop 1
	v_mov_b32_e32 v40, v200
	v_mov_b32_e32 v41, v201
	v_mov_b32_e32 v42, v202
	v_mov_b32_e32 v43, v203
	v_mov_b32_e32 v44, v204
	v_mov_b32_e32 v45, v205
	v_mov_b32_e32 v46, v206
	v_mov_b32_e32 v47, v207
	v_lshlrev_b64 v[208:209], 11, v[140:141]
	v_lshl_add_u64 v[210:211], v[208:209], 0, v[148:149]
	v_lshl_add_u64 v[212:213], v[210:211], 0, s[50:51]
	v_lshl_add_u64 v[214:215], v[212:213], 2, s[60:61]
	global_load_dwordx4 v[200:203], v[214:215], off offset:512 nt
	global_load_dwordx4 v[204:207], v[214:215], off offset:528 nt
	v_pk_add_f32 v[36:37], v[36:37], v[40:41]
	v_pk_add_f32 v[40:41], v[34:35], v[46:47]
	v_pk_add_f32 v[34:35], v[32:33], v[44:45]
	v_pk_add_f32 v[38:39], v[38:39], v[42:43]
	v_cvt_pk_bf16_f32 v32, v36, v37
	s_nop 0
	v_cvt_pk_bf16_f32 v33, v38, v39
	v_cvt_pk_bf16_f32 v34, v34, v35
	v_cvt_pk_bf16_f32 v35, v40, v41
	flat_store_dwordx4 v[56:57], v[32:35] offset:256
	s_nop 0
	v_lshl_add_u64 v[40:41], v[48:49], 1, s[58:59]
	s_waitcnt vmcnt(10)
	s_nop 1
	v_mov_b32_e32 v32, v176
	v_mov_b32_e32 v33, v177
	v_mov_b32_e32 v34, v178
	v_mov_b32_e32 v35, v179
	v_mov_b32_e32 v36, v180
	v_mov_b32_e32 v37, v181
	v_mov_b32_e32 v38, v182
	v_mov_b32_e32 v39, v183
	v_pk_add_f32 v[28:29], v[28:29], v[32:33]
	v_pk_add_f32 v[32:33], v[26:27], v[38:39]
	v_pk_add_f32 v[26:27], v[24:25], v[36:37]
	v_pk_add_f32 v[30:31], v[30:31], v[34:35]
	v_cvt_pk_bf16_f32 v24, v28, v29
	s_nop 0
	v_cvt_pk_bf16_f32 v25, v30, v31
	v_cvt_pk_bf16_f32 v26, v26, v27
	v_cvt_pk_bf16_f32 v27, v32, v33
	flat_store_dwordx4 v[40:41], v[24:27]
	s_nop 0
	v_lshlrev_b64 v[32:33], 11, v[140:141]
	v_lshl_add_u64 v[32:33], v[32:33], 0, v[148:149]
	v_lshl_add_u64 v[32:33], v[32:33], 0, s[50:51]
	v_lshl_add_u64 v[34:35], v[32:33], 2, s[60:61]
	s_waitcnt vmcnt(8)
	s_nop 1
	v_mov_b32_e32 v24, v184
	v_mov_b32_e32 v25, v185
	v_mov_b32_e32 v26, v186
	v_mov_b32_e32 v27, v187
	v_mov_b32_e32 v28, v188
	v_mov_b32_e32 v29, v189
	v_mov_b32_e32 v30, v190
	v_mov_b32_e32 v31, v191
	v_pk_add_f32 v[20:21], v[20:21], v[24:25]
	v_pk_add_f32 v[24:25], v[18:19], v[30:31]
	v_pk_add_f32 v[18:19], v[16:17], v[28:29]
	v_pk_add_f32 v[22:23], v[22:23], v[26:27]
	v_cvt_pk_bf16_f32 v16, v20, v21
	s_nop 0
	v_cvt_pk_bf16_f32 v17, v22, v23
	v_cvt_pk_bf16_f32 v18, v18, v19
	v_cvt_pk_bf16_f32 v19, v24, v25
	flat_store_dwordx4 v[40:41], v[16:19] offset:256
	s_nop 0
	v_lshl_add_u64 v[24:25], v[32:33], 1, s[58:59]
	s_waitcnt vmcnt(6)
	s_nop 1
	v_mov_b32_e32 v16, v192
	v_mov_b32_e32 v17, v193
	v_mov_b32_e32 v18, v194
	v_mov_b32_e32 v19, v195
	v_mov_b32_e32 v20, v196
	v_mov_b32_e32 v21, v197
	v_mov_b32_e32 v22, v198
	v_mov_b32_e32 v23, v199
	v_pk_add_f32 v[12:13], v[12:13], v[16:17]
	v_pk_add_f32 v[16:17], v[10:11], v[22:23]
	v_pk_add_f32 v[10:11], v[8:9], v[20:21]
	v_pk_add_f32 v[14:15], v[14:15], v[18:19]
	v_cvt_pk_bf16_f32 v8, v12, v13
	s_nop 0
	v_cvt_pk_bf16_f32 v9, v14, v15
	v_cvt_pk_bf16_f32 v10, v10, v11
	v_cvt_pk_bf16_f32 v11, v16, v17
	flat_store_dwordx4 v[24:25], v[8:11]
	s_nop 0
	s_waitcnt vmcnt(4)
	s_nop 1
	v_mov_b32_e32 v8, v200
	v_mov_b32_e32 v9, v201
	v_mov_b32_e32 v10, v202
	v_mov_b32_e32 v11, v203
	v_mov_b32_e32 v12, v204
	v_mov_b32_e32 v13, v205
	v_mov_b32_e32 v14, v206
	v_mov_b32_e32 v15, v207
	v_pk_add_f32 v[4:5], v[4:5], v[8:9]
	v_pk_add_f32 v[8:9], v[2:3], v[14:15]
	v_pk_add_f32 v[2:3], v[0:1], v[12:13]
	v_pk_add_f32 v[6:7], v[6:7], v[10:11]
	v_cvt_pk_bf16_f32 v0, v4, v5
	s_nop 0
	v_cvt_pk_bf16_f32 v1, v6, v7
	v_cvt_pk_bf16_f32 v2, v2, v3
	v_cvt_pk_bf16_f32 v3, v8, v9
	flat_store_dwordx4 v[24:25], v[0:3] offset:256

.LBB0_632:
	s_cmpk_lg_i32 s26, 0x100
	s_cbranch_scc1 .Lsrow_r1_orig
	s_add_i32 s93, s52, 0xffffe000
	s_and_b32 s97, s93, 7
	s_cmp_gt_u32 s97, 3
	s_cbranch_scc1 .LBB0_662
	s_lshr_b32 s93, s93, 3
	s_lshl_b32 s93, s93, 2
	s_add_i32 s93, s93, s97
	s_add_i32 s32, s93, 0x2000
	s_waitcnt lgkmcnt(0)
	v_and_b32_e32 v195, 63, v164
	v_lshlrev_b32_e32 v162, 4, v195
	v_lshlrev_b32_e32 v163, 5, v195
	v_lshlrev_b32_e32 v243, 2, v195
	v_add_u32_e32 v194, 0x1000, v163
	s_lshl_b32 s97, s93, 12
	s_add_u32 s98, s34, s97
	s_addc_u32 s99, s35, 0
	s_add_u32 s98, s98, 0x19600000
	s_addc_u32 s99, s99, 0
	s_waitcnt lgkmcnt(0)
	s_lshl_b32 s97, s93, 13
	s_add_u32 s94, s10, s97
	s_addc_u32 s95, s11, 0
	global_load_dwordx4 v[118:121], v163, s[94:95] nt
	global_load_dwordx4 v[122:125], v163, s[94:95] offset:16 nt
	global_load_dwordx4 v[126:129], v163, s[94:95] offset:2048 nt
	global_load_dwordx4 v[130:133], v163, s[94:95] offset:2064 nt
	global_load_dwordx4 v[134:137], v194, s[94:95] nt
	global_load_dwordx4 v[138:141], v194, s[94:95] offset:16 nt
	global_load_dwordx4 v[142:145], v194, s[94:95] offset:2048 nt
	global_load_dwordx4 v[146:149], v194, s[94:95] offset:2064 nt
	global_load_dwordx4 v[150:153], v162, s[98:99] nt
	global_load_dwordx4 v[154:157], v162, s[98:99] offset:1024 nt
	global_load_dwordx4 v[158:161], v162, s[98:99] offset:2048 nt
	global_load_dwordx4 v[166:169], v162, s[98:99] offset:3072 nt
	s_add_u32 s98, s98, 0x400000
	s_addc_u32 s99, s99, 0
	global_load_dwordx4 v[170:173], v162, s[98:99] nt
	global_load_dwordx4 v[174:177], v162, s[98:99] offset:1024 nt
	global_load_dwordx4 v[178:181], v162, s[98:99] offset:2048 nt
	global_load_dwordx4 v[182:185], v162, s[98:99] offset:3072 nt
	s_add_u32 s98, s98, 0x400000
	s_addc_u32 s99, s99, 0
	global_load_dwordx4 v[186:189], v162, s[98:99] nt
	global_load_dwordx4 v[190:193], v162, s[98:99] offset:1024 nt
	global_load_dwordx4 v[198:201], v162, s[98:99] offset:2048 nt
	global_load_dwordx4 v[202:205], v162, s[98:99] offset:3072 nt
	s_add_u32 s98, s98, 0x400000
	s_addc_u32 s99, s99, 0
	global_load_dwordx4 v[206:209], v162, s[98:99] nt
	global_load_dwordx4 v[210:213], v162, s[98:99] offset:1024 nt
	global_load_dwordx4 v[214:217], v162, s[98:99] offset:2048 nt
	global_load_dwordx4 v[218:221], v162, s[98:99] offset:3072 nt
	s_add_u32 s98, s98, 0x400000
	s_addc_u32 s99, s99, 0
	s_waitcnt vmcnt(12)
	v_lshlrev_b32_e32 v195, 16, v150
	v_and_b32_e32 v197, 0xffff0000, v150
	v_add_f32_e32 v118, v118, v195
	v_add_f32_e32 v119, v119, v197
	v_lshlrev_b32_e32 v195, 16, v151
	v_and_b32_e32 v197, 0xffff0000, v151
	v_add_f32_e32 v120, v120, v195
	v_add_f32_e32 v121, v121, v197
	v_lshlrev_b32_e32 v195, 16, v152
	v_and_b32_e32 v197, 0xffff0000, v152
	v_add_f32_e32 v122, v122, v195
	v_add_f32_e32 v123, v123, v197
	v_lshlrev_b32_e32 v195, 16, v153
	v_and_b32_e32 v197, 0xffff0000, v153
	v_add_f32_e32 v124, v124, v195
	v_add_f32_e32 v125, v125, v197
	v_lshlrev_b32_e32 v195, 16, v154
	v_and_b32_e32 v197, 0xffff0000, v154
	v_add_f32_e32 v126, v126, v195
	v_add_f32_e32 v127, v127, v197
	v_lshlrev_b32_e32 v195, 16, v155
	v_and_b32_e32 v197, 0xffff0000, v155
	v_add_f32_e32 v128, v128, v195
	v_add_f32_e32 v129, v129, v197
	v_lshlrev_b32_e32 v195, 16, v156
	v_and_b32_e32 v197, 0xffff0000, v156
	v_add_f32_e32 v130, v130, v195
	v_add_f32_e32 v131, v131, v197
	v_lshlrev_b32_e32 v195, 16, v157
	v_and_b32_e32 v197, 0xffff0000, v157
	v_add_f32_e32 v132, v132, v195
	v_add_f32_e32 v133, v133, v197
	v_lshlrev_b32_e32 v195, 16, v158
	v_and_b32_e32 v197, 0xffff0000, v158
	v_add_f32_e32 v134, v134, v195
	v_add_f32_e32 v135, v135, v197
	v_lshlrev_b32_e32 v195, 16, v159
	v_and_b32_e32 v197, 0xffff0000, v159
	v_add_f32_e32 v136, v136, v195
	v_add_f32_e32 v137, v137, v197
	v_lshlrev_b32_e32 v195, 16, v160
	v_and_b32_e32 v197, 0xffff0000, v160
	v_add_f32_e32 v138, v138, v195
	v_add_f32_e32 v139, v139, v197
	v_lshlrev_b32_e32 v195, 16, v161
	v_and_b32_e32 v197, 0xffff0000, v161
	v_add_f32_e32 v140, v140, v195
	v_add_f32_e32 v141, v141, v197
	v_lshlrev_b32_e32 v195, 16, v166
	v_and_b32_e32 v197, 0xffff0000, v166
	v_add_f32_e32 v142, v142, v195
	v_add_f32_e32 v143, v143, v197
	v_lshlrev_b32_e32 v195, 16, v167
	v_and_b32_e32 v197, 0xffff0000, v167
	v_add_f32_e32 v144, v144, v195
	v_add_f32_e32 v145, v145, v197
	v_lshlrev_b32_e32 v195, 16, v168
	v_and_b32_e32 v197, 0xffff0000, v168
	v_add_f32_e32 v146, v146, v195
	v_add_f32_e32 v147, v147, v197
	v_lshlrev_b32_e32 v195, 16, v169
	v_and_b32_e32 v197, 0xffff0000, v169
	v_add_f32_e32 v148, v148, v195
	v_add_f32_e32 v149, v149, v197
	global_load_dwordx4 v[150:153], v162, s[98:99] nt
	global_load_dwordx4 v[154:157], v162, s[98:99] offset:1024 nt
	global_load_dwordx4 v[158:161], v162, s[98:99] offset:2048 nt
	global_load_dwordx4 v[166:169], v162, s[98:99] offset:3072 nt
	s_add_u32 s98, s98, 0x400000
	s_addc_u32 s99, s99, 0
	s_waitcnt vmcnt(12)
	v_lshlrev_b32_e32 v195, 16, v170
	v_and_b32_e32 v197, 0xffff0000, v170
	v_add_f32_e32 v118, v118, v195
	v_add_f32_e32 v119, v119, v197
	v_lshlrev_b32_e32 v195, 16, v171
	v_and_b32_e32 v197, 0xffff0000, v171
	v_add_f32_e32 v120, v120, v195
	v_add_f32_e32 v121, v121, v197
	v_lshlrev_b32_e32 v195, 16, v172
	v_and_b32_e32 v197, 0xffff0000, v172
	v_add_f32_e32 v122, v122, v195
	v_add_f32_e32 v123, v123, v197
	v_lshlrev_b32_e32 v195, 16, v173
	v_and_b32_e32 v197, 0xffff0000, v173
	v_add_f32_e32 v124, v124, v195
	v_add_f32_e32 v125, v125, v197
	v_lshlrev_b32_e32 v195, 16, v174
	v_and_b32_e32 v197, 0xffff0000, v174
	v_add_f32_e32 v126, v126, v195
	v_add_f32_e32 v127, v127, v197
	v_lshlrev_b32_e32 v195, 16, v175
	v_and_b32_e32 v197, 0xffff0000, v175
	v_add_f32_e32 v128, v128, v195
	v_add_f32_e32 v129, v129, v197
	v_lshlrev_b32_e32 v195, 16, v176
	v_and_b32_e32 v197, 0xffff0000, v176
	v_add_f32_e32 v130, v130, v195
	v_add_f32_e32 v131, v131, v197
	v_lshlrev_b32_e32 v195, 16, v177
	v_and_b32_e32 v197, 0xffff0000, v177
	v_add_f32_e32 v132, v132, v195
	v_add_f32_e32 v133, v133, v197
	v_lshlrev_b32_e32 v195, 16, v178
	v_and_b32_e32 v197, 0xffff0000, v178
	v_add_f32_e32 v134, v134, v195
	v_add_f32_e32 v135, v135, v197
	v_lshlrev_b32_e32 v195, 16, v179
	v_and_b32_e32 v197, 0xffff0000, v179
	v_add_f32_e32 v136, v136, v195
	v_add_f32_e32 v137, v137, v197
	v_lshlrev_b32_e32 v195, 16, v180
	v_and_b32_e32 v197, 0xffff0000, v180
	v_add_f32_e32 v138, v138, v195
	v_add_f32_e32 v139, v139, v197
	v_lshlrev_b32_e32 v195, 16, v181
	v_and_b32_e32 v197, 0xffff0000, v181
	v_add_f32_e32 v140, v140, v195
	v_add_f32_e32 v141, v141, v197
	v_lshlrev_b32_e32 v195, 16, v182
	v_and_b32_e32 v197, 0xffff0000, v182
	v_add_f32_e32 v142, v142, v195
	v_add_f32_e32 v143, v143, v197
	v_lshlrev_b32_e32 v195, 16, v183
	v_and_b32_e32 v197, 0xffff0000, v183
	v_add_f32_e32 v144, v144, v195
	v_add_f32_e32 v145, v145, v197
	v_lshlrev_b32_e32 v195, 16, v184
	v_and_b32_e32 v197, 0xffff0000, v184
	v_add_f32_e32 v146, v146, v195
	v_add_f32_e32 v147, v147, v197
	v_lshlrev_b32_e32 v195, 16, v185
	v_and_b32_e32 v197, 0xffff0000, v185
	v_add_f32_e32 v148, v148, v195
	v_add_f32_e32 v149, v149, v197
	global_load_dwordx4 v[170:173], v162, s[98:99] nt
	global_load_dwordx4 v[174:177], v162, s[98:99] offset:1024 nt
	global_load_dwordx4 v[178:181], v162, s[98:99] offset:2048 nt
	global_load_dwordx4 v[182:185], v162, s[98:99] offset:3072 nt
	s_add_u32 s98, s98, 0x400000
	s_addc_u32 s99, s99, 0
	s_waitcnt vmcnt(12)
	v_lshlrev_b32_e32 v195, 16, v186
	v_and_b32_e32 v197, 0xffff0000, v186
	v_add_f32_e32 v118, v118, v195
	v_add_f32_e32 v119, v119, v197
	v_lshlrev_b32_e32 v195, 16, v187
	v_and_b32_e32 v197, 0xffff0000, v187
	v_add_f32_e32 v120, v120, v195
	v_add_f32_e32 v121, v121, v197
	v_lshlrev_b32_e32 v195, 16, v188
	v_and_b32_e32 v197, 0xffff0000, v188
	v_add_f32_e32 v122, v122, v195
	v_add_f32_e32 v123, v123, v197
	v_lshlrev_b32_e32 v195, 16, v189
	v_and_b32_e32 v197, 0xffff0000, v189
	v_add_f32_e32 v124, v124, v195
	v_add_f32_e32 v125, v125, v197
	v_lshlrev_b32_e32 v195, 16, v190
	v_and_b32_e32 v197, 0xffff0000, v190
	v_add_f32_e32 v126, v126, v195
	v_add_f32_e32 v127, v127, v197
	v_lshlrev_b32_e32 v195, 16, v191
	v_and_b32_e32 v197, 0xffff0000, v191
	v_add_f32_e32 v128, v128, v195
	v_add_f32_e32 v129, v129, v197
	v_lshlrev_b32_e32 v195, 16, v192
	v_and_b32_e32 v197, 0xffff0000, v192
	v_add_f32_e32 v130, v130, v195
	v_add_f32_e32 v131, v131, v197
	v_lshlrev_b32_e32 v195, 16, v193
	v_and_b32_e32 v197, 0xffff0000, v193
	v_add_f32_e32 v132, v132, v195
	v_add_f32_e32 v133, v133, v197
	v_lshlrev_b32_e32 v195, 16, v198
	v_and_b32_e32 v197, 0xffff0000, v198
	v_add_f32_e32 v134, v134, v195
	v_add_f32_e32 v135, v135, v197
	v_lshlrev_b32_e32 v195, 16, v199
	v_and_b32_e32 v197, 0xffff0000, v199
	v_add_f32_e32 v136, v136, v195
	v_add_f32_e32 v137, v137, v197
	v_lshlrev_b32_e32 v195, 16, v200
	v_and_b32_e32 v197, 0xffff0000, v200
	v_add_f32_e32 v138, v138, v195
	v_add_f32_e32 v139, v139, v197
	v_lshlrev_b32_e32 v195, 16, v201
	v_and_b32_e32 v197, 0xffff0000, v201
	v_add_f32_e32 v140, v140, v195
	v_add_f32_e32 v141, v141, v197
	v_lshlrev_b32_e32 v195, 16, v202
	v_and_b32_e32 v197, 0xffff0000, v202
	v_add_f32_e32 v142, v142, v195
	v_add_f32_e32 v143, v143, v197
	v_lshlrev_b32_e32 v195, 16, v203
	v_and_b32_e32 v197, 0xffff0000, v203
	v_add_f32_e32 v144, v144, v195
	v_add_f32_e32 v145, v145, v197
	v_lshlrev_b32_e32 v195, 16, v204
	v_and_b32_e32 v197, 0xffff0000, v204
	v_add_f32_e32 v146, v146, v195
	v_add_f32_e32 v147, v147, v197
	v_lshlrev_b32_e32 v195, 16, v205
	v_and_b32_e32 v197, 0xffff0000, v205
	v_add_f32_e32 v148, v148, v195
	v_add_f32_e32 v149, v149, v197
	global_load_dwordx4 v[186:189], v162, s[98:99] nt
	global_load_dwordx4 v[190:193], v162, s[98:99] offset:1024 nt
	global_load_dwordx4 v[198:201], v162, s[98:99] offset:2048 nt
	global_load_dwordx4 v[202:205], v162, s[98:99] offset:3072 nt
	s_add_u32 s98, s98, 0x400000
	s_addc_u32 s99, s99, 0
	s_waitcnt vmcnt(12)
	v_lshlrev_b32_e32 v195, 16, v206
	v_and_b32_e32 v197, 0xffff0000, v206
	v_add_f32_e32 v118, v118, v195
	v_add_f32_e32 v119, v119, v197
	v_lshlrev_b32_e32 v195, 16, v207
	v_and_b32_e32 v197, 0xffff0000, v207
	v_add_f32_e32 v120, v120, v195
	v_add_f32_e32 v121, v121, v197
	v_lshlrev_b32_e32 v195, 16, v208
	v_and_b32_e32 v197, 0xffff0000, v208
	v_add_f32_e32 v122, v122, v195
	v_add_f32_e32 v123, v123, v197
	v_lshlrev_b32_e32 v195, 16, v209
	v_and_b32_e32 v197, 0xffff0000, v209
	v_add_f32_e32 v124, v124, v195
	v_add_f32_e32 v125, v125, v197
	v_lshlrev_b32_e32 v195, 16, v210
	v_and_b32_e32 v197, 0xffff0000, v210
	v_add_f32_e32 v126, v126, v195
	v_add_f32_e32 v127, v127, v197
	v_lshlrev_b32_e32 v195, 16, v211
	v_and_b32_e32 v197, 0xffff0000, v211
	v_add_f32_e32 v128, v128, v195
	v_add_f32_e32 v129, v129, v197
	v_lshlrev_b32_e32 v195, 16, v212
	v_and_b32_e32 v197, 0xffff0000, v212
	v_add_f32_e32 v130, v130, v195
	v_add_f32_e32 v131, v131, v197
	v_lshlrev_b32_e32 v195, 16, v213
	v_and_b32_e32 v197, 0xffff0000, v213
	v_add_f32_e32 v132, v132, v195
	v_add_f32_e32 v133, v133, v197
	v_lshlrev_b32_e32 v195, 16, v214
	v_and_b32_e32 v197, 0xffff0000, v214
	v_add_f32_e32 v134, v134, v195
	v_add_f32_e32 v135, v135, v197
	v_lshlrev_b32_e32 v195, 16, v215
	v_and_b32_e32 v197, 0xffff0000, v215
	v_add_f32_e32 v136, v136, v195
	v_add_f32_e32 v137, v137, v197
	v_lshlrev_b32_e32 v195, 16, v216
	v_and_b32_e32 v197, 0xffff0000, v216
	v_add_f32_e32 v138, v138, v195
	v_add_f32_e32 v139, v139, v197
	v_lshlrev_b32_e32 v195, 16, v217
	v_and_b32_e32 v197, 0xffff0000, v217
	v_add_f32_e32 v140, v140, v195
	v_add_f32_e32 v141, v141, v197
	v_lshlrev_b32_e32 v195, 16, v218
	v_and_b32_e32 v197, 0xffff0000, v218
	v_add_f32_e32 v142, v142, v195
	v_add_f32_e32 v143, v143, v197
	v_lshlrev_b32_e32 v195, 16, v219
	v_and_b32_e32 v197, 0xffff0000, v219
	v_add_f32_e32 v144, v144, v195
	v_add_f32_e32 v145, v145, v197
	v_lshlrev_b32_e32 v195, 16, v220
	v_and_b32_e32 v197, 0xffff0000, v220
	v_add_f32_e32 v146, v146, v195
	v_add_f32_e32 v147, v147, v197
	v_lshlrev_b32_e32 v195, 16, v221
	v_and_b32_e32 v197, 0xffff0000, v221
	v_add_f32_e32 v148, v148, v195
	v_add_f32_e32 v149, v149, v197
	global_load_dwordx4 v[206:209], v162, s[98:99] nt
	global_load_dwordx4 v[210:213], v162, s[98:99] offset:1024 nt
	global_load_dwordx4 v[214:217], v162, s[98:99] offset:2048 nt
	global_load_dwordx4 v[218:221], v162, s[98:99] offset:3072 nt
	s_add_u32 s98, s98, 0x400000
	s_addc_u32 s99, s99, 0
	s_waitcnt vmcnt(12)
	v_lshlrev_b32_e32 v195, 16, v150
	v_and_b32_e32 v197, 0xffff0000, v150
	v_add_f32_e32 v118, v118, v195
	v_add_f32_e32 v119, v119, v197
	v_lshlrev_b32_e32 v195, 16, v151
	v_and_b32_e32 v197, 0xffff0000, v151
	v_add_f32_e32 v120, v120, v195
	v_add_f32_e32 v121, v121, v197
	v_lshlrev_b32_e32 v195, 16, v152
	v_and_b32_e32 v197, 0xffff0000, v152
	v_add_f32_e32 v122, v122, v195
	v_add_f32_e32 v123, v123, v197
	v_lshlrev_b32_e32 v195, 16, v153
	v_and_b32_e32 v197, 0xffff0000, v153
	v_add_f32_e32 v124, v124, v195
	v_add_f32_e32 v125, v125, v197
	v_lshlrev_b32_e32 v195, 16, v154
	v_and_b32_e32 v197, 0xffff0000, v154
	v_add_f32_e32 v126, v126, v195
	v_add_f32_e32 v127, v127, v197
	v_lshlrev_b32_e32 v195, 16, v155
	v_and_b32_e32 v197, 0xffff0000, v155
	v_add_f32_e32 v128, v128, v195
	v_add_f32_e32 v129, v129, v197
	v_lshlrev_b32_e32 v195, 16, v156
	v_and_b32_e32 v197, 0xffff0000, v156
	v_add_f32_e32 v130, v130, v195
	v_add_f32_e32 v131, v131, v197
	v_lshlrev_b32_e32 v195, 16, v157
	v_and_b32_e32 v197, 0xffff0000, v157
	v_add_f32_e32 v132, v132, v195
	v_add_f32_e32 v133, v133, v197
	v_lshlrev_b32_e32 v195, 16, v158
	v_and_b32_e32 v197, 0xffff0000, v158
	v_add_f32_e32 v134, v134, v195
	v_add_f32_e32 v135, v135, v197
	v_lshlrev_b32_e32 v195, 16, v159
	v_and_b32_e32 v197, 0xffff0000, v159
	v_add_f32_e32 v136, v136, v195
	v_add_f32_e32 v137, v137, v197
	v_lshlrev_b32_e32 v195, 16, v160
	v_and_b32_e32 v197, 0xffff0000, v160
	v_add_f32_e32 v138, v138, v195
	v_add_f32_e32 v139, v139, v197
	v_lshlrev_b32_e32 v195, 16, v161
	v_and_b32_e32 v197, 0xffff0000, v161
	v_add_f32_e32 v140, v140, v195
	v_add_f32_e32 v141, v141, v197
	v_lshlrev_b32_e32 v195, 16, v166
	v_and_b32_e32 v197, 0xffff0000, v166
	v_add_f32_e32 v142, v142, v195
	v_add_f32_e32 v143, v143, v197
	v_lshlrev_b32_e32 v195, 16, v167
	v_and_b32_e32 v197, 0xffff0000, v167
	v_add_f32_e32 v144, v144, v195
	v_add_f32_e32 v145, v145, v197
	v_lshlrev_b32_e32 v195, 16, v168
	v_and_b32_e32 v197, 0xffff0000, v168
	v_add_f32_e32 v146, v146, v195
	v_add_f32_e32 v147, v147, v197
	v_lshlrev_b32_e32 v195, 16, v169
	v_and_b32_e32 v197, 0xffff0000, v169
	v_add_f32_e32 v148, v148, v195
	v_add_f32_e32 v149, v149, v197
	global_load_dwordx4 v[150:153], v163, s[14:15]
	global_load_dwordx4 v[154:157], v163, s[14:15] offset:16
	global_load_dwordx4 v[158:161], v163, s[14:15] offset:2048
	global_load_dwordx4 v[166:169], v163, s[14:15] offset:2064
	s_waitcnt vmcnt(12)
	v_lshlrev_b32_e32 v195, 16, v170
	v_and_b32_e32 v197, 0xffff0000, v170
	v_add_f32_e32 v118, v118, v195
	v_add_f32_e32 v119, v119, v197
	v_lshlrev_b32_e32 v195, 16, v171
	v_and_b32_e32 v197, 0xffff0000, v171
	v_add_f32_e32 v120, v120, v195
	v_add_f32_e32 v121, v121, v197
	v_lshlrev_b32_e32 v195, 16, v172
	v_and_b32_e32 v197, 0xffff0000, v172
	v_add_f32_e32 v122, v122, v195
	v_add_f32_e32 v123, v123, v197
	v_lshlrev_b32_e32 v195, 16, v173
	v_and_b32_e32 v197, 0xffff0000, v173
	v_add_f32_e32 v124, v124, v195
	v_add_f32_e32 v125, v125, v197
	v_lshlrev_b32_e32 v195, 16, v174
	v_and_b32_e32 v197, 0xffff0000, v174
	v_add_f32_e32 v126, v126, v195
	v_add_f32_e32 v127, v127, v197
	v_lshlrev_b32_e32 v195, 16, v175
	v_and_b32_e32 v197, 0xffff0000, v175
	v_add_f32_e32 v128, v128, v195
	v_add_f32_e32 v129, v129, v197
	v_lshlrev_b32_e32 v195, 16, v176
	v_and_b32_e32 v197, 0xffff0000, v176
	v_add_f32_e32 v130, v130, v195
	v_add_f32_e32 v131, v131, v197
	v_lshlrev_b32_e32 v195, 16, v177
	v_and_b32_e32 v197, 0xffff0000, v177
	v_add_f32_e32 v132, v132, v195
	v_add_f32_e32 v133, v133, v197
	v_lshlrev_b32_e32 v195, 16, v178
	v_and_b32_e32 v197, 0xffff0000, v178
	v_add_f32_e32 v134, v134, v195
	v_add_f32_e32 v135, v135, v197
	v_lshlrev_b32_e32 v195, 16, v179
	v_and_b32_e32 v197, 0xffff0000, v179
	v_add_f32_e32 v136, v136, v195
	v_add_f32_e32 v137, v137, v197
	v_lshlrev_b32_e32 v195, 16, v180
	v_and_b32_e32 v197, 0xffff0000, v180
	v_add_f32_e32 v138, v138, v195
	v_add_f32_e32 v139, v139, v197
	v_lshlrev_b32_e32 v195, 16, v181
	v_and_b32_e32 v197, 0xffff0000, v181
	v_add_f32_e32 v140, v140, v195
	v_add_f32_e32 v141, v141, v197
	v_lshlrev_b32_e32 v195, 16, v182
	v_and_b32_e32 v197, 0xffff0000, v182
	v_add_f32_e32 v142, v142, v195
	v_add_f32_e32 v143, v143, v197
	v_lshlrev_b32_e32 v195, 16, v183
	v_and_b32_e32 v197, 0xffff0000, v183
	v_add_f32_e32 v144, v144, v195
	v_add_f32_e32 v145, v145, v197
	v_lshlrev_b32_e32 v195, 16, v184
	v_and_b32_e32 v197, 0xffff0000, v184
	v_add_f32_e32 v146, v146, v195
	v_add_f32_e32 v147, v147, v197
	v_lshlrev_b32_e32 v195, 16, v185
	v_and_b32_e32 v197, 0xffff0000, v185
	v_add_f32_e32 v148, v148, v195
	v_add_f32_e32 v149, v149, v197
	global_load_dwordx4 v[170:173], v194, s[14:15]
	global_load_dwordx4 v[174:177], v194, s[14:15] offset:16
	global_load_dwordx4 v[178:181], v194, s[14:15] offset:2048
	global_load_dwordx4 v[182:185], v194, s[14:15] offset:2064
	s_waitcnt vmcnt(12)
	v_lshlrev_b32_e32 v195, 16, v186
	v_and_b32_e32 v197, 0xffff0000, v186
	v_add_f32_e32 v118, v118, v195
	v_add_f32_e32 v119, v119, v197
	v_lshlrev_b32_e32 v195, 16, v187
	v_and_b32_e32 v197, 0xffff0000, v187
	v_add_f32_e32 v120, v120, v195
	v_add_f32_e32 v121, v121, v197
	v_lshlrev_b32_e32 v195, 16, v188
	v_and_b32_e32 v197, 0xffff0000, v188
	v_add_f32_e32 v122, v122, v195
	v_add_f32_e32 v123, v123, v197
	v_lshlrev_b32_e32 v195, 16, v189
	v_and_b32_e32 v197, 0xffff0000, v189
	v_add_f32_e32 v124, v124, v195
	v_add_f32_e32 v125, v125, v197
	v_lshlrev_b32_e32 v195, 16, v190
	v_and_b32_e32 v197, 0xffff0000, v190
	v_add_f32_e32 v126, v126, v195
	v_add_f32_e32 v127, v127, v197
	v_lshlrev_b32_e32 v195, 16, v191
	v_and_b32_e32 v197, 0xffff0000, v191
	v_add_f32_e32 v128, v128, v195
	v_add_f32_e32 v129, v129, v197
	v_lshlrev_b32_e32 v195, 16, v192
	v_and_b32_e32 v197, 0xffff0000, v192
	v_add_f32_e32 v130, v130, v195
	v_add_f32_e32 v131, v131, v197
	v_lshlrev_b32_e32 v195, 16, v193
	v_and_b32_e32 v197, 0xffff0000, v193
	v_add_f32_e32 v132, v132, v195
	v_add_f32_e32 v133, v133, v197
	v_lshlrev_b32_e32 v195, 16, v198
	v_and_b32_e32 v197, 0xffff0000, v198
	v_add_f32_e32 v134, v134, v195
	v_add_f32_e32 v135, v135, v197
	v_lshlrev_b32_e32 v195, 16, v199
	v_and_b32_e32 v197, 0xffff0000, v199
	v_add_f32_e32 v136, v136, v195
	v_add_f32_e32 v137, v137, v197
	v_lshlrev_b32_e32 v195, 16, v200
	v_and_b32_e32 v197, 0xffff0000, v200
	v_add_f32_e32 v138, v138, v195
	v_add_f32_e32 v139, v139, v197
	v_lshlrev_b32_e32 v195, 16, v201
	v_and_b32_e32 v197, 0xffff0000, v201
	v_add_f32_e32 v140, v140, v195
	v_add_f32_e32 v141, v141, v197
	v_lshlrev_b32_e32 v195, 16, v202
	v_and_b32_e32 v197, 0xffff0000, v202
	v_add_f32_e32 v142, v142, v195
	v_add_f32_e32 v143, v143, v197
	v_lshlrev_b32_e32 v195, 16, v203
	v_and_b32_e32 v197, 0xffff0000, v203
	v_add_f32_e32 v144, v144, v195
	v_add_f32_e32 v145, v145, v197
	v_lshlrev_b32_e32 v195, 16, v204
	v_and_b32_e32 v197, 0xffff0000, v204
	v_add_f32_e32 v146, v146, v195
	v_add_f32_e32 v147, v147, v197
	v_lshlrev_b32_e32 v195, 16, v205
	v_and_b32_e32 v197, 0xffff0000, v205
	v_add_f32_e32 v148, v148, v195
	v_add_f32_e32 v149, v149, v197
	s_waitcnt vmcnt(8)
	v_lshlrev_b32_e32 v195, 16, v206
	v_and_b32_e32 v197, 0xffff0000, v206
	v_add_f32_e32 v118, v118, v195
	v_add_f32_e32 v119, v119, v197
	v_lshlrev_b32_e32 v195, 16, v207
	v_and_b32_e32 v197, 0xffff0000, v207
	v_add_f32_e32 v120, v120, v195
	v_add_f32_e32 v121, v121, v197
	v_lshlrev_b32_e32 v195, 16, v208
	v_and_b32_e32 v197, 0xffff0000, v208
	v_add_f32_e32 v122, v122, v195
	v_add_f32_e32 v123, v123, v197
	v_lshlrev_b32_e32 v195, 16, v209
	v_and_b32_e32 v197, 0xffff0000, v209
	v_add_f32_e32 v124, v124, v195
	v_add_f32_e32 v125, v125, v197
	v_lshlrev_b32_e32 v195, 16, v210
	v_and_b32_e32 v197, 0xffff0000, v210
	v_add_f32_e32 v126, v126, v195
	v_add_f32_e32 v127, v127, v197
	v_lshlrev_b32_e32 v195, 16, v211
	v_and_b32_e32 v197, 0xffff0000, v211
	v_add_f32_e32 v128, v128, v195
	v_add_f32_e32 v129, v129, v197
	v_lshlrev_b32_e32 v195, 16, v212
	v_and_b32_e32 v197, 0xffff0000, v212
	v_add_f32_e32 v130, v130, v195
	v_add_f32_e32 v131, v131, v197
	v_lshlrev_b32_e32 v195, 16, v213
	v_and_b32_e32 v197, 0xffff0000, v213
	v_add_f32_e32 v132, v132, v195
	v_add_f32_e32 v133, v133, v197
	v_lshlrev_b32_e32 v195, 16, v214
	v_and_b32_e32 v197, 0xffff0000, v214
	v_add_f32_e32 v134, v134, v195
	v_add_f32_e32 v135, v135, v197
	v_lshlrev_b32_e32 v195, 16, v215
	v_and_b32_e32 v197, 0xffff0000, v215
	v_add_f32_e32 v136, v136, v195
	v_add_f32_e32 v137, v137, v197
	v_lshlrev_b32_e32 v195, 16, v216
	v_and_b32_e32 v197, 0xffff0000, v216
	v_add_f32_e32 v138, v138, v195
	v_add_f32_e32 v139, v139, v197
	v_lshlrev_b32_e32 v195, 16, v217
	v_and_b32_e32 v197, 0xffff0000, v217
	v_add_f32_e32 v140, v140, v195
	v_add_f32_e32 v141, v141, v197
	v_lshlrev_b32_e32 v195, 16, v218
	v_and_b32_e32 v197, 0xffff0000, v218
	v_add_f32_e32 v142, v142, v195
	v_add_f32_e32 v143, v143, v197
	v_lshlrev_b32_e32 v195, 16, v219
	v_and_b32_e32 v197, 0xffff0000, v219
	v_add_f32_e32 v144, v144, v195
	v_add_f32_e32 v145, v145, v197
	v_lshlrev_b32_e32 v195, 16, v220
	v_and_b32_e32 v197, 0xffff0000, v220
	v_add_f32_e32 v146, v146, v195
	v_add_f32_e32 v147, v147, v197
	v_lshlrev_b32_e32 v195, 16, v221
	v_and_b32_e32 v197, 0xffff0000, v221
	v_add_f32_e32 v148, v148, v195
	v_add_f32_e32 v149, v149, v197
	s_lshl_b32 s97, s32, 12
	s_add_u32 s94, s34, s97
	s_addc_u32 s95, s35, 0
	s_add_u32 s94, s94, 0x20200000
	s_addc_u32 s95, s95, 0
	v_cvt_pk_bf16_f32 v186, v118, v119
	v_cvt_pk_bf16_f32 v187, v120, v121
	v_cvt_pk_bf16_f32 v188, v122, v123
	v_cvt_pk_bf16_f32 v189, v124, v125
	global_store_dwordx4 v162, v[186:189], s[94:95]
	v_cvt_pk_bf16_f32 v190, v126, v127
	v_cvt_pk_bf16_f32 v191, v128, v129
	v_cvt_pk_bf16_f32 v192, v130, v131
	v_cvt_pk_bf16_f32 v193, v132, v133
	global_store_dwordx4 v162, v[190:193], s[94:95] offset:1024
	v_cvt_pk_bf16_f32 v198, v134, v135
	v_cvt_pk_bf16_f32 v199, v136, v137
	v_cvt_pk_bf16_f32 v200, v138, v139
	v_cvt_pk_bf16_f32 v201, v140, v141
	global_store_dwordx4 v162, v[198:201], s[94:95] offset:2048
	v_cvt_pk_bf16_f32 v202, v142, v143
	v_cvt_pk_bf16_f32 v203, v144, v145
	v_cvt_pk_bf16_f32 v204, v146, v147
	v_cvt_pk_bf16_f32 v205, v148, v149
	global_store_dwordx4 v162, v[202:205], s[94:95] offset:3072
	v_lshlrev_b32_e32 v118, 16, v186
	v_and_b32_e32 v119, 0xffff0000, v186
	v_lshlrev_b32_e32 v120, 16, v187
	v_and_b32_e32 v121, 0xffff0000, v187
	v_lshlrev_b32_e32 v122, 16, v188
	v_and_b32_e32 v123, 0xffff0000, v188
	v_lshlrev_b32_e32 v124, 16, v189
	v_and_b32_e32 v125, 0xffff0000, v189
	v_lshlrev_b32_e32 v126, 16, v190
	v_and_b32_e32 v127, 0xffff0000, v190
	v_lshlrev_b32_e32 v128, 16, v191
	v_and_b32_e32 v129, 0xffff0000, v191
	v_lshlrev_b32_e32 v130, 16, v192
	v_and_b32_e32 v131, 0xffff0000, v192
	v_lshlrev_b32_e32 v132, 16, v193
	v_and_b32_e32 v133, 0xffff0000, v193
	v_lshlrev_b32_e32 v134, 16, v198
	v_and_b32_e32 v135, 0xffff0000, v198
	v_lshlrev_b32_e32 v136, 16, v199
	v_and_b32_e32 v137, 0xffff0000, v199
	v_lshlrev_b32_e32 v138, 16, v200
	v_and_b32_e32 v139, 0xffff0000, v200
	v_lshlrev_b32_e32 v140, 16, v201
	v_and_b32_e32 v141, 0xffff0000, v201
	v_lshlrev_b32_e32 v142, 16, v202
	v_and_b32_e32 v143, 0xffff0000, v202
	v_lshlrev_b32_e32 v144, 16, v203
	v_and_b32_e32 v145, 0xffff0000, v203
	v_lshlrev_b32_e32 v146, 16, v204
	v_and_b32_e32 v147, 0xffff0000, v204
	v_lshlrev_b32_e32 v148, 16, v205
	v_and_b32_e32 v149, 0xffff0000, v205
	v_mul_f32_e32 v227, v118, v118
	v_fmac_f32_e32 v227, v119, v119
	v_fmac_f32_e32 v227, v120, v120
	v_fmac_f32_e32 v227, v121, v121
	v_fmac_f32_e32 v227, v122, v122
	v_fmac_f32_e32 v227, v123, v123
	v_fmac_f32_e32 v227, v124, v124
	v_fmac_f32_e32 v227, v125, v125
	v_fmac_f32_e32 v227, v126, v126
	v_fmac_f32_e32 v227, v127, v127
	v_fmac_f32_e32 v227, v128, v128
	v_fmac_f32_e32 v227, v129, v129
	v_fmac_f32_e32 v227, v130, v130
	v_fmac_f32_e32 v227, v131, v131
	v_fmac_f32_e32 v227, v132, v132
	v_fmac_f32_e32 v227, v133, v133
	v_fmac_f32_e32 v227, v134, v134
	v_fmac_f32_e32 v227, v135, v135
	v_fmac_f32_e32 v227, v136, v136
	v_fmac_f32_e32 v227, v137, v137
	v_fmac_f32_e32 v227, v138, v138
	v_fmac_f32_e32 v227, v139, v139
	v_fmac_f32_e32 v227, v140, v140
	v_fmac_f32_e32 v227, v141, v141
	v_fmac_f32_e32 v227, v142, v142
	v_fmac_f32_e32 v227, v143, v143
	v_fmac_f32_e32 v227, v144, v144
	v_fmac_f32_e32 v227, v145, v145
	v_fmac_f32_e32 v227, v146, v146
	v_fmac_f32_e32 v227, v147, v147
	v_fmac_f32_e32 v227, v148, v148
	v_fmac_f32_e32 v227, v149, v149
	v_xor_b32_e32 v195, 4, v243
	ds_bpermute_b32 v242, v195, v227
	s_waitcnt lgkmcnt(0)
	v_add_f32_e32 v227, v227, v242
	v_xor_b32_e32 v195, 8, v243
	ds_bpermute_b32 v242, v195, v227
	s_waitcnt lgkmcnt(0)
	v_add_f32_e32 v227, v227, v242
	v_xor_b32_e32 v195, 16, v243
	ds_bpermute_b32 v242, v195, v227
	s_waitcnt lgkmcnt(0)
	v_add_f32_e32 v227, v227, v242
	v_xor_b32_e32 v195, 32, v243
	ds_bpermute_b32 v242, v195, v227
	s_waitcnt lgkmcnt(0)
	v_add_f32_e32 v227, v227, v242
	v_xor_b32_e32 v195, 64, v243
	ds_bpermute_b32 v242, v195, v227
	s_waitcnt lgkmcnt(0)
	v_add_f32_e32 v227, v227, v242
	v_xor_b32_e32 v195, 128, v243
	ds_bpermute_b32 v242, v195, v227
	s_waitcnt lgkmcnt(0)
	v_add_f32_e32 v227, v227, v242
	v_mov_b32_e32 v240, 0x3a000000
	v_mov_b32_e32 v241, 0x358637bd
	v_fma_f32 v227, v227, v240, v241
	v_rsq_f32_e32 v227, v227
	s_lshl_b32 s97, s32, 12
	s_add_u32 s100, s34, s97
	s_addc_u32 s101, s35, 0
	s_add_u32 s100, s100, 0x9800000
	s_addc_u32 s101, s101, 0
	s_waitcnt vmcnt(4)
	v_mul_f32_e32 v118, v118, v227
	v_mul_f32_e32 v118, v118, v150
	v_mul_f32_e32 v119, v119, v227
	v_mul_f32_e32 v119, v119, v151
	v_mul_f32_e32 v120, v120, v227
	v_mul_f32_e32 v120, v120, v152
	v_mul_f32_e32 v121, v121, v227
	v_mul_f32_e32 v121, v121, v153
	v_mul_f32_e32 v122, v122, v227
	v_mul_f32_e32 v122, v122, v154
	v_mul_f32_e32 v123, v123, v227
	v_mul_f32_e32 v123, v123, v155
	v_mul_f32_e32 v124, v124, v227
	v_mul_f32_e32 v124, v124, v156
	v_mul_f32_e32 v125, v125, v227
	v_mul_f32_e32 v125, v125, v157
	v_mul_f32_e32 v126, v126, v227
	v_mul_f32_e32 v126, v126, v158
	v_mul_f32_e32 v127, v127, v227
	v_mul_f32_e32 v127, v127, v159
	v_mul_f32_e32 v128, v128, v227
	v_mul_f32_e32 v128, v128, v160
	v_mul_f32_e32 v129, v129, v227
	v_mul_f32_e32 v129, v129, v161
	v_mul_f32_e32 v130, v130, v227
	v_mul_f32_e32 v130, v130, v166
	v_mul_f32_e32 v131, v131, v227
	v_mul_f32_e32 v131, v131, v167
	v_mul_f32_e32 v132, v132, v227
	v_mul_f32_e32 v132, v132, v168
	v_mul_f32_e32 v133, v133, v227
	v_mul_f32_e32 v133, v133, v169
	v_mul_f32_e32 v134, v134, v227
	v_mul_f32_e32 v134, v134, v170
	v_mul_f32_e32 v135, v135, v227
	v_mul_f32_e32 v135, v135, v171
	v_mul_f32_e32 v136, v136, v227
	v_mul_f32_e32 v136, v136, v172
	v_mul_f32_e32 v137, v137, v227
	v_mul_f32_e32 v137, v137, v173
	v_mul_f32_e32 v138, v138, v227
	v_mul_f32_e32 v138, v138, v174
	v_mul_f32_e32 v139, v139, v227
	v_mul_f32_e32 v139, v139, v175
	v_mul_f32_e32 v140, v140, v227
	v_mul_f32_e32 v140, v140, v176
	v_mul_f32_e32 v141, v141, v227
	v_mul_f32_e32 v141, v141, v177
	v_mul_f32_e32 v142, v142, v227
	v_mul_f32_e32 v142, v142, v178
	v_mul_f32_e32 v143, v143, v227
	v_mul_f32_e32 v143, v143, v179
	v_mul_f32_e32 v144, v144, v227
	v_mul_f32_e32 v144, v144, v180
	v_mul_f32_e32 v145, v145, v227
	v_mul_f32_e32 v145, v145, v181
	v_mul_f32_e32 v146, v146, v227
	v_mul_f32_e32 v146, v146, v182
	v_mul_f32_e32 v147, v147, v227
	v_mul_f32_e32 v147, v147, v183
	v_mul_f32_e32 v148, v148, v227
	v_mul_f32_e32 v148, v148, v184
	v_mul_f32_e32 v149, v149, v227
	v_mul_f32_e32 v149, v149, v185
	v_cvt_pk_bf16_f32 v206, v118, v119
	v_cvt_pk_bf16_f32 v207, v120, v121
	v_cvt_pk_bf16_f32 v208, v122, v123
	v_cvt_pk_bf16_f32 v209, v124, v125
	global_store_dwordx4 v162, v[206:209], s[100:101]
	v_cvt_pk_bf16_f32 v210, v126, v127
	v_cvt_pk_bf16_f32 v211, v128, v129
	v_cvt_pk_bf16_f32 v212, v130, v131
	v_cvt_pk_bf16_f32 v213, v132, v133
	global_store_dwordx4 v162, v[210:213], s[100:101] offset:1024
	v_cvt_pk_bf16_f32 v214, v134, v135
	v_cvt_pk_bf16_f32 v215, v136, v137
	v_cvt_pk_bf16_f32 v216, v138, v139
	v_cvt_pk_bf16_f32 v217, v140, v141
	global_store_dwordx4 v162, v[214:217], s[100:101] offset:2048
	v_cvt_pk_bf16_f32 v218, v142, v143
	v_cvt_pk_bf16_f32 v219, v144, v145
	v_cvt_pk_bf16_f32 v220, v146, v147
	v_cvt_pk_bf16_f32 v221, v148, v149
	global_store_dwordx4 v162, v[218:221], s[100:101] offset:3072
	s_branch .LBB0_662

.LBB0_962:
	v_lshl_add_u32 v146, v165, 3, s81
	v_ashrrev_i32_e32 v147, 31, v146
	v_lshlrev_b64 v[156:157], 11, v[156:157]
	s_ashr_i32 s55, s54, 31
	v_lshl_add_u64 v[156:157], v[156:157], 0, v[146:147]
	s_lshl_b64 s[56:57], s[54:55], 12
	v_lshl_add_u64 v[156:157], v[156:157], 0, s[46:47]
	s_add_u32 s54, s71, s56
	s_addc_u32 s55, s72, s57
	v_lshlrev_b64 v[156:157], 1, v[156:157]
	v_lshl_add_u64 v[170:171], s[54:55], 0, v[156:157]
	flat_load_dwordx4 v[166:169], v[170:171] nt
	v_ashrrev_i32_e32 v155, 31, v154
	s_add_u32 s56, s73, s56
	v_lshlrev_b64 v[154:155], 11, v[154:155]
	s_addc_u32 s57, s74, s57
	v_lshl_add_u64 v[154:155], v[154:155], 0, v[146:147]
	v_lshl_add_u64 v[156:157], s[56:57], 0, v[156:157]
	v_lshl_add_u64 v[154:155], v[154:155], 0, s[46:47]
	v_lshlrev_b64 v[154:155], 1, v[154:155]
	v_ashrrev_i32_e32 v153, 31, v152
	v_ashrrev_i32_e32 v151, 31, v150
	v_ashrrev_i32_e32 v149, 31, v148
	v_ashrrev_i32_e32 v145, 31, v144
	v_ashrrev_i32_e32 v143, 31, v142
	v_ashrrev_i32_e32 v141, 31, v140
	global_load_dwordx4 v[232:235], v[170:171], off offset:256 nt
	v_lshl_add_u64 v[198:199], s[54:55], 0, v[154:155]
	global_load_dwordx4 v[236:239], v[198:199], off nt
	v_lshl_add_u64 v[198:199], s[54:55], 0, v[154:155]
	global_load_dwordx4 v[240:243], v[198:199], off offset:256 nt
	v_lshlrev_b64 v[198:199], 11, v[152:153]
	v_lshl_add_u64 v[200:201], v[198:199], 0, v[146:147]
	v_lshl_add_u64 v[202:203], v[200:201], 0, s[46:47]
	v_lshlrev_b64 v[204:205], 1, v[202:203]
	v_lshl_add_u64 v[206:207], s[54:55], 0, v[204:205]
	global_load_dwordx4 v[244:247], v[206:207], off nt
	v_lshlrev_b64 v[198:199], 11, v[152:153]
	v_lshl_add_u64 v[200:201], v[198:199], 0, v[146:147]
	v_lshl_add_u64 v[202:203], v[200:201], 0, s[46:47]
	v_lshlrev_b64 v[204:205], 1, v[202:203]
	v_lshl_add_u64 v[206:207], s[54:55], 0, v[204:205]
	global_load_dwordx4 v[248:251], v[206:207], off offset:256 nt
	v_lshlrev_b64 v[198:199], 11, v[150:151]
	v_lshl_add_u64 v[200:201], v[198:199], 0, v[146:147]
	v_lshl_add_u64 v[202:203], v[200:201], 0, s[46:47]
	v_lshlrev_b64 v[204:205], 1, v[202:203]
	v_lshl_add_u64 v[206:207], s[54:55], 0, v[204:205]
	global_load_dwordx4 v[252:255], v[206:207], off nt
	s_waitcnt vmcnt(6) lgkmcnt(0)
	v_lshlrev_b64 v[198:199], 11, v[150:151]
	v_lshl_add_u64 v[200:201], v[198:199], 0, v[146:147]
	v_lshl_add_u64 v[202:203], v[200:201], 0, s[46:47]
	v_lshlrev_b64 v[204:205], 1, v[202:203]
	v_lshl_add_u64 v[206:207], s[54:55], 0, v[204:205]
	global_load_dwordx4 v[228:231], v[206:207], off offset:256 nt
	v_lshlrev_b32_e32 v172, 16, v166
	v_and_b32_e32 v173, 0xffff0000, v166
	v_lshlrev_b32_e32 v166, 16, v167
	v_and_b32_e32 v167, 0xffff0000, v167
	v_lshlrev_b32_e32 v174, 16, v168
	v_and_b32_e32 v175, 0xffff0000, v168
	v_lshlrev_b32_e32 v168, 16, v169
	v_and_b32_e32 v169, 0xffff0000, v169
	v_pk_add_f32 v[126:127], v[126:127], v[166:167]
	v_pk_add_f32 v[124:125], v[124:125], v[172:173]
	v_pk_add_f32 v[166:167], v[122:123], v[168:169]
	v_pk_add_f32 v[122:123], v[120:121], v[174:175]
	v_cvt_pk_bf16_f32 v120, v124, v125
	v_cvt_pk_bf16_f32 v121, v126, v127
	s_nop 0
	v_cvt_pk_bf16_f32 v122, v122, v123
	v_cvt_pk_bf16_f32 v123, v166, v167
	v_lshl_add_u64 v[166:167], s[54:55], 0, v[154:155]
	flat_store_dwordx4 v[156:157], v[120:123]
	s_waitcnt vmcnt(7) lgkmcnt(0)
	s_nop 1
	v_mov_b32_e32 v124, v232
	v_mov_b32_e32 v125, v233
	v_mov_b32_e32 v126, v234
	v_mov_b32_e32 v127, v235
	v_lshlrev_b64 v[198:199], 11, v[148:149]
	v_lshl_add_u64 v[200:201], v[198:199], 0, v[146:147]
	v_lshl_add_u64 v[202:203], v[200:201], 0, s[46:47]
	v_lshlrev_b64 v[204:205], 1, v[202:203]
	v_lshl_add_u64 v[206:207], s[54:55], 0, v[204:205]
	global_load_dwordx4 v[232:235], v[206:207], off nt
	s_nop 0
	v_lshlrev_b32_e32 v120, 16, v124
	v_and_b32_e32 v121, 0xffff0000, v124
	v_lshlrev_b32_e32 v122, 16, v125
	v_and_b32_e32 v123, 0xffff0000, v125
	v_lshlrev_b32_e32 v124, 16, v126
	v_and_b32_e32 v125, 0xffff0000, v126
	v_lshlrev_b32_e32 v126, 16, v127
	v_and_b32_e32 v127, 0xffff0000, v127
	v_pk_add_f32 v[116:117], v[116:117], v[120:121]
	v_pk_add_f32 v[120:121], v[114:115], v[126:127]
	v_pk_add_f32 v[114:115], v[112:113], v[124:125]
	v_pk_add_f32 v[118:119], v[118:119], v[122:123]
	v_cvt_pk_bf16_f32 v112, v116, v117
	s_nop 0
	v_cvt_pk_bf16_f32 v113, v118, v119
	v_cvt_pk_bf16_f32 v114, v114, v115
	v_cvt_pk_bf16_f32 v115, v120, v121
	flat_store_dwordx4 v[156:157], v[112:115] offset:256
	s_waitcnt vmcnt(8) lgkmcnt(0)
	s_nop 1
	v_mov_b32_e32 v112, v236
	v_mov_b32_e32 v113, v237
	v_mov_b32_e32 v114, v238
	v_mov_b32_e32 v115, v239
	v_lshlrev_b64 v[198:199], 11, v[148:149]
	v_lshl_add_u64 v[200:201], v[198:199], 0, v[146:147]
	v_lshl_add_u64 v[202:203], v[200:201], 0, s[46:47]
	v_lshlrev_b64 v[204:205], 1, v[202:203]
	v_lshl_add_u64 v[206:207], s[54:55], 0, v[204:205]
	global_load_dwordx4 v[236:239], v[206:207], off offset:256 nt
	v_lshlrev_b32_e32 v116, 16, v112
	v_and_b32_e32 v117, 0xffff0000, v112
	v_lshlrev_b32_e32 v112, 16, v113
	v_and_b32_e32 v113, 0xffff0000, v113
	v_lshlrev_b32_e32 v118, 16, v114
	v_and_b32_e32 v119, 0xffff0000, v114
	v_lshlrev_b32_e32 v114, 16, v115
	v_and_b32_e32 v115, 0xffff0000, v115
	v_pk_add_f32 v[110:111], v[110:111], v[112:113]
	v_pk_add_f32 v[108:109], v[108:109], v[116:117]
	v_pk_add_f32 v[112:113], v[106:107], v[114:115]
	v_pk_add_f32 v[106:107], v[104:105], v[118:119]
	v_cvt_pk_bf16_f32 v104, v108, v109
	v_cvt_pk_bf16_f32 v105, v110, v111
	v_lshl_add_u64 v[116:117], s[56:57], 0, v[154:155]
	v_cvt_pk_bf16_f32 v106, v106, v107
	v_cvt_pk_bf16_f32 v107, v112, v113
	v_lshlrev_b64 v[112:113], 11, v[152:153]
	v_lshl_add_u64 v[112:113], v[112:113], 0, v[146:147]
	v_lshl_add_u64 v[112:113], v[112:113], 0, s[46:47]
	flat_store_dwordx4 v[116:117], v[104:107]
	v_lshlrev_b64 v[112:113], 1, v[112:113]
	v_lshl_add_u64 v[114:115], s[54:55], 0, v[112:113]
	s_waitcnt vmcnt(9) lgkmcnt(0)
	s_nop 1
	v_mov_b32_e32 v108, v240
	v_mov_b32_e32 v109, v241
	v_mov_b32_e32 v110, v242
	v_mov_b32_e32 v111, v243
	v_lshlrev_b64 v[198:199], 11, v[144:145]
	v_lshl_add_u64 v[200:201], v[198:199], 0, v[146:147]
	v_lshl_add_u64 v[202:203], v[200:201], 0, s[46:47]
	v_lshlrev_b64 v[204:205], 1, v[202:203]
	v_lshl_add_u64 v[206:207], s[54:55], 0, v[204:205]
	global_load_dwordx4 v[240:243], v[206:207], off nt
	v_lshlrev_b32_e32 v104, 16, v108
	v_and_b32_e32 v105, 0xffff0000, v108
	v_lshlrev_b32_e32 v106, 16, v109
	v_and_b32_e32 v107, 0xffff0000, v109
	v_lshlrev_b32_e32 v108, 16, v110
	v_and_b32_e32 v109, 0xffff0000, v110
	v_lshlrev_b32_e32 v110, 16, v111
	v_and_b32_e32 v111, 0xffff0000, v111
	v_pk_add_f32 v[100:101], v[100:101], v[104:105]
	v_pk_add_f32 v[104:105], v[98:99], v[110:111]
	v_pk_add_f32 v[98:99], v[96:97], v[108:109]
	v_pk_add_f32 v[102:103], v[102:103], v[106:107]
	v_cvt_pk_bf16_f32 v96, v100, v101
	s_nop 0
	v_cvt_pk_bf16_f32 v97, v102, v103
	v_cvt_pk_bf16_f32 v98, v98, v99
	v_cvt_pk_bf16_f32 v99, v104, v105
	flat_store_dwordx4 v[116:117], v[96:99] offset:256
	s_waitcnt vmcnt(10) lgkmcnt(0)
	s_nop 1
	v_mov_b32_e32 v96, v244
	v_mov_b32_e32 v97, v245
	v_mov_b32_e32 v98, v246
	v_mov_b32_e32 v99, v247
	v_lshlrev_b64 v[198:199], 11, v[144:145]
	v_lshl_add_u64 v[200:201], v[198:199], 0, v[146:147]
	v_lshl_add_u64 v[202:203], v[200:201], 0, s[46:47]
	v_lshlrev_b64 v[204:205], 1, v[202:203]
	v_lshl_add_u64 v[206:207], s[54:55], 0, v[204:205]
	global_load_dwordx4 v[244:247], v[206:207], off offset:256 nt
	v_lshlrev_b32_e32 v100, 16, v96
	v_and_b32_e32 v101, 0xffff0000, v96
	v_lshlrev_b32_e32 v96, 16, v97
	v_and_b32_e32 v97, 0xffff0000, v97
	v_lshlrev_b32_e32 v102, 16, v98
	v_and_b32_e32 v103, 0xffff0000, v98
	v_lshlrev_b32_e32 v98, 16, v99
	v_and_b32_e32 v99, 0xffff0000, v99
	v_pk_add_f32 v[94:95], v[94:95], v[96:97]
	v_pk_add_f32 v[92:93], v[92:93], v[100:101]
	v_pk_add_f32 v[96:97], v[90:91], v[98:99]
	v_pk_add_f32 v[90:91], v[88:89], v[102:103]
	v_cvt_pk_bf16_f32 v88, v92, v93
	v_cvt_pk_bf16_f32 v89, v94, v95
	v_lshl_add_u64 v[100:101], s[56:57], 0, v[112:113]
	v_cvt_pk_bf16_f32 v90, v90, v91
	v_cvt_pk_bf16_f32 v91, v96, v97
	v_lshlrev_b64 v[96:97], 11, v[150:151]
	v_lshl_add_u64 v[96:97], v[96:97], 0, v[146:147]
	v_lshl_add_u64 v[96:97], v[96:97], 0, s[46:47]
	flat_store_dwordx4 v[100:101], v[88:91]
	v_lshlrev_b64 v[96:97], 1, v[96:97]
	v_lshl_add_u64 v[98:99], s[54:55], 0, v[96:97]
	s_waitcnt vmcnt(11) lgkmcnt(0)
	s_nop 1
	v_mov_b32_e32 v92, v248
	v_mov_b32_e32 v93, v249
	v_mov_b32_e32 v94, v250
	v_mov_b32_e32 v95, v251
	v_lshlrev_b64 v[198:199], 11, v[142:143]
	v_lshl_add_u64 v[200:201], v[198:199], 0, v[146:147]
	v_lshl_add_u64 v[202:203], v[200:201], 0, s[46:47]
	v_lshlrev_b64 v[204:205], 1, v[202:203]
	v_lshl_add_u64 v[206:207], s[54:55], 0, v[204:205]
	global_load_dwordx4 v[248:251], v[206:207], off nt
	v_lshlrev_b32_e32 v88, 16, v92
	v_and_b32_e32 v89, 0xffff0000, v92
	v_lshlrev_b32_e32 v90, 16, v93
	v_and_b32_e32 v91, 0xffff0000, v93
	v_lshlrev_b32_e32 v92, 16, v94
	v_and_b32_e32 v93, 0xffff0000, v94
	v_lshlrev_b32_e32 v94, 16, v95
	v_and_b32_e32 v95, 0xffff0000, v95
	v_pk_add_f32 v[84:85], v[84:85], v[88:89]
	v_pk_add_f32 v[88:89], v[82:83], v[94:95]
	v_pk_add_f32 v[82:83], v[80:81], v[92:93]
	v_pk_add_f32 v[86:87], v[86:87], v[90:91]
	v_cvt_pk_bf16_f32 v80, v84, v85
	s_nop 0
	v_cvt_pk_bf16_f32 v81, v86, v87
	v_cvt_pk_bf16_f32 v82, v82, v83
	v_cvt_pk_bf16_f32 v83, v88, v89
	flat_store_dwordx4 v[100:101], v[80:83] offset:256
	s_waitcnt vmcnt(12) lgkmcnt(0)
	s_nop 1
	v_mov_b32_e32 v80, v252
	v_mov_b32_e32 v81, v253
	v_mov_b32_e32 v82, v254
	v_mov_b32_e32 v83, v255
	v_lshlrev_b64 v[198:199], 11, v[142:143]
	v_lshl_add_u64 v[200:201], v[198:199], 0, v[146:147]
	v_lshl_add_u64 v[202:203], v[200:201], 0, s[46:47]
	v_lshlrev_b64 v[204:205], 1, v[202:203]
	v_lshl_add_u64 v[206:207], s[54:55], 0, v[204:205]
	global_load_dwordx4 v[252:255], v[206:207], off offset:256 nt
	v_lshlrev_b32_e32 v84, 16, v80
	v_and_b32_e32 v85, 0xffff0000, v80
	v_lshlrev_b32_e32 v80, 16, v81
	v_and_b32_e32 v81, 0xffff0000, v81
	v_lshlrev_b32_e32 v86, 16, v82
	v_and_b32_e32 v87, 0xffff0000, v82
	v_lshlrev_b32_e32 v82, 16, v83
	v_and_b32_e32 v83, 0xffff0000, v83
	v_pk_add_f32 v[78:79], v[78:79], v[80:81]
	v_pk_add_f32 v[76:77], v[76:77], v[84:85]
	v_pk_add_f32 v[80:81], v[74:75], v[82:83]
	v_pk_add_f32 v[74:75], v[72:73], v[86:87]
	v_cvt_pk_bf16_f32 v72, v76, v77
	v_cvt_pk_bf16_f32 v73, v78, v79
	v_lshl_add_u64 v[84:85], s[56:57], 0, v[96:97]
	v_cvt_pk_bf16_f32 v74, v74, v75
	v_cvt_pk_bf16_f32 v75, v80, v81
	v_lshlrev_b64 v[80:81], 11, v[148:149]
	v_lshl_add_u64 v[80:81], v[80:81], 0, v[146:147]
	v_lshl_add_u64 v[80:81], v[80:81], 0, s[46:47]
	flat_store_dwordx4 v[84:85], v[72:75]
	v_lshlrev_b64 v[80:81], 1, v[80:81]
	v_lshl_add_u64 v[82:83], s[54:55], 0, v[80:81]
	s_waitcnt vmcnt(13) lgkmcnt(0)
	s_nop 1
	v_mov_b32_e32 v76, v228
	v_mov_b32_e32 v77, v229
	v_mov_b32_e32 v78, v230
	v_mov_b32_e32 v79, v231
	v_lshlrev_b64 v[198:199], 11, v[140:141]
	v_lshl_add_u64 v[200:201], v[198:199], 0, v[146:147]
	v_lshl_add_u64 v[202:203], v[200:201], 0, s[46:47]
	v_lshlrev_b64 v[204:205], 1, v[202:203]
	v_lshl_add_u64 v[206:207], s[54:55], 0, v[204:205]
	global_load_dwordx4 v[228:231], v[206:207], off nt
	v_lshlrev_b32_e32 v72, 16, v76
	v_and_b32_e32 v73, 0xffff0000, v76
	v_lshlrev_b32_e32 v74, 16, v77
	v_and_b32_e32 v75, 0xffff0000, v77
	v_lshlrev_b32_e32 v76, 16, v78
	v_and_b32_e32 v77, 0xffff0000, v78
	v_lshlrev_b32_e32 v78, 16, v79
	v_and_b32_e32 v79, 0xffff0000, v79
	v_pk_add_f32 v[68:69], v[68:69], v[72:73]
	v_pk_add_f32 v[72:73], v[66:67], v[78:79]
	v_pk_add_f32 v[66:67], v[64:65], v[76:77]
	v_pk_add_f32 v[70:71], v[70:71], v[74:75]
	v_cvt_pk_bf16_f32 v64, v68, v69
	s_nop 0
	v_cvt_pk_bf16_f32 v65, v70, v71
	v_cvt_pk_bf16_f32 v66, v66, v67
	v_cvt_pk_bf16_f32 v67, v72, v73
	flat_store_dwordx4 v[84:85], v[64:67] offset:256
	s_waitcnt vmcnt(13) lgkmcnt(0)
	s_nop 1
	v_mov_b32_e32 v64, v232
	v_mov_b32_e32 v65, v233
	v_mov_b32_e32 v66, v234
	v_mov_b32_e32 v67, v235
	v_lshlrev_b64 v[198:199], 11, v[140:141]
	v_lshl_add_u64 v[200:201], v[198:199], 0, v[146:147]
	v_lshl_add_u64 v[202:203], v[200:201], 0, s[46:47]
	v_lshlrev_b64 v[204:205], 1, v[202:203]
	v_lshl_add_u64 v[206:207], s[54:55], 0, v[204:205]
	global_load_dwordx4 v[232:235], v[206:207], off offset:256 nt
	v_lshlrev_b32_e32 v68, 16, v64
	v_and_b32_e32 v69, 0xffff0000, v64
	v_lshlrev_b32_e32 v64, 16, v65
	v_and_b32_e32 v65, 0xffff0000, v65
	v_lshlrev_b32_e32 v70, 16, v66
	v_and_b32_e32 v71, 0xffff0000, v66
	v_lshlrev_b32_e32 v66, 16, v67
	v_and_b32_e32 v67, 0xffff0000, v67
	v_pk_add_f32 v[62:63], v[62:63], v[64:65]
	v_pk_add_f32 v[60:61], v[60:61], v[68:69]
	v_pk_add_f32 v[64:65], v[58:59], v[66:67]
	v_pk_add_f32 v[58:59], v[56:57], v[70:71]
	v_cvt_pk_bf16_f32 v56, v60, v61
	v_cvt_pk_bf16_f32 v57, v62, v63
	v_lshl_add_u64 v[68:69], s[56:57], 0, v[80:81]
	v_cvt_pk_bf16_f32 v58, v58, v59
	v_cvt_pk_bf16_f32 v59, v64, v65
	v_lshlrev_b64 v[64:65], 11, v[144:145]
	v_lshl_add_u64 v[64:65], v[64:65], 0, v[146:147]
	v_lshl_add_u64 v[64:65], v[64:65], 0, s[46:47]
	flat_store_dwordx4 v[68:69], v[56:59]
	v_lshlrev_b64 v[64:65], 1, v[64:65]
	v_lshl_add_u64 v[66:67], s[54:55], 0, v[64:65]
	s_waitcnt vmcnt(13) lgkmcnt(0)
	s_nop 1
	v_mov_b32_e32 v60, v236
	v_mov_b32_e32 v61, v237
	v_mov_b32_e32 v62, v238
	v_mov_b32_e32 v63, v239
	v_lshlrev_b32_e32 v56, 16, v60
	v_and_b32_e32 v57, 0xffff0000, v60
	v_lshlrev_b32_e32 v58, 16, v61
	v_and_b32_e32 v59, 0xffff0000, v61
	v_lshlrev_b32_e32 v60, 16, v62
	v_and_b32_e32 v61, 0xffff0000, v62
	v_lshlrev_b32_e32 v62, 16, v63
	v_and_b32_e32 v63, 0xffff0000, v63
	v_pk_add_f32 v[52:53], v[52:53], v[56:57]
	v_pk_add_f32 v[56:57], v[50:51], v[62:63]
	v_pk_add_f32 v[50:51], v[48:49], v[60:61]
	v_pk_add_f32 v[54:55], v[54:55], v[58:59]
	v_cvt_pk_bf16_f32 v48, v52, v53
	s_nop 0
	v_cvt_pk_bf16_f32 v49, v54, v55
	v_cvt_pk_bf16_f32 v50, v50, v51
	v_cvt_pk_bf16_f32 v51, v56, v57
	flat_store_dwordx4 v[68:69], v[48:51] offset:256
	s_waitcnt vmcnt(12) lgkmcnt(0)
	s_nop 1
	v_mov_b32_e32 v48, v240
	v_mov_b32_e32 v49, v241
	v_mov_b32_e32 v50, v242
	v_mov_b32_e32 v51, v243
	v_lshlrev_b32_e32 v52, 16, v48
	v_and_b32_e32 v53, 0xffff0000, v48
	v_lshlrev_b32_e32 v48, 16, v49
	v_and_b32_e32 v49, 0xffff0000, v49
	v_lshlrev_b32_e32 v54, 16, v50
	v_and_b32_e32 v55, 0xffff0000, v50
	v_lshlrev_b32_e32 v50, 16, v51
	v_and_b32_e32 v51, 0xffff0000, v51
	v_pk_add_f32 v[46:47], v[46:47], v[48:49]
	v_pk_add_f32 v[44:45], v[44:45], v[52:53]
	v_pk_add_f32 v[48:49], v[42:43], v[50:51]
	v_pk_add_f32 v[42:43], v[40:41], v[54:55]
	v_cvt_pk_bf16_f32 v40, v44, v45
	v_cvt_pk_bf16_f32 v41, v46, v47
	v_lshl_add_u64 v[52:53], s[56:57], 0, v[64:65]
	v_cvt_pk_bf16_f32 v42, v42, v43
	v_cvt_pk_bf16_f32 v43, v48, v49
	v_lshlrev_b64 v[48:49], 11, v[142:143]
	v_lshl_add_u64 v[48:49], v[48:49], 0, v[146:147]
	v_lshl_add_u64 v[48:49], v[48:49], 0, s[46:47]
	flat_store_dwordx4 v[52:53], v[40:43]
	v_lshlrev_b64 v[48:49], 1, v[48:49]
	v_lshl_add_u64 v[50:51], s[54:55], 0, v[48:49]
	s_waitcnt vmcnt(11) lgkmcnt(0)
	s_nop 1
	v_mov_b32_e32 v44, v244
	v_mov_b32_e32 v45, v245
	v_mov_b32_e32 v46, v246
	v_mov_b32_e32 v47, v247
	v_lshlrev_b32_e32 v40, 16, v44
	v_and_b32_e32 v41, 0xffff0000, v44
	v_lshlrev_b32_e32 v42, 16, v45
	v_and_b32_e32 v43, 0xffff0000, v45
	v_lshlrev_b32_e32 v44, 16, v46
	v_and_b32_e32 v45, 0xffff0000, v46
	v_lshlrev_b32_e32 v46, 16, v47
	v_and_b32_e32 v47, 0xffff0000, v47
	v_pk_add_f32 v[36:37], v[36:37], v[40:41]
	v_pk_add_f32 v[40:41], v[34:35], v[46:47]
	v_pk_add_f32 v[34:35], v[32:33], v[44:45]
	v_pk_add_f32 v[38:39], v[38:39], v[42:43]
	v_cvt_pk_bf16_f32 v32, v36, v37
	s_nop 0
	v_cvt_pk_bf16_f32 v33, v38, v39
	v_cvt_pk_bf16_f32 v34, v34, v35
	v_cvt_pk_bf16_f32 v35, v40, v41
	flat_store_dwordx4 v[52:53], v[32:35] offset:256
	s_waitcnt vmcnt(10) lgkmcnt(0)
	s_nop 1
	v_mov_b32_e32 v32, v248
	v_mov_b32_e32 v33, v249
	v_mov_b32_e32 v34, v250
	v_mov_b32_e32 v35, v251
	v_lshlrev_b32_e32 v36, 16, v32
	v_and_b32_e32 v37, 0xffff0000, v32
	v_lshlrev_b32_e32 v32, 16, v33
	v_and_b32_e32 v33, 0xffff0000, v33
	v_lshlrev_b32_e32 v38, 16, v34
	v_and_b32_e32 v39, 0xffff0000, v34
	v_lshlrev_b32_e32 v34, 16, v35
	v_and_b32_e32 v35, 0xffff0000, v35
	v_pk_add_f32 v[30:31], v[30:31], v[32:33]
	v_pk_add_f32 v[28:29], v[28:29], v[36:37]
	v_pk_add_f32 v[32:33], v[26:27], v[34:35]
	v_pk_add_f32 v[26:27], v[24:25], v[38:39]
	v_cvt_pk_bf16_f32 v24, v28, v29
	v_cvt_pk_bf16_f32 v25, v30, v31
	v_lshl_add_u64 v[36:37], s[56:57], 0, v[48:49]
	v_cvt_pk_bf16_f32 v26, v26, v27
	v_cvt_pk_bf16_f32 v27, v32, v33
	v_lshlrev_b64 v[32:33], 11, v[140:141]
	v_lshl_add_u64 v[32:33], v[32:33], 0, v[146:147]
	v_lshl_add_u64 v[32:33], v[32:33], 0, s[46:47]
	flat_store_dwordx4 v[36:37], v[24:27]
	v_lshlrev_b64 v[32:33], 1, v[32:33]
	v_lshl_add_u64 v[34:35], s[54:55], 0, v[32:33]
	s_waitcnt vmcnt(9) lgkmcnt(0)
	s_nop 1
	v_mov_b32_e32 v28, v252
	v_mov_b32_e32 v29, v253
	v_mov_b32_e32 v30, v254
	v_mov_b32_e32 v31, v255
	v_lshlrev_b32_e32 v24, 16, v28
	v_and_b32_e32 v25, 0xffff0000, v28
	v_lshlrev_b32_e32 v26, 16, v29
	v_and_b32_e32 v27, 0xffff0000, v29
	v_lshlrev_b32_e32 v28, 16, v30
	v_and_b32_e32 v29, 0xffff0000, v30
	v_lshlrev_b32_e32 v30, 16, v31
	v_and_b32_e32 v31, 0xffff0000, v31
	v_pk_add_f32 v[20:21], v[20:21], v[24:25]
	v_pk_add_f32 v[24:25], v[18:19], v[30:31]
	v_pk_add_f32 v[18:19], v[16:17], v[28:29]
	v_pk_add_f32 v[22:23], v[22:23], v[26:27]
	v_cvt_pk_bf16_f32 v16, v20, v21
	s_nop 0
	v_cvt_pk_bf16_f32 v17, v22, v23
	v_cvt_pk_bf16_f32 v18, v18, v19
	v_cvt_pk_bf16_f32 v19, v24, v25
	flat_store_dwordx4 v[36:37], v[16:19] offset:256
	s_waitcnt vmcnt(8) lgkmcnt(0)
	s_nop 1
	v_mov_b32_e32 v16, v228
	v_mov_b32_e32 v17, v229
	v_mov_b32_e32 v18, v230
	v_mov_b32_e32 v19, v231
	v_lshlrev_b32_e32 v20, 16, v16
	v_and_b32_e32 v21, 0xffff0000, v16
	v_lshlrev_b32_e32 v16, 16, v17
	v_and_b32_e32 v17, 0xffff0000, v17
	v_lshlrev_b32_e32 v22, 16, v18
	v_and_b32_e32 v23, 0xffff0000, v18
	v_lshlrev_b32_e32 v18, 16, v19
	v_and_b32_e32 v19, 0xffff0000, v19
	v_pk_add_f32 v[14:15], v[14:15], v[16:17]
	v_pk_add_f32 v[12:13], v[12:13], v[20:21]
	v_pk_add_f32 v[16:17], v[10:11], v[18:19]
	v_pk_add_f32 v[10:11], v[8:9], v[22:23]
	v_cvt_pk_bf16_f32 v8, v12, v13
	v_cvt_pk_bf16_f32 v9, v14, v15
	s_nop 0
	v_cvt_pk_bf16_f32 v10, v10, v11
	v_cvt_pk_bf16_f32 v11, v16, v17
	v_lshl_add_u64 v[16:17], s[56:57], 0, v[32:33]
	flat_store_dwordx4 v[16:17], v[8:11]
	s_waitcnt vmcnt(7) lgkmcnt(0)
	s_nop 1
	v_mov_b32_e32 v12, v232
	v_mov_b32_e32 v13, v233
	v_mov_b32_e32 v14, v234
	v_mov_b32_e32 v15, v235
	s_nop 0
	v_lshlrev_b32_e32 v8, 16, v12
	v_and_b32_e32 v9, 0xffff0000, v12
	v_lshlrev_b32_e32 v10, 16, v13
	v_and_b32_e32 v11, 0xffff0000, v13
	v_lshlrev_b32_e32 v12, 16, v14
	v_and_b32_e32 v13, 0xffff0000, v14
	v_lshlrev_b32_e32 v14, 16, v15
	v_and_b32_e32 v15, 0xffff0000, v15
	v_pk_add_f32 v[4:5], v[4:5], v[8:9]
	v_pk_add_f32 v[8:9], v[2:3], v[14:15]
	v_pk_add_f32 v[2:3], v[0:1], v[12:13]
	v_pk_add_f32 v[6:7], v[6:7], v[10:11]
	v_cvt_pk_bf16_f32 v0, v4, v5
	s_nop 0
	v_cvt_pk_bf16_f32 v1, v6, v7
	v_cvt_pk_bf16_f32 v2, v2, v3
	v_cvt_pk_bf16_f32 v3, v8, v9
	flat_store_dwordx4 v[16:17], v[0:3] offset:256

.LBB0_1028:
	s_cmpk_lg_i32 s26, 0x100
	s_cbranch_scc1 .Lsrow_r2_orig
	s_add_i32 s93, s48, 0xffffe000
	s_and_b32 s97, s93, 7
	s_cmp_gt_u32 s97, 3
	s_cbranch_scc1 .LBB0_1042
	s_lshr_b32 s93, s93, 3
	s_lshl_b32 s93, s93, 2
	s_add_i32 s93, s93, s97
	s_add_i32 s32, s93, 0x2000
	s_waitcnt lgkmcnt(0)
	v_and_b32_e32 v195, 63, v164
	v_lshlrev_b32_e32 v162, 4, v195
	v_lshlrev_b32_e32 v163, 5, v195
	v_lshlrev_b32_e32 v243, 2, v195
	v_add_u32_e32 v194, 0x1000, v163
	s_lshl_b32 s97, s93, 12
	s_add_u32 s98, s34, s97
	s_addc_u32 s99, s35, 0
	s_add_u32 s98, s98, 0x19600000
	s_addc_u32 s99, s99, 0
	s_lshl_b32 s97, s32, 12
	s_add_u32 s94, s34, s97
	s_addc_u32 s95, s35, 0
	s_add_u32 s94, s94, 0x20200000
	s_addc_u32 s95, s95, 0
	global_load_dwordx4 v[222:225], v162, s[94:95] nt
	global_load_dwordx4 v[228:231], v162, s[94:95] offset:1024 nt
	global_load_dwordx4 v[232:235], v162, s[94:95] offset:2048 nt
	global_load_dwordx4 v[236:239], v162, s[94:95] offset:3072 nt
	global_load_dwordx4 v[150:153], v162, s[98:99] nt
	global_load_dwordx4 v[154:157], v162, s[98:99] offset:1024 nt
	global_load_dwordx4 v[158:161], v162, s[98:99] offset:2048 nt
	global_load_dwordx4 v[166:169], v162, s[98:99] offset:3072 nt
	s_add_u32 s98, s98, 0x400000
	s_addc_u32 s99, s99, 0
	global_load_dwordx4 v[170:173], v162, s[98:99] nt
	global_load_dwordx4 v[174:177], v162, s[98:99] offset:1024 nt
	global_load_dwordx4 v[178:181], v162, s[98:99] offset:2048 nt
	global_load_dwordx4 v[182:185], v162, s[98:99] offset:3072 nt
	s_add_u32 s98, s98, 0x400000
	s_addc_u32 s99, s99, 0
	global_load_dwordx4 v[186:189], v162, s[98:99] nt
	global_load_dwordx4 v[190:193], v162, s[98:99] offset:1024 nt
	global_load_dwordx4 v[198:201], v162, s[98:99] offset:2048 nt
	global_load_dwordx4 v[202:205], v162, s[98:99] offset:3072 nt
	s_add_u32 s98, s98, 0x400000
	s_addc_u32 s99, s99, 0
	global_load_dwordx4 v[206:209], v162, s[98:99] nt
	global_load_dwordx4 v[210:213], v162, s[98:99] offset:1024 nt
	global_load_dwordx4 v[214:217], v162, s[98:99] offset:2048 nt
	global_load_dwordx4 v[218:221], v162, s[98:99] offset:3072 nt
	s_add_u32 s98, s98, 0x400000
	s_addc_u32 s99, s99, 0
	s_waitcnt vmcnt(16)
	v_lshlrev_b32_e32 v118, 16, v222
	v_and_b32_e32 v119, 0xffff0000, v222
	v_lshlrev_b32_e32 v120, 16, v223
	v_and_b32_e32 v121, 0xffff0000, v223
	v_lshlrev_b32_e32 v122, 16, v224
	v_and_b32_e32 v123, 0xffff0000, v224
	v_lshlrev_b32_e32 v124, 16, v225
	v_and_b32_e32 v125, 0xffff0000, v225
	v_lshlrev_b32_e32 v126, 16, v228
	v_and_b32_e32 v127, 0xffff0000, v228
	v_lshlrev_b32_e32 v128, 16, v229
	v_and_b32_e32 v129, 0xffff0000, v229
	v_lshlrev_b32_e32 v130, 16, v230
	v_and_b32_e32 v131, 0xffff0000, v230
	v_lshlrev_b32_e32 v132, 16, v231
	v_and_b32_e32 v133, 0xffff0000, v231
	v_lshlrev_b32_e32 v134, 16, v232
	v_and_b32_e32 v135, 0xffff0000, v232
	v_lshlrev_b32_e32 v136, 16, v233
	v_and_b32_e32 v137, 0xffff0000, v233
	v_lshlrev_b32_e32 v138, 16, v234
	v_and_b32_e32 v139, 0xffff0000, v234
	v_lshlrev_b32_e32 v140, 16, v235
	v_and_b32_e32 v141, 0xffff0000, v235
	v_lshlrev_b32_e32 v142, 16, v236
	v_and_b32_e32 v143, 0xffff0000, v236
	v_lshlrev_b32_e32 v144, 16, v237
	v_and_b32_e32 v145, 0xffff0000, v237
	v_lshlrev_b32_e32 v146, 16, v238
	v_and_b32_e32 v147, 0xffff0000, v238
	v_lshlrev_b32_e32 v148, 16, v239
	v_and_b32_e32 v149, 0xffff0000, v239
	s_waitcnt vmcnt(12)
	v_lshlrev_b32_e32 v195, 16, v150
	v_and_b32_e32 v197, 0xffff0000, v150
	v_add_f32_e32 v118, v118, v195
	v_add_f32_e32 v119, v119, v197
	v_lshlrev_b32_e32 v195, 16, v151
	v_and_b32_e32 v197, 0xffff0000, v151
	v_add_f32_e32 v120, v120, v195
	v_add_f32_e32 v121, v121, v197
	v_lshlrev_b32_e32 v195, 16, v152
	v_and_b32_e32 v197, 0xffff0000, v152
	v_add_f32_e32 v122, v122, v195
	v_add_f32_e32 v123, v123, v197
	v_lshlrev_b32_e32 v195, 16, v153
	v_and_b32_e32 v197, 0xffff0000, v153
	v_add_f32_e32 v124, v124, v195
	v_add_f32_e32 v125, v125, v197
	v_lshlrev_b32_e32 v195, 16, v154
	v_and_b32_e32 v197, 0xffff0000, v154
	v_add_f32_e32 v126, v126, v195
	v_add_f32_e32 v127, v127, v197
	v_lshlrev_b32_e32 v195, 16, v155
	v_and_b32_e32 v197, 0xffff0000, v155
	v_add_f32_e32 v128, v128, v195
	v_add_f32_e32 v129, v129, v197
	v_lshlrev_b32_e32 v195, 16, v156
	v_and_b32_e32 v197, 0xffff0000, v156
	v_add_f32_e32 v130, v130, v195
	v_add_f32_e32 v131, v131, v197
	v_lshlrev_b32_e32 v195, 16, v157
	v_and_b32_e32 v197, 0xffff0000, v157
	v_add_f32_e32 v132, v132, v195
	v_add_f32_e32 v133, v133, v197
	v_lshlrev_b32_e32 v195, 16, v158
	v_and_b32_e32 v197, 0xffff0000, v158
	v_add_f32_e32 v134, v134, v195
	v_add_f32_e32 v135, v135, v197
	v_lshlrev_b32_e32 v195, 16, v159
	v_and_b32_e32 v197, 0xffff0000, v159
	v_add_f32_e32 v136, v136, v195
	v_add_f32_e32 v137, v137, v197
	v_lshlrev_b32_e32 v195, 16, v160
	v_and_b32_e32 v197, 0xffff0000, v160
	v_add_f32_e32 v138, v138, v195
	v_add_f32_e32 v139, v139, v197
	v_lshlrev_b32_e32 v195, 16, v161
	v_and_b32_e32 v197, 0xffff0000, v161
	v_add_f32_e32 v140, v140, v195
	v_add_f32_e32 v141, v141, v197
	v_lshlrev_b32_e32 v195, 16, v166
	v_and_b32_e32 v197, 0xffff0000, v166
	v_add_f32_e32 v142, v142, v195
	v_add_f32_e32 v143, v143, v197
	v_lshlrev_b32_e32 v195, 16, v167
	v_and_b32_e32 v197, 0xffff0000, v167
	v_add_f32_e32 v144, v144, v195
	v_add_f32_e32 v145, v145, v197
	v_lshlrev_b32_e32 v195, 16, v168
	v_and_b32_e32 v197, 0xffff0000, v168
	v_add_f32_e32 v146, v146, v195
	v_add_f32_e32 v147, v147, v197
	v_lshlrev_b32_e32 v195, 16, v169
	v_and_b32_e32 v197, 0xffff0000, v169
	v_add_f32_e32 v148, v148, v195
	v_add_f32_e32 v149, v149, v197
	global_load_dwordx4 v[150:153], v162, s[98:99] nt
	global_load_dwordx4 v[154:157], v162, s[98:99] offset:1024 nt
	global_load_dwordx4 v[158:161], v162, s[98:99] offset:2048 nt
	global_load_dwordx4 v[166:169], v162, s[98:99] offset:3072 nt
	s_add_u32 s98, s98, 0x400000
	s_addc_u32 s99, s99, 0
	s_waitcnt vmcnt(12)
	v_lshlrev_b32_e32 v195, 16, v170
	v_and_b32_e32 v197, 0xffff0000, v170
	v_add_f32_e32 v118, v118, v195
	v_add_f32_e32 v119, v119, v197
	v_lshlrev_b32_e32 v195, 16, v171
	v_and_b32_e32 v197, 0xffff0000, v171
	v_add_f32_e32 v120, v120, v195
	v_add_f32_e32 v121, v121, v197
	v_lshlrev_b32_e32 v195, 16, v172
	v_and_b32_e32 v197, 0xffff0000, v172
	v_add_f32_e32 v122, v122, v195
	v_add_f32_e32 v123, v123, v197
	v_lshlrev_b32_e32 v195, 16, v173
	v_and_b32_e32 v197, 0xffff0000, v173
	v_add_f32_e32 v124, v124, v195
	v_add_f32_e32 v125, v125, v197
	v_lshlrev_b32_e32 v195, 16, v174
	v_and_b32_e32 v197, 0xffff0000, v174
	v_add_f32_e32 v126, v126, v195
	v_add_f32_e32 v127, v127, v197
	v_lshlrev_b32_e32 v195, 16, v175
	v_and_b32_e32 v197, 0xffff0000, v175
	v_add_f32_e32 v128, v128, v195
	v_add_f32_e32 v129, v129, v197
	v_lshlrev_b32_e32 v195, 16, v176
	v_and_b32_e32 v197, 0xffff0000, v176
	v_add_f32_e32 v130, v130, v195
	v_add_f32_e32 v131, v131, v197
	v_lshlrev_b32_e32 v195, 16, v177
	v_and_b32_e32 v197, 0xffff0000, v177
	v_add_f32_e32 v132, v132, v195
	v_add_f32_e32 v133, v133, v197
	v_lshlrev_b32_e32 v195, 16, v178
	v_and_b32_e32 v197, 0xffff0000, v178
	v_add_f32_e32 v134, v134, v195
	v_add_f32_e32 v135, v135, v197
	v_lshlrev_b32_e32 v195, 16, v179
	v_and_b32_e32 v197, 0xffff0000, v179
	v_add_f32_e32 v136, v136, v195
	v_add_f32_e32 v137, v137, v197
	v_lshlrev_b32_e32 v195, 16, v180
	v_and_b32_e32 v197, 0xffff0000, v180
	v_add_f32_e32 v138, v138, v195
	v_add_f32_e32 v139, v139, v197
	v_lshlrev_b32_e32 v195, 16, v181
	v_and_b32_e32 v197, 0xffff0000, v181
	v_add_f32_e32 v140, v140, v195
	v_add_f32_e32 v141, v141, v197
	v_lshlrev_b32_e32 v195, 16, v182
	v_and_b32_e32 v197, 0xffff0000, v182
	v_add_f32_e32 v142, v142, v195
	v_add_f32_e32 v143, v143, v197
	v_lshlrev_b32_e32 v195, 16, v183
	v_and_b32_e32 v197, 0xffff0000, v183
	v_add_f32_e32 v144, v144, v195
	v_add_f32_e32 v145, v145, v197
	v_lshlrev_b32_e32 v195, 16, v184
	v_and_b32_e32 v197, 0xffff0000, v184
	v_add_f32_e32 v146, v146, v195
	v_add_f32_e32 v147, v147, v197
	v_lshlrev_b32_e32 v195, 16, v185
	v_and_b32_e32 v197, 0xffff0000, v185
	v_add_f32_e32 v148, v148, v195
	v_add_f32_e32 v149, v149, v197
	global_load_dwordx4 v[170:173], v162, s[98:99] nt
	global_load_dwordx4 v[174:177], v162, s[98:99] offset:1024 nt
	global_load_dwordx4 v[178:181], v162, s[98:99] offset:2048 nt
	global_load_dwordx4 v[182:185], v162, s[98:99] offset:3072 nt
	s_add_u32 s98, s98, 0x400000
	s_addc_u32 s99, s99, 0
	s_waitcnt vmcnt(12)
	v_lshlrev_b32_e32 v195, 16, v186
	v_and_b32_e32 v197, 0xffff0000, v186
	v_add_f32_e32 v118, v118, v195
	v_add_f32_e32 v119, v119, v197
	v_lshlrev_b32_e32 v195, 16, v187
	v_and_b32_e32 v197, 0xffff0000, v187
	v_add_f32_e32 v120, v120, v195
	v_add_f32_e32 v121, v121, v197
	v_lshlrev_b32_e32 v195, 16, v188
	v_and_b32_e32 v197, 0xffff0000, v188
	v_add_f32_e32 v122, v122, v195
	v_add_f32_e32 v123, v123, v197
	v_lshlrev_b32_e32 v195, 16, v189
	v_and_b32_e32 v197, 0xffff0000, v189
	v_add_f32_e32 v124, v124, v195
	v_add_f32_e32 v125, v125, v197
	v_lshlrev_b32_e32 v195, 16, v190
	v_and_b32_e32 v197, 0xffff0000, v190
	v_add_f32_e32 v126, v126, v195
	v_add_f32_e32 v127, v127, v197
	v_lshlrev_b32_e32 v195, 16, v191
	v_and_b32_e32 v197, 0xffff0000, v191
	v_add_f32_e32 v128, v128, v195
	v_add_f32_e32 v129, v129, v197
	v_lshlrev_b32_e32 v195, 16, v192
	v_and_b32_e32 v197, 0xffff0000, v192
	v_add_f32_e32 v130, v130, v195
	v_add_f32_e32 v131, v131, v197
	v_lshlrev_b32_e32 v195, 16, v193
	v_and_b32_e32 v197, 0xffff0000, v193
	v_add_f32_e32 v132, v132, v195
	v_add_f32_e32 v133, v133, v197
	v_lshlrev_b32_e32 v195, 16, v198
	v_and_b32_e32 v197, 0xffff0000, v198
	v_add_f32_e32 v134, v134, v195
	v_add_f32_e32 v135, v135, v197
	v_lshlrev_b32_e32 v195, 16, v199
	v_and_b32_e32 v197, 0xffff0000, v199
	v_add_f32_e32 v136, v136, v195
	v_add_f32_e32 v137, v137, v197
	v_lshlrev_b32_e32 v195, 16, v200
	v_and_b32_e32 v197, 0xffff0000, v200
	v_add_f32_e32 v138, v138, v195
	v_add_f32_e32 v139, v139, v197
	v_lshlrev_b32_e32 v195, 16, v201
	v_and_b32_e32 v197, 0xffff0000, v201
	v_add_f32_e32 v140, v140, v195
	v_add_f32_e32 v141, v141, v197
	v_lshlrev_b32_e32 v195, 16, v202
	v_and_b32_e32 v197, 0xffff0000, v202
	v_add_f32_e32 v142, v142, v195
	v_add_f32_e32 v143, v143, v197
	v_lshlrev_b32_e32 v195, 16, v203
	v_and_b32_e32 v197, 0xffff0000, v203
	v_add_f32_e32 v144, v144, v195
	v_add_f32_e32 v145, v145, v197
	v_lshlrev_b32_e32 v195, 16, v204
	v_and_b32_e32 v197, 0xffff0000, v204
	v_add_f32_e32 v146, v146, v195
	v_add_f32_e32 v147, v147, v197
	v_lshlrev_b32_e32 v195, 16, v205
	v_and_b32_e32 v197, 0xffff0000, v205
	v_add_f32_e32 v148, v148, v195
	v_add_f32_e32 v149, v149, v197
	global_load_dwordx4 v[186:189], v162, s[98:99] nt
	global_load_dwordx4 v[190:193], v162, s[98:99] offset:1024 nt
	global_load_dwordx4 v[198:201], v162, s[98:99] offset:2048 nt
	global_load_dwordx4 v[202:205], v162, s[98:99] offset:3072 nt
	s_add_u32 s98, s98, 0x400000
	s_addc_u32 s99, s99, 0
	s_waitcnt vmcnt(12)
	v_lshlrev_b32_e32 v195, 16, v206
	v_and_b32_e32 v197, 0xffff0000, v206
	v_add_f32_e32 v118, v118, v195
	v_add_f32_e32 v119, v119, v197
	v_lshlrev_b32_e32 v195, 16, v207
	v_and_b32_e32 v197, 0xffff0000, v207
	v_add_f32_e32 v120, v120, v195
	v_add_f32_e32 v121, v121, v197
	v_lshlrev_b32_e32 v195, 16, v208
	v_and_b32_e32 v197, 0xffff0000, v208
	v_add_f32_e32 v122, v122, v195
	v_add_f32_e32 v123, v123, v197
	v_lshlrev_b32_e32 v195, 16, v209
	v_and_b32_e32 v197, 0xffff0000, v209
	v_add_f32_e32 v124, v124, v195
	v_add_f32_e32 v125, v125, v197
	v_lshlrev_b32_e32 v195, 16, v210
	v_and_b32_e32 v197, 0xffff0000, v210
	v_add_f32_e32 v126, v126, v195
	v_add_f32_e32 v127, v127, v197
	v_lshlrev_b32_e32 v195, 16, v211
	v_and_b32_e32 v197, 0xffff0000, v211
	v_add_f32_e32 v128, v128, v195
	v_add_f32_e32 v129, v129, v197
	v_lshlrev_b32_e32 v195, 16, v212
	v_and_b32_e32 v197, 0xffff0000, v212
	v_add_f32_e32 v130, v130, v195
	v_add_f32_e32 v131, v131, v197
	v_lshlrev_b32_e32 v195, 16, v213
	v_and_b32_e32 v197, 0xffff0000, v213
	v_add_f32_e32 v132, v132, v195
	v_add_f32_e32 v133, v133, v197
	v_lshlrev_b32_e32 v195, 16, v214
	v_and_b32_e32 v197, 0xffff0000, v214
	v_add_f32_e32 v134, v134, v195
	v_add_f32_e32 v135, v135, v197
	v_lshlrev_b32_e32 v195, 16, v215
	v_and_b32_e32 v197, 0xffff0000, v215
	v_add_f32_e32 v136, v136, v195
	v_add_f32_e32 v137, v137, v197
	v_lshlrev_b32_e32 v195, 16, v216
	v_and_b32_e32 v197, 0xffff0000, v216
	v_add_f32_e32 v138, v138, v195
	v_add_f32_e32 v139, v139, v197
	v_lshlrev_b32_e32 v195, 16, v217
	v_and_b32_e32 v197, 0xffff0000, v217
	v_add_f32_e32 v140, v140, v195
	v_add_f32_e32 v141, v141, v197
	v_lshlrev_b32_e32 v195, 16, v218
	v_and_b32_e32 v197, 0xffff0000, v218
	v_add_f32_e32 v142, v142, v195
	v_add_f32_e32 v143, v143, v197
	v_lshlrev_b32_e32 v195, 16, v219
	v_and_b32_e32 v197, 0xffff0000, v219
	v_add_f32_e32 v144, v144, v195
	v_add_f32_e32 v145, v145, v197
	v_lshlrev_b32_e32 v195, 16, v220
	v_and_b32_e32 v197, 0xffff0000, v220
	v_add_f32_e32 v146, v146, v195
	v_add_f32_e32 v147, v147, v197
	v_lshlrev_b32_e32 v195, 16, v221
	v_and_b32_e32 v197, 0xffff0000, v221
	v_add_f32_e32 v148, v148, v195
	v_add_f32_e32 v149, v149, v197
	global_load_dwordx4 v[206:209], v162, s[98:99] nt
	global_load_dwordx4 v[210:213], v162, s[98:99] offset:1024 nt
	global_load_dwordx4 v[214:217], v162, s[98:99] offset:2048 nt
	global_load_dwordx4 v[218:221], v162, s[98:99] offset:3072 nt
	s_add_u32 s98, s98, 0x400000
	s_addc_u32 s99, s99, 0
	s_waitcnt vmcnt(12)
	v_lshlrev_b32_e32 v195, 16, v150
	v_and_b32_e32 v197, 0xffff0000, v150
	v_add_f32_e32 v118, v118, v195
	v_add_f32_e32 v119, v119, v197
	v_lshlrev_b32_e32 v195, 16, v151
	v_and_b32_e32 v197, 0xffff0000, v151
	v_add_f32_e32 v120, v120, v195
	v_add_f32_e32 v121, v121, v197
	v_lshlrev_b32_e32 v195, 16, v152
	v_and_b32_e32 v197, 0xffff0000, v152
	v_add_f32_e32 v122, v122, v195
	v_add_f32_e32 v123, v123, v197
	v_lshlrev_b32_e32 v195, 16, v153
	v_and_b32_e32 v197, 0xffff0000, v153
	v_add_f32_e32 v124, v124, v195
	v_add_f32_e32 v125, v125, v197
	v_lshlrev_b32_e32 v195, 16, v154
	v_and_b32_e32 v197, 0xffff0000, v154
	v_add_f32_e32 v126, v126, v195
	v_add_f32_e32 v127, v127, v197
	v_lshlrev_b32_e32 v195, 16, v155
	v_and_b32_e32 v197, 0xffff0000, v155
	v_add_f32_e32 v128, v128, v195
	v_add_f32_e32 v129, v129, v197
	v_lshlrev_b32_e32 v195, 16, v156
	v_and_b32_e32 v197, 0xffff0000, v156
	v_add_f32_e32 v130, v130, v195
	v_add_f32_e32 v131, v131, v197
	v_lshlrev_b32_e32 v195, 16, v157
	v_and_b32_e32 v197, 0xffff0000, v157
	v_add_f32_e32 v132, v132, v195
	v_add_f32_e32 v133, v133, v197
	v_lshlrev_b32_e32 v195, 16, v158
	v_and_b32_e32 v197, 0xffff0000, v158
	v_add_f32_e32 v134, v134, v195
	v_add_f32_e32 v135, v135, v197
	v_lshlrev_b32_e32 v195, 16, v159
	v_and_b32_e32 v197, 0xffff0000, v159
	v_add_f32_e32 v136, v136, v195
	v_add_f32_e32 v137, v137, v197
	v_lshlrev_b32_e32 v195, 16, v160
	v_and_b32_e32 v197, 0xffff0000, v160
	v_add_f32_e32 v138, v138, v195
	v_add_f32_e32 v139, v139, v197
	v_lshlrev_b32_e32 v195, 16, v161
	v_and_b32_e32 v197, 0xffff0000, v161
	v_add_f32_e32 v140, v140, v195
	v_add_f32_e32 v141, v141, v197
	v_lshlrev_b32_e32 v195, 16, v166
	v_and_b32_e32 v197, 0xffff0000, v166
	v_add_f32_e32 v142, v142, v195
	v_add_f32_e32 v143, v143, v197
	v_lshlrev_b32_e32 v195, 16, v167
	v_and_b32_e32 v197, 0xffff0000, v167
	v_add_f32_e32 v144, v144, v195
	v_add_f32_e32 v145, v145, v197
	v_lshlrev_b32_e32 v195, 16, v168
	v_and_b32_e32 v197, 0xffff0000, v168
	v_add_f32_e32 v146, v146, v195
	v_add_f32_e32 v147, v147, v197
	v_lshlrev_b32_e32 v195, 16, v169
	v_and_b32_e32 v197, 0xffff0000, v169
	v_add_f32_e32 v148, v148, v195
	v_add_f32_e32 v149, v149, v197
	global_load_dwordx4 v[150:153], v163, s[12:13]
	global_load_dwordx4 v[154:157], v163, s[12:13] offset:16
	global_load_dwordx4 v[158:161], v163, s[12:13] offset:2048
	global_load_dwordx4 v[166:169], v163, s[12:13] offset:2064
	s_waitcnt vmcnt(12)
	v_lshlrev_b32_e32 v195, 16, v170
	v_and_b32_e32 v197, 0xffff0000, v170
	v_add_f32_e32 v118, v118, v195
	v_add_f32_e32 v119, v119, v197
	v_lshlrev_b32_e32 v195, 16, v171
	v_and_b32_e32 v197, 0xffff0000, v171
	v_add_f32_e32 v120, v120, v195
	v_add_f32_e32 v121, v121, v197
	v_lshlrev_b32_e32 v195, 16, v172
	v_and_b32_e32 v197, 0xffff0000, v172
	v_add_f32_e32 v122, v122, v195
	v_add_f32_e32 v123, v123, v197
	v_lshlrev_b32_e32 v195, 16, v173
	v_and_b32_e32 v197, 0xffff0000, v173
	v_add_f32_e32 v124, v124, v195
	v_add_f32_e32 v125, v125, v197
	v_lshlrev_b32_e32 v195, 16, v174
	v_and_b32_e32 v197, 0xffff0000, v174
	v_add_f32_e32 v126, v126, v195
	v_add_f32_e32 v127, v127, v197
	v_lshlrev_b32_e32 v195, 16, v175
	v_and_b32_e32 v197, 0xffff0000, v175
	v_add_f32_e32 v128, v128, v195
	v_add_f32_e32 v129, v129, v197
	v_lshlrev_b32_e32 v195, 16, v176
	v_and_b32_e32 v197, 0xffff0000, v176
	v_add_f32_e32 v130, v130, v195
	v_add_f32_e32 v131, v131, v197
	v_lshlrev_b32_e32 v195, 16, v177
	v_and_b32_e32 v197, 0xffff0000, v177
	v_add_f32_e32 v132, v132, v195
	v_add_f32_e32 v133, v133, v197
	v_lshlrev_b32_e32 v195, 16, v178
	v_and_b32_e32 v197, 0xffff0000, v178
	v_add_f32_e32 v134, v134, v195
	v_add_f32_e32 v135, v135, v197
	v_lshlrev_b32_e32 v195, 16, v179
	v_and_b32_e32 v197, 0xffff0000, v179
	v_add_f32_e32 v136, v136, v195
	v_add_f32_e32 v137, v137, v197
	v_lshlrev_b32_e32 v195, 16, v180
	v_and_b32_e32 v197, 0xffff0000, v180
	v_add_f32_e32 v138, v138, v195
	v_add_f32_e32 v139, v139, v197
	v_lshlrev_b32_e32 v195, 16, v181
	v_and_b32_e32 v197, 0xffff0000, v181
	v_add_f32_e32 v140, v140, v195
	v_add_f32_e32 v141, v141, v197
	v_lshlrev_b32_e32 v195, 16, v182
	v_and_b32_e32 v197, 0xffff0000, v182
	v_add_f32_e32 v142, v142, v195
	v_add_f32_e32 v143, v143, v197
	v_lshlrev_b32_e32 v195, 16, v183
	v_and_b32_e32 v197, 0xffff0000, v183
	v_add_f32_e32 v144, v144, v195
	v_add_f32_e32 v145, v145, v197
	v_lshlrev_b32_e32 v195, 16, v184
	v_and_b32_e32 v197, 0xffff0000, v184
	v_add_f32_e32 v146, v146, v195
	v_add_f32_e32 v147, v147, v197
	v_lshlrev_b32_e32 v195, 16, v185
	v_and_b32_e32 v197, 0xffff0000, v185
	v_add_f32_e32 v148, v148, v195
	v_add_f32_e32 v149, v149, v197
	global_load_dwordx4 v[170:173], v194, s[12:13]
	global_load_dwordx4 v[174:177], v194, s[12:13] offset:16
	global_load_dwordx4 v[178:181], v194, s[12:13] offset:2048
	global_load_dwordx4 v[182:185], v194, s[12:13] offset:2064
	s_waitcnt vmcnt(12)
	v_lshlrev_b32_e32 v195, 16, v186
	v_and_b32_e32 v197, 0xffff0000, v186
	v_add_f32_e32 v118, v118, v195
	v_add_f32_e32 v119, v119, v197
	v_lshlrev_b32_e32 v195, 16, v187
	v_and_b32_e32 v197, 0xffff0000, v187
	v_add_f32_e32 v120, v120, v195
	v_add_f32_e32 v121, v121, v197
	v_lshlrev_b32_e32 v195, 16, v188
	v_and_b32_e32 v197, 0xffff0000, v188
	v_add_f32_e32 v122, v122, v195
	v_add_f32_e32 v123, v123, v197
	v_lshlrev_b32_e32 v195, 16, v189
	v_and_b32_e32 v197, 0xffff0000, v189
	v_add_f32_e32 v124, v124, v195
	v_add_f32_e32 v125, v125, v197
	v_lshlrev_b32_e32 v195, 16, v190
	v_and_b32_e32 v197, 0xffff0000, v190
	v_add_f32_e32 v126, v126, v195
	v_add_f32_e32 v127, v127, v197
	v_lshlrev_b32_e32 v195, 16, v191
	v_and_b32_e32 v197, 0xffff0000, v191
	v_add_f32_e32 v128, v128, v195
	v_add_f32_e32 v129, v129, v197
	v_lshlrev_b32_e32 v195, 16, v192
	v_and_b32_e32 v197, 0xffff0000, v192
	v_add_f32_e32 v130, v130, v195
	v_add_f32_e32 v131, v131, v197
	v_lshlrev_b32_e32 v195, 16, v193
	v_and_b32_e32 v197, 0xffff0000, v193
	v_add_f32_e32 v132, v132, v195
	v_add_f32_e32 v133, v133, v197
	v_lshlrev_b32_e32 v195, 16, v198
	v_and_b32_e32 v197, 0xffff0000, v198
	v_add_f32_e32 v134, v134, v195
	v_add_f32_e32 v135, v135, v197
	v_lshlrev_b32_e32 v195, 16, v199
	v_and_b32_e32 v197, 0xffff0000, v199
	v_add_f32_e32 v136, v136, v195
	v_add_f32_e32 v137, v137, v197
	v_lshlrev_b32_e32 v195, 16, v200
	v_and_b32_e32 v197, 0xffff0000, v200
	v_add_f32_e32 v138, v138, v195
	v_add_f32_e32 v139, v139, v197
	v_lshlrev_b32_e32 v195, 16, v201
	v_and_b32_e32 v197, 0xffff0000, v201
	v_add_f32_e32 v140, v140, v195
	v_add_f32_e32 v141, v141, v197
	v_lshlrev_b32_e32 v195, 16, v202
	v_and_b32_e32 v197, 0xffff0000, v202
	v_add_f32_e32 v142, v142, v195
	v_add_f32_e32 v143, v143, v197
	v_lshlrev_b32_e32 v195, 16, v203
	v_and_b32_e32 v197, 0xffff0000, v203
	v_add_f32_e32 v144, v144, v195
	v_add_f32_e32 v145, v145, v197
	v_lshlrev_b32_e32 v195, 16, v204
	v_and_b32_e32 v197, 0xffff0000, v204
	v_add_f32_e32 v146, v146, v195
	v_add_f32_e32 v147, v147, v197
	v_lshlrev_b32_e32 v195, 16, v205
	v_and_b32_e32 v197, 0xffff0000, v205
	v_add_f32_e32 v148, v148, v195
	v_add_f32_e32 v149, v149, v197
	s_waitcnt vmcnt(8)
	v_lshlrev_b32_e32 v195, 16, v206
	v_and_b32_e32 v197, 0xffff0000, v206
	v_add_f32_e32 v118, v118, v195
	v_add_f32_e32 v119, v119, v197
	v_lshlrev_b32_e32 v195, 16, v207
	v_and_b32_e32 v197, 0xffff0000, v207
	v_add_f32_e32 v120, v120, v195
	v_add_f32_e32 v121, v121, v197
	v_lshlrev_b32_e32 v195, 16, v208
	v_and_b32_e32 v197, 0xffff0000, v208
	v_add_f32_e32 v122, v122, v195
	v_add_f32_e32 v123, v123, v197
	v_lshlrev_b32_e32 v195, 16, v209
	v_and_b32_e32 v197, 0xffff0000, v209
	v_add_f32_e32 v124, v124, v195
	v_add_f32_e32 v125, v125, v197
	v_lshlrev_b32_e32 v195, 16, v210
	v_and_b32_e32 v197, 0xffff0000, v210
	v_add_f32_e32 v126, v126, v195
	v_add_f32_e32 v127, v127, v197
	v_lshlrev_b32_e32 v195, 16, v211
	v_and_b32_e32 v197, 0xffff0000, v211
	v_add_f32_e32 v128, v128, v195
	v_add_f32_e32 v129, v129, v197
	v_lshlrev_b32_e32 v195, 16, v212
	v_and_b32_e32 v197, 0xffff0000, v212
	v_add_f32_e32 v130, v130, v195
	v_add_f32_e32 v131, v131, v197
	v_lshlrev_b32_e32 v195, 16, v213
	v_and_b32_e32 v197, 0xffff0000, v213
	v_add_f32_e32 v132, v132, v195
	v_add_f32_e32 v133, v133, v197
	v_lshlrev_b32_e32 v195, 16, v214
	v_and_b32_e32 v197, 0xffff0000, v214
	v_add_f32_e32 v134, v134, v195
	v_add_f32_e32 v135, v135, v197
	v_lshlrev_b32_e32 v195, 16, v215
	v_and_b32_e32 v197, 0xffff0000, v215
	v_add_f32_e32 v136, v136, v195
	v_add_f32_e32 v137, v137, v197
	v_lshlrev_b32_e32 v195, 16, v216
	v_and_b32_e32 v197, 0xffff0000, v216
	v_add_f32_e32 v138, v138, v195
	v_add_f32_e32 v139, v139, v197
	v_lshlrev_b32_e32 v195, 16, v217
	v_and_b32_e32 v197, 0xffff0000, v217
	v_add_f32_e32 v140, v140, v195
	v_add_f32_e32 v141, v141, v197
	v_lshlrev_b32_e32 v195, 16, v218
	v_and_b32_e32 v197, 0xffff0000, v218
	v_add_f32_e32 v142, v142, v195
	v_add_f32_e32 v143, v143, v197
	v_lshlrev_b32_e32 v195, 16, v219
	v_and_b32_e32 v197, 0xffff0000, v219
	v_add_f32_e32 v144, v144, v195
	v_add_f32_e32 v145, v145, v197
	v_lshlrev_b32_e32 v195, 16, v220
	v_and_b32_e32 v197, 0xffff0000, v220
	v_add_f32_e32 v146, v146, v195
	v_add_f32_e32 v147, v147, v197
	v_lshlrev_b32_e32 v195, 16, v221
	v_and_b32_e32 v197, 0xffff0000, v221
	v_add_f32_e32 v148, v148, v195
	v_add_f32_e32 v149, v149, v197
	s_lshl_b32 s97, s32, 12
	s_add_u32 s94, s34, s97
	s_addc_u32 s95, s35, 0
	s_add_u32 s94, s94, 0x2aa00000
	s_addc_u32 s95, s95, 0
	v_cvt_pk_bf16_f32 v186, v118, v119
	v_cvt_pk_bf16_f32 v187, v120, v121
	v_cvt_pk_bf16_f32 v188, v122, v123
	v_cvt_pk_bf16_f32 v189, v124, v125
	global_store_dwordx4 v162, v[186:189], s[94:95]
	v_cvt_pk_bf16_f32 v190, v126, v127
	v_cvt_pk_bf16_f32 v191, v128, v129
	v_cvt_pk_bf16_f32 v192, v130, v131
	v_cvt_pk_bf16_f32 v193, v132, v133
	global_store_dwordx4 v162, v[190:193], s[94:95] offset:1024
	v_cvt_pk_bf16_f32 v198, v134, v135
	v_cvt_pk_bf16_f32 v199, v136, v137
	v_cvt_pk_bf16_f32 v200, v138, v139
	v_cvt_pk_bf16_f32 v201, v140, v141
	global_store_dwordx4 v162, v[198:201], s[94:95] offset:2048
	v_cvt_pk_bf16_f32 v202, v142, v143
	v_cvt_pk_bf16_f32 v203, v144, v145
	v_cvt_pk_bf16_f32 v204, v146, v147
	v_cvt_pk_bf16_f32 v205, v148, v149
	global_store_dwordx4 v162, v[202:205], s[94:95] offset:3072
	v_lshlrev_b32_e32 v118, 16, v186
	v_and_b32_e32 v119, 0xffff0000, v186
	v_lshlrev_b32_e32 v120, 16, v187
	v_and_b32_e32 v121, 0xffff0000, v187
	v_lshlrev_b32_e32 v122, 16, v188
	v_and_b32_e32 v123, 0xffff0000, v188
	v_lshlrev_b32_e32 v124, 16, v189
	v_and_b32_e32 v125, 0xffff0000, v189
	v_lshlrev_b32_e32 v126, 16, v190
	v_and_b32_e32 v127, 0xffff0000, v190
	v_lshlrev_b32_e32 v128, 16, v191
	v_and_b32_e32 v129, 0xffff0000, v191
	v_lshlrev_b32_e32 v130, 16, v192
	v_and_b32_e32 v131, 0xffff0000, v192
	v_lshlrev_b32_e32 v132, 16, v193
	v_and_b32_e32 v133, 0xffff0000, v193
	v_lshlrev_b32_e32 v134, 16, v198
	v_and_b32_e32 v135, 0xffff0000, v198
	v_lshlrev_b32_e32 v136, 16, v199
	v_and_b32_e32 v137, 0xffff0000, v199
	v_lshlrev_b32_e32 v138, 16, v200
	v_and_b32_e32 v139, 0xffff0000, v200
	v_lshlrev_b32_e32 v140, 16, v201
	v_and_b32_e32 v141, 0xffff0000, v201
	v_lshlrev_b32_e32 v142, 16, v202
	v_and_b32_e32 v143, 0xffff0000, v202
	v_lshlrev_b32_e32 v144, 16, v203
	v_and_b32_e32 v145, 0xffff0000, v203
	v_lshlrev_b32_e32 v146, 16, v204
	v_and_b32_e32 v147, 0xffff0000, v204
	v_lshlrev_b32_e32 v148, 16, v205
	v_and_b32_e32 v149, 0xffff0000, v205
	v_mul_f32_e32 v227, v118, v118
	v_fmac_f32_e32 v227, v119, v119
	v_fmac_f32_e32 v227, v120, v120
	v_fmac_f32_e32 v227, v121, v121
	v_fmac_f32_e32 v227, v122, v122
	v_fmac_f32_e32 v227, v123, v123
	v_fmac_f32_e32 v227, v124, v124
	v_fmac_f32_e32 v227, v125, v125
	v_fmac_f32_e32 v227, v126, v126
	v_fmac_f32_e32 v227, v127, v127
	v_fmac_f32_e32 v227, v128, v128
	v_fmac_f32_e32 v227, v129, v129
	v_fmac_f32_e32 v227, v130, v130
	v_fmac_f32_e32 v227, v131, v131
	v_fmac_f32_e32 v227, v132, v132
	v_fmac_f32_e32 v227, v133, v133
	v_fmac_f32_e32 v227, v134, v134
	v_fmac_f32_e32 v227, v135, v135
	v_fmac_f32_e32 v227, v136, v136
	v_fmac_f32_e32 v227, v137, v137
	v_fmac_f32_e32 v227, v138, v138
	v_fmac_f32_e32 v227, v139, v139
	v_fmac_f32_e32 v227, v140, v140
	v_fmac_f32_e32 v227, v141, v141
	v_fmac_f32_e32 v227, v142, v142
	v_fmac_f32_e32 v227, v143, v143
	v_fmac_f32_e32 v227, v144, v144
	v_fmac_f32_e32 v227, v145, v145
	v_fmac_f32_e32 v227, v146, v146
	v_fmac_f32_e32 v227, v147, v147
	v_fmac_f32_e32 v227, v148, v148
	v_fmac_f32_e32 v227, v149, v149
	v_xor_b32_e32 v195, 4, v243
	ds_bpermute_b32 v242, v195, v227
	s_waitcnt lgkmcnt(0)
	v_add_f32_e32 v227, v227, v242
	v_xor_b32_e32 v195, 8, v243
	ds_bpermute_b32 v242, v195, v227
	s_waitcnt lgkmcnt(0)
	v_add_f32_e32 v227, v227, v242
	v_xor_b32_e32 v195, 16, v243
	ds_bpermute_b32 v242, v195, v227
	s_waitcnt lgkmcnt(0)
	v_add_f32_e32 v227, v227, v242
	v_xor_b32_e32 v195, 32, v243
	ds_bpermute_b32 v242, v195, v227
	s_waitcnt lgkmcnt(0)
	v_add_f32_e32 v227, v227, v242
	v_xor_b32_e32 v195, 64, v243
	ds_bpermute_b32 v242, v195, v227
	s_waitcnt lgkmcnt(0)
	v_add_f32_e32 v227, v227, v242
	v_xor_b32_e32 v195, 128, v243
	ds_bpermute_b32 v242, v195, v227
	s_waitcnt lgkmcnt(0)
	v_add_f32_e32 v227, v227, v242
	v_mov_b32_e32 v240, 0x3a000000
	v_mov_b32_e32 v241, 0x358637bd
	v_fma_f32 v227, v227, v240, v241
	v_rsq_f32_e32 v227, v227
	s_lshl_b32 s97, s32, 12
	s_add_u32 s100, s34, s97
	s_addc_u32 s101, s35, 0
	s_add_u32 s100, s100, 0x9800000
	s_addc_u32 s101, s101, 0
	s_waitcnt vmcnt(4)
	v_mul_f32_e32 v118, v118, v227
	v_mul_f32_e32 v118, v118, v150
	v_mul_f32_e32 v119, v119, v227
	v_mul_f32_e32 v119, v119, v151
	v_mul_f32_e32 v120, v120, v227
	v_mul_f32_e32 v120, v120, v152
	v_mul_f32_e32 v121, v121, v227
	v_mul_f32_e32 v121, v121, v153
	v_mul_f32_e32 v122, v122, v227
	v_mul_f32_e32 v122, v122, v154
	v_mul_f32_e32 v123, v123, v227
	v_mul_f32_e32 v123, v123, v155
	v_mul_f32_e32 v124, v124, v227
	v_mul_f32_e32 v124, v124, v156
	v_mul_f32_e32 v125, v125, v227
	v_mul_f32_e32 v125, v125, v157
	v_mul_f32_e32 v126, v126, v227
	v_mul_f32_e32 v126, v126, v158
	v_mul_f32_e32 v127, v127, v227
	v_mul_f32_e32 v127, v127, v159
	v_mul_f32_e32 v128, v128, v227
	v_mul_f32_e32 v128, v128, v160
	v_mul_f32_e32 v129, v129, v227
	v_mul_f32_e32 v129, v129, v161
	v_mul_f32_e32 v130, v130, v227
	v_mul_f32_e32 v130, v130, v166
	v_mul_f32_e32 v131, v131, v227
	v_mul_f32_e32 v131, v131, v167
	v_mul_f32_e32 v132, v132, v227
	v_mul_f32_e32 v132, v132, v168
	v_mul_f32_e32 v133, v133, v227
	v_mul_f32_e32 v133, v133, v169
	v_mul_f32_e32 v134, v134, v227
	v_mul_f32_e32 v134, v134, v170
	v_mul_f32_e32 v135, v135, v227
	v_mul_f32_e32 v135, v135, v171
	v_mul_f32_e32 v136, v136, v227
	v_mul_f32_e32 v136, v136, v172
	v_mul_f32_e32 v137, v137, v227
	v_mul_f32_e32 v137, v137, v173
	v_mul_f32_e32 v138, v138, v227
	v_mul_f32_e32 v138, v138, v174
	v_mul_f32_e32 v139, v139, v227
	v_mul_f32_e32 v139, v139, v175
	v_mul_f32_e32 v140, v140, v227
	v_mul_f32_e32 v140, v140, v176
	v_mul_f32_e32 v141, v141, v227
	v_mul_f32_e32 v141, v141, v177
	v_mul_f32_e32 v142, v142, v227
	v_mul_f32_e32 v142, v142, v178
	v_mul_f32_e32 v143, v143, v227
	v_mul_f32_e32 v143, v143, v179
	v_mul_f32_e32 v144, v144, v227
	v_mul_f32_e32 v144, v144, v180
	v_mul_f32_e32 v145, v145, v227
	v_mul_f32_e32 v145, v145, v181
	v_mul_f32_e32 v146, v146, v227
	v_mul_f32_e32 v146, v146, v182
	v_mul_f32_e32 v147, v147, v227
	v_mul_f32_e32 v147, v147, v183
	v_mul_f32_e32 v148, v148, v227
	v_mul_f32_e32 v148, v148, v184
	v_mul_f32_e32 v149, v149, v227
	v_mul_f32_e32 v149, v149, v185
	v_cvt_pk_bf16_f32 v206, v118, v119
	v_cvt_pk_bf16_f32 v207, v120, v121
	v_cvt_pk_bf16_f32 v208, v122, v123
	v_cvt_pk_bf16_f32 v209, v124, v125
	global_store_dwordx4 v162, v[206:209], s[100:101]
	v_cvt_pk_bf16_f32 v210, v126, v127
	v_cvt_pk_bf16_f32 v211, v128, v129
	v_cvt_pk_bf16_f32 v212, v130, v131
	v_cvt_pk_bf16_f32 v213, v132, v133
	global_store_dwordx4 v162, v[210:213], s[100:101] offset:1024
	v_cvt_pk_bf16_f32 v214, v134, v135
	v_cvt_pk_bf16_f32 v215, v136, v137
	v_cvt_pk_bf16_f32 v216, v138, v139
	v_cvt_pk_bf16_f32 v217, v140, v141
	global_store_dwordx4 v162, v[214:217], s[100:101] offset:2048
	v_cvt_pk_bf16_f32 v218, v142, v143
	v_cvt_pk_bf16_f32 v219, v144, v145
	v_cvt_pk_bf16_f32 v220, v146, v147
	v_cvt_pk_bf16_f32 v221, v148, v149
	global_store_dwordx4 v162, v[218:221], s[100:101] offset:3072
	s_branch .LBB0_1042

.LBB0_1227:
	v_lshl_add_u32 v146, v165, 3, s72
	s_ashr_i32 s51, s50, 31
	v_ashrrev_i32_e32 v147, 31, v146
	v_lshlrev_b64 v[156:157], 11, v[156:157]
	s_lshl_b64 s[50:51], s[50:51], 12
	v_lshl_add_u64 v[156:157], v[156:157], 0, v[146:147]
	s_add_u32 s50, s67, s50
	s_addc_u32 s51, s68, s51
	v_lshlrev_b64 v[156:157], 1, v[156:157]
	v_lshl_add_u64 v[166:167], s[50:51], 0, v[156:157]
	s_lshl_b64 s[52:53], s[48:49], 1
	v_lshl_add_u64 v[170:171], v[166:167], 0, s[52:53]
	flat_load_dwordx4 v[166:169], v[170:171] nt
	s_add_u32 s48, s50, s52
	s_addc_u32 s49, s51, s53
	v_lshl_add_u64 v[156:157], s[48:49], 0, v[156:157]
	v_ashrrev_i32_e32 v155, 31, v154
	v_lshlrev_b64 v[154:155], 11, v[154:155]
	v_lshl_add_u64 v[154:155], v[154:155], 0, v[146:147]
	v_lshlrev_b64 v[154:155], 1, v[154:155]
	v_ashrrev_i32_e32 v153, 31, v152
	v_ashrrev_i32_e32 v151, 31, v150
	v_ashrrev_i32_e32 v149, 31, v148
	v_ashrrev_i32_e32 v145, 31, v144
	v_ashrrev_i32_e32 v143, 31, v142
	v_ashrrev_i32_e32 v141, 31, v140
	global_load_dwordx4 v[232:235], v[156:157], off offset:256 nt
	v_lshl_add_u64 v[198:199], s[50:51], 0, v[154:155]
	v_lshl_add_u64 v[200:201], v[198:199], 0, s[52:53]
	global_load_dwordx4 v[236:239], v[200:201], off nt
	v_lshl_add_u64 v[198:199], s[48:49], 0, v[154:155]
	global_load_dwordx4 v[240:243], v[198:199], off offset:256 nt
	v_lshlrev_b64 v[198:199], 11, v[152:153]
	v_lshl_add_u64 v[200:201], v[198:199], 0, v[146:147]
	v_lshlrev_b64 v[202:203], 1, v[200:201]
	v_lshl_add_u64 v[204:205], s[50:51], 0, v[202:203]
	v_lshl_add_u64 v[206:207], v[204:205], 0, s[52:53]
	global_load_dwordx4 v[244:247], v[206:207], off nt
	v_lshlrev_b64 v[198:199], 11, v[152:153]
	v_lshl_add_u64 v[200:201], v[198:199], 0, v[146:147]
	v_lshlrev_b64 v[202:203], 1, v[200:201]
	v_lshl_add_u64 v[204:205], s[48:49], 0, v[202:203]
	global_load_dwordx4 v[248:251], v[204:205], off offset:256 nt
	v_lshlrev_b64 v[198:199], 11, v[150:151]
	v_lshl_add_u64 v[200:201], v[198:199], 0, v[146:147]
	v_lshlrev_b64 v[202:203], 1, v[200:201]
	v_lshl_add_u64 v[204:205], s[50:51], 0, v[202:203]
	v_lshl_add_u64 v[206:207], v[204:205], 0, s[52:53]
	global_load_dwordx4 v[252:255], v[206:207], off nt
	s_waitcnt vmcnt(6) lgkmcnt(0)
	v_lshlrev_b64 v[198:199], 11, v[150:151]
	v_lshl_add_u64 v[200:201], v[198:199], 0, v[146:147]
	v_lshlrev_b64 v[202:203], 1, v[200:201]
	v_lshl_add_u64 v[204:205], s[48:49], 0, v[202:203]
	global_load_dwordx4 v[228:231], v[204:205], off offset:256 nt
	v_lshlrev_b32_e32 v172, 16, v166
	v_and_b32_e32 v173, 0xffff0000, v166
	v_lshlrev_b32_e32 v166, 16, v167
	v_and_b32_e32 v167, 0xffff0000, v167
	v_lshlrev_b32_e32 v174, 16, v168
	v_and_b32_e32 v175, 0xffff0000, v168
	v_lshlrev_b32_e32 v168, 16, v169
	v_and_b32_e32 v169, 0xffff0000, v169
	v_pk_add_f32 v[126:127], v[126:127], v[166:167]
	v_pk_add_f32 v[124:125], v[124:125], v[172:173]
	v_pk_add_f32 v[166:167], v[122:123], v[168:169]
	v_pk_add_f32 v[122:123], v[120:121], v[174:175]
	v_cvt_pk_bf16_f32 v120, v124, v125
	v_cvt_pk_bf16_f32 v121, v126, v127
	s_nop 0
	v_cvt_pk_bf16_f32 v122, v122, v123
	v_cvt_pk_bf16_f32 v123, v166, v167
	v_lshl_add_u64 v[166:167], s[50:51], 0, v[154:155]
	flat_store_dwordx4 v[170:171], v[120:123]
	v_lshl_add_u64 v[166:167], v[166:167], 0, s[52:53]
	s_waitcnt vmcnt(7) lgkmcnt(0)
	s_nop 1
	v_mov_b32_e32 v124, v232
	v_mov_b32_e32 v125, v233
	v_mov_b32_e32 v126, v234
	v_mov_b32_e32 v127, v235
	v_lshlrev_b64 v[198:199], 11, v[148:149]
	v_lshl_add_u64 v[200:201], v[198:199], 0, v[146:147]
	v_lshlrev_b64 v[202:203], 1, v[200:201]
	v_lshl_add_u64 v[204:205], s[50:51], 0, v[202:203]
	v_lshl_add_u64 v[206:207], v[204:205], 0, s[52:53]
	global_load_dwordx4 v[232:235], v[206:207], off nt
	v_lshlrev_b32_e32 v120, 16, v124
	v_and_b32_e32 v121, 0xffff0000, v124
	v_lshlrev_b32_e32 v122, 16, v125
	v_and_b32_e32 v123, 0xffff0000, v125
	v_lshlrev_b32_e32 v124, 16, v126
	v_and_b32_e32 v125, 0xffff0000, v126
	v_lshlrev_b32_e32 v126, 16, v127
	v_and_b32_e32 v127, 0xffff0000, v127
	v_pk_add_f32 v[116:117], v[116:117], v[120:121]
	v_pk_add_f32 v[120:121], v[114:115], v[126:127]
	v_pk_add_f32 v[114:115], v[112:113], v[124:125]
	v_pk_add_f32 v[118:119], v[118:119], v[122:123]
	v_cvt_pk_bf16_f32 v112, v116, v117
	v_lshl_add_u64 v[116:117], s[48:49], 0, v[154:155]
	v_cvt_pk_bf16_f32 v113, v118, v119
	v_cvt_pk_bf16_f32 v114, v114, v115
	v_cvt_pk_bf16_f32 v115, v120, v121
	flat_store_dwordx4 v[156:157], v[112:115] offset:256
	s_waitcnt vmcnt(8) lgkmcnt(0)
	s_nop 1
	v_mov_b32_e32 v112, v236
	v_mov_b32_e32 v113, v237
	v_mov_b32_e32 v114, v238
	v_mov_b32_e32 v115, v239
	v_lshlrev_b64 v[198:199], 11, v[148:149]
	v_lshl_add_u64 v[200:201], v[198:199], 0, v[146:147]
	v_lshlrev_b64 v[202:203], 1, v[200:201]
	v_lshl_add_u64 v[204:205], s[48:49], 0, v[202:203]
	global_load_dwordx4 v[236:239], v[204:205], off offset:256 nt
	v_lshlrev_b32_e32 v118, 16, v112
	v_and_b32_e32 v119, 0xffff0000, v112
	v_lshlrev_b32_e32 v112, 16, v113
	v_and_b32_e32 v113, 0xffff0000, v113
	v_lshlrev_b32_e32 v120, 16, v114
	v_and_b32_e32 v121, 0xffff0000, v114
	v_lshlrev_b32_e32 v114, 16, v115
	v_and_b32_e32 v115, 0xffff0000, v115
	v_pk_add_f32 v[110:111], v[110:111], v[112:113]
	v_pk_add_f32 v[108:109], v[108:109], v[118:119]
	v_pk_add_f32 v[112:113], v[106:107], v[114:115]
	v_pk_add_f32 v[106:107], v[104:105], v[120:121]
	v_cvt_pk_bf16_f32 v104, v108, v109
	v_cvt_pk_bf16_f32 v105, v110, v111
	s_nop 0
	v_cvt_pk_bf16_f32 v106, v106, v107
	v_cvt_pk_bf16_f32 v107, v112, v113
	v_lshlrev_b64 v[112:113], 11, v[152:153]
	v_lshl_add_u64 v[112:113], v[112:113], 0, v[146:147]
	v_lshlrev_b64 v[112:113], 1, v[112:113]
	flat_store_dwordx4 v[166:167], v[104:107]
	v_lshl_add_u64 v[114:115], s[50:51], 0, v[112:113]
	v_lshl_add_u64 v[114:115], v[114:115], 0, s[52:53]
	s_waitcnt vmcnt(9) lgkmcnt(0)
	s_nop 1
	v_mov_b32_e32 v108, v240
	v_mov_b32_e32 v109, v241
	v_mov_b32_e32 v110, v242
	v_mov_b32_e32 v111, v243
	v_lshlrev_b64 v[198:199], 11, v[144:145]
	v_lshl_add_u64 v[200:201], v[198:199], 0, v[146:147]
	v_lshlrev_b64 v[202:203], 1, v[200:201]
	v_lshl_add_u64 v[204:205], s[50:51], 0, v[202:203]
	v_lshl_add_u64 v[206:207], v[204:205], 0, s[52:53]
	global_load_dwordx4 v[240:243], v[206:207], off nt
	v_lshlrev_b32_e32 v104, 16, v108
	v_and_b32_e32 v105, 0xffff0000, v108
	v_lshlrev_b32_e32 v106, 16, v109
	v_and_b32_e32 v107, 0xffff0000, v109
	v_lshlrev_b32_e32 v108, 16, v110
	v_and_b32_e32 v109, 0xffff0000, v110
	v_lshlrev_b32_e32 v110, 16, v111
	v_and_b32_e32 v111, 0xffff0000, v111
	v_pk_add_f32 v[100:101], v[100:101], v[104:105]
	v_pk_add_f32 v[104:105], v[98:99], v[110:111]
	v_pk_add_f32 v[98:99], v[96:97], v[108:109]
	v_pk_add_f32 v[102:103], v[102:103], v[106:107]
	v_cvt_pk_bf16_f32 v96, v100, v101
	v_lshl_add_u64 v[100:101], s[48:49], 0, v[112:113]
	v_cvt_pk_bf16_f32 v97, v102, v103
	v_cvt_pk_bf16_f32 v98, v98, v99
	v_cvt_pk_bf16_f32 v99, v104, v105
	flat_store_dwordx4 v[116:117], v[96:99] offset:256
	s_waitcnt vmcnt(10) lgkmcnt(0)
	s_nop 1
	v_mov_b32_e32 v96, v244
	v_mov_b32_e32 v97, v245
	v_mov_b32_e32 v98, v246
	v_mov_b32_e32 v99, v247
	v_lshlrev_b64 v[198:199], 11, v[144:145]
	v_lshl_add_u64 v[200:201], v[198:199], 0, v[146:147]
	v_lshlrev_b64 v[202:203], 1, v[200:201]
	v_lshl_add_u64 v[204:205], s[48:49], 0, v[202:203]
	global_load_dwordx4 v[244:247], v[204:205], off offset:256 nt
	v_lshlrev_b32_e32 v102, 16, v96
	v_and_b32_e32 v103, 0xffff0000, v96
	v_lshlrev_b32_e32 v96, 16, v97
	v_and_b32_e32 v97, 0xffff0000, v97
	v_lshlrev_b32_e32 v104, 16, v98
	v_and_b32_e32 v105, 0xffff0000, v98
	v_lshlrev_b32_e32 v98, 16, v99
	v_and_b32_e32 v99, 0xffff0000, v99
	v_pk_add_f32 v[94:95], v[94:95], v[96:97]
	v_pk_add_f32 v[92:93], v[92:93], v[102:103]
	v_pk_add_f32 v[96:97], v[90:91], v[98:99]
	v_pk_add_f32 v[90:91], v[88:89], v[104:105]
	v_cvt_pk_bf16_f32 v88, v92, v93
	v_cvt_pk_bf16_f32 v89, v94, v95
	s_nop 0
	v_cvt_pk_bf16_f32 v90, v90, v91
	v_cvt_pk_bf16_f32 v91, v96, v97
	v_lshlrev_b64 v[96:97], 11, v[150:151]
	v_lshl_add_u64 v[96:97], v[96:97], 0, v[146:147]
	v_lshlrev_b64 v[96:97], 1, v[96:97]
	flat_store_dwordx4 v[114:115], v[88:91]
	v_lshl_add_u64 v[98:99], s[50:51], 0, v[96:97]
	v_lshl_add_u64 v[98:99], v[98:99], 0, s[52:53]
	s_waitcnt vmcnt(11) lgkmcnt(0)
	s_nop 1
	v_mov_b32_e32 v92, v248
	v_mov_b32_e32 v93, v249
	v_mov_b32_e32 v94, v250
	v_mov_b32_e32 v95, v251
	v_lshlrev_b64 v[198:199], 11, v[142:143]
	v_lshl_add_u64 v[200:201], v[198:199], 0, v[146:147]
	v_lshlrev_b64 v[202:203], 1, v[200:201]
	v_lshl_add_u64 v[204:205], s[50:51], 0, v[202:203]
	v_lshl_add_u64 v[206:207], v[204:205], 0, s[52:53]
	global_load_dwordx4 v[248:251], v[206:207], off nt
	v_lshlrev_b32_e32 v88, 16, v92
	v_and_b32_e32 v89, 0xffff0000, v92
	v_lshlrev_b32_e32 v90, 16, v93
	v_and_b32_e32 v91, 0xffff0000, v93
	v_lshlrev_b32_e32 v92, 16, v94
	v_and_b32_e32 v93, 0xffff0000, v94
	v_lshlrev_b32_e32 v94, 16, v95
	v_and_b32_e32 v95, 0xffff0000, v95
	v_pk_add_f32 v[84:85], v[84:85], v[88:89]
	v_pk_add_f32 v[88:89], v[82:83], v[94:95]
	v_pk_add_f32 v[82:83], v[80:81], v[92:93]
	v_pk_add_f32 v[86:87], v[86:87], v[90:91]
	v_cvt_pk_bf16_f32 v80, v84, v85
	v_lshl_add_u64 v[84:85], s[48:49], 0, v[96:97]
	v_cvt_pk_bf16_f32 v81, v86, v87
	v_cvt_pk_bf16_f32 v82, v82, v83
	v_cvt_pk_bf16_f32 v83, v88, v89
	flat_store_dwordx4 v[100:101], v[80:83] offset:256
	s_waitcnt vmcnt(12) lgkmcnt(0)
	s_nop 1
	v_mov_b32_e32 v80, v252
	v_mov_b32_e32 v81, v253
	v_mov_b32_e32 v82, v254
	v_mov_b32_e32 v83, v255
	v_lshlrev_b64 v[198:199], 11, v[142:143]
	v_lshl_add_u64 v[200:201], v[198:199], 0, v[146:147]
	v_lshlrev_b64 v[202:203], 1, v[200:201]
	v_lshl_add_u64 v[204:205], s[48:49], 0, v[202:203]
	global_load_dwordx4 v[252:255], v[204:205], off offset:256 nt
	v_lshlrev_b32_e32 v86, 16, v80
	v_and_b32_e32 v87, 0xffff0000, v80
	v_lshlrev_b32_e32 v80, 16, v81
	v_and_b32_e32 v81, 0xffff0000, v81
	v_lshlrev_b32_e32 v88, 16, v82
	v_and_b32_e32 v89, 0xffff0000, v82
	v_lshlrev_b32_e32 v82, 16, v83
	v_and_b32_e32 v83, 0xffff0000, v83
	v_pk_add_f32 v[78:79], v[78:79], v[80:81]
	v_pk_add_f32 v[76:77], v[76:77], v[86:87]
	v_pk_add_f32 v[80:81], v[74:75], v[82:83]
	v_pk_add_f32 v[74:75], v[72:73], v[88:89]
	v_cvt_pk_bf16_f32 v72, v76, v77
	v_cvt_pk_bf16_f32 v73, v78, v79
	s_nop 0
	v_cvt_pk_bf16_f32 v74, v74, v75
	v_cvt_pk_bf16_f32 v75, v80, v81
	v_lshlrev_b64 v[80:81], 11, v[148:149]
	v_lshl_add_u64 v[80:81], v[80:81], 0, v[146:147]
	v_lshlrev_b64 v[80:81], 1, v[80:81]
	flat_store_dwordx4 v[98:99], v[72:75]
	v_lshl_add_u64 v[82:83], s[50:51], 0, v[80:81]
	v_lshl_add_u64 v[82:83], v[82:83], 0, s[52:53]
	s_waitcnt vmcnt(13) lgkmcnt(0)
	s_nop 1
	v_mov_b32_e32 v76, v228
	v_mov_b32_e32 v77, v229
	v_mov_b32_e32 v78, v230
	v_mov_b32_e32 v79, v231
	v_lshlrev_b64 v[198:199], 11, v[140:141]
	v_lshl_add_u64 v[200:201], v[198:199], 0, v[146:147]
	v_lshlrev_b64 v[202:203], 1, v[200:201]
	v_lshl_add_u64 v[204:205], s[50:51], 0, v[202:203]
	v_lshl_add_u64 v[206:207], v[204:205], 0, s[52:53]
	global_load_dwordx4 v[228:231], v[206:207], off nt
	v_lshlrev_b32_e32 v72, 16, v76
	v_and_b32_e32 v73, 0xffff0000, v76
	v_lshlrev_b32_e32 v74, 16, v77
	v_and_b32_e32 v75, 0xffff0000, v77
	v_lshlrev_b32_e32 v76, 16, v78
	v_and_b32_e32 v77, 0xffff0000, v78
	v_lshlrev_b32_e32 v78, 16, v79
	v_and_b32_e32 v79, 0xffff0000, v79
	v_pk_add_f32 v[68:69], v[68:69], v[72:73]
	v_pk_add_f32 v[72:73], v[66:67], v[78:79]
	v_pk_add_f32 v[66:67], v[64:65], v[76:77]
	v_pk_add_f32 v[70:71], v[70:71], v[74:75]
	v_cvt_pk_bf16_f32 v64, v68, v69
	v_lshl_add_u64 v[68:69], s[48:49], 0, v[80:81]
	v_cvt_pk_bf16_f32 v65, v70, v71
	v_cvt_pk_bf16_f32 v66, v66, v67
	v_cvt_pk_bf16_f32 v67, v72, v73
	flat_store_dwordx4 v[84:85], v[64:67] offset:256
	s_waitcnt vmcnt(13) lgkmcnt(0)
	s_nop 1
	v_mov_b32_e32 v64, v232
	v_mov_b32_e32 v65, v233
	v_mov_b32_e32 v66, v234
	v_mov_b32_e32 v67, v235
	v_lshlrev_b64 v[198:199], 11, v[140:141]
	v_lshl_add_u64 v[200:201], v[198:199], 0, v[146:147]
	v_lshlrev_b64 v[202:203], 1, v[200:201]
	v_lshl_add_u64 v[204:205], s[48:49], 0, v[202:203]
	global_load_dwordx4 v[232:235], v[204:205], off offset:256 nt
	v_lshlrev_b32_e32 v70, 16, v64
	v_and_b32_e32 v71, 0xffff0000, v64
	v_lshlrev_b32_e32 v64, 16, v65
	v_and_b32_e32 v65, 0xffff0000, v65
	v_lshlrev_b32_e32 v72, 16, v66
	v_and_b32_e32 v73, 0xffff0000, v66
	v_lshlrev_b32_e32 v66, 16, v67
	v_and_b32_e32 v67, 0xffff0000, v67
	v_pk_add_f32 v[62:63], v[62:63], v[64:65]
	v_pk_add_f32 v[60:61], v[60:61], v[70:71]
	v_pk_add_f32 v[64:65], v[58:59], v[66:67]
	v_pk_add_f32 v[58:59], v[56:57], v[72:73]
	v_cvt_pk_bf16_f32 v56, v60, v61
	v_cvt_pk_bf16_f32 v57, v62, v63
	s_nop 0
	v_cvt_pk_bf16_f32 v58, v58, v59
	v_cvt_pk_bf16_f32 v59, v64, v65
	v_lshlrev_b64 v[64:65], 11, v[144:145]
	v_lshl_add_u64 v[64:65], v[64:65], 0, v[146:147]
	v_lshlrev_b64 v[64:65], 1, v[64:65]
	flat_store_dwordx4 v[82:83], v[56:59]
	v_lshl_add_u64 v[66:67], s[50:51], 0, v[64:65]
	v_lshl_add_u64 v[66:67], v[66:67], 0, s[52:53]
	s_waitcnt vmcnt(13) lgkmcnt(0)
	s_nop 1
	v_mov_b32_e32 v60, v236
	v_mov_b32_e32 v61, v237
	v_mov_b32_e32 v62, v238
	v_mov_b32_e32 v63, v239
	v_lshlrev_b32_e32 v56, 16, v60
	v_and_b32_e32 v57, 0xffff0000, v60
	v_lshlrev_b32_e32 v58, 16, v61
	v_and_b32_e32 v59, 0xffff0000, v61
	v_lshlrev_b32_e32 v60, 16, v62
	v_and_b32_e32 v61, 0xffff0000, v62
	v_lshlrev_b32_e32 v62, 16, v63
	v_and_b32_e32 v63, 0xffff0000, v63
	v_pk_add_f32 v[52:53], v[52:53], v[56:57]
	v_pk_add_f32 v[56:57], v[50:51], v[62:63]
	v_pk_add_f32 v[50:51], v[48:49], v[60:61]
	v_pk_add_f32 v[54:55], v[54:55], v[58:59]
	v_cvt_pk_bf16_f32 v48, v52, v53
	v_lshl_add_u64 v[52:53], s[48:49], 0, v[64:65]
	v_cvt_pk_bf16_f32 v49, v54, v55
	v_cvt_pk_bf16_f32 v50, v50, v51
	v_cvt_pk_bf16_f32 v51, v56, v57
	flat_store_dwordx4 v[68:69], v[48:51] offset:256
	s_waitcnt vmcnt(12) lgkmcnt(0)
	s_nop 1
	v_mov_b32_e32 v48, v240
	v_mov_b32_e32 v49, v241
	v_mov_b32_e32 v50, v242
	v_mov_b32_e32 v51, v243
	v_lshlrev_b32_e32 v54, 16, v48
	v_and_b32_e32 v55, 0xffff0000, v48
	v_lshlrev_b32_e32 v48, 16, v49
	v_and_b32_e32 v49, 0xffff0000, v49
	v_lshlrev_b32_e32 v56, 16, v50
	v_and_b32_e32 v57, 0xffff0000, v50
	v_lshlrev_b32_e32 v50, 16, v51
	v_and_b32_e32 v51, 0xffff0000, v51
	v_pk_add_f32 v[46:47], v[46:47], v[48:49]
	v_pk_add_f32 v[44:45], v[44:45], v[54:55]
	v_pk_add_f32 v[48:49], v[42:43], v[50:51]
	v_pk_add_f32 v[42:43], v[40:41], v[56:57]
	v_cvt_pk_bf16_f32 v40, v44, v45
	v_cvt_pk_bf16_f32 v41, v46, v47
	s_nop 0
	v_cvt_pk_bf16_f32 v42, v42, v43
	v_cvt_pk_bf16_f32 v43, v48, v49
	v_lshlrev_b64 v[48:49], 11, v[142:143]
	v_lshl_add_u64 v[48:49], v[48:49], 0, v[146:147]
	v_lshlrev_b64 v[48:49], 1, v[48:49]
	flat_store_dwordx4 v[66:67], v[40:43]
	v_lshl_add_u64 v[50:51], s[50:51], 0, v[48:49]
	v_lshl_add_u64 v[50:51], v[50:51], 0, s[52:53]
	s_waitcnt vmcnt(11) lgkmcnt(0)
	s_nop 1
	v_mov_b32_e32 v44, v244
	v_mov_b32_e32 v45, v245
	v_mov_b32_e32 v46, v246
	v_mov_b32_e32 v47, v247
	v_lshlrev_b32_e32 v40, 16, v44
	v_and_b32_e32 v41, 0xffff0000, v44
	v_lshlrev_b32_e32 v42, 16, v45
	v_and_b32_e32 v43, 0xffff0000, v45
	v_lshlrev_b32_e32 v44, 16, v46
	v_and_b32_e32 v45, 0xffff0000, v46
	v_lshlrev_b32_e32 v46, 16, v47
	v_and_b32_e32 v47, 0xffff0000, v47
	v_pk_add_f32 v[36:37], v[36:37], v[40:41]
	v_pk_add_f32 v[40:41], v[34:35], v[46:47]
	v_pk_add_f32 v[34:35], v[32:33], v[44:45]
	v_pk_add_f32 v[38:39], v[38:39], v[42:43]
	v_cvt_pk_bf16_f32 v32, v36, v37
	v_lshl_add_u64 v[36:37], s[48:49], 0, v[48:49]
	v_cvt_pk_bf16_f32 v33, v38, v39
	v_cvt_pk_bf16_f32 v34, v34, v35
	v_cvt_pk_bf16_f32 v35, v40, v41
	flat_store_dwordx4 v[52:53], v[32:35] offset:256
	s_waitcnt vmcnt(10) lgkmcnt(0)
	s_nop 1
	v_mov_b32_e32 v32, v248
	v_mov_b32_e32 v33, v249
	v_mov_b32_e32 v34, v250
	v_mov_b32_e32 v35, v251
	v_lshlrev_b32_e32 v38, 16, v32
	v_and_b32_e32 v39, 0xffff0000, v32
	v_lshlrev_b32_e32 v32, 16, v33
	v_and_b32_e32 v33, 0xffff0000, v33
	v_lshlrev_b32_e32 v40, 16, v34
	v_and_b32_e32 v41, 0xffff0000, v34
	v_lshlrev_b32_e32 v34, 16, v35
	v_and_b32_e32 v35, 0xffff0000, v35
	v_pk_add_f32 v[30:31], v[30:31], v[32:33]
	v_pk_add_f32 v[28:29], v[28:29], v[38:39]
	v_pk_add_f32 v[32:33], v[26:27], v[34:35]
	v_pk_add_f32 v[26:27], v[24:25], v[40:41]
	v_cvt_pk_bf16_f32 v24, v28, v29
	v_cvt_pk_bf16_f32 v25, v30, v31
	s_nop 0
	v_cvt_pk_bf16_f32 v26, v26, v27
	v_cvt_pk_bf16_f32 v27, v32, v33
	v_lshlrev_b64 v[32:33], 11, v[140:141]
	v_lshl_add_u64 v[32:33], v[32:33], 0, v[146:147]
	v_lshlrev_b64 v[32:33], 1, v[32:33]
	flat_store_dwordx4 v[50:51], v[24:27]
	v_lshl_add_u64 v[34:35], s[50:51], 0, v[32:33]
	v_lshl_add_u64 v[34:35], v[34:35], 0, s[52:53]
	s_waitcnt vmcnt(9) lgkmcnt(0)
	s_nop 1
	v_mov_b32_e32 v28, v252
	v_mov_b32_e32 v29, v253
	v_mov_b32_e32 v30, v254
	v_mov_b32_e32 v31, v255
	v_lshlrev_b32_e32 v24, 16, v28
	v_and_b32_e32 v25, 0xffff0000, v28
	v_lshlrev_b32_e32 v26, 16, v29
	v_and_b32_e32 v27, 0xffff0000, v29
	v_lshlrev_b32_e32 v28, 16, v30
	v_and_b32_e32 v29, 0xffff0000, v30
	v_lshlrev_b32_e32 v30, 16, v31
	v_and_b32_e32 v31, 0xffff0000, v31
	v_pk_add_f32 v[20:21], v[20:21], v[24:25]
	v_pk_add_f32 v[24:25], v[18:19], v[30:31]
	v_pk_add_f32 v[18:19], v[16:17], v[28:29]
	v_pk_add_f32 v[22:23], v[22:23], v[26:27]
	v_cvt_pk_bf16_f32 v16, v20, v21
	v_lshl_add_u64 v[20:21], s[48:49], 0, v[32:33]
	v_cvt_pk_bf16_f32 v17, v22, v23
	v_cvt_pk_bf16_f32 v18, v18, v19
	v_cvt_pk_bf16_f32 v19, v24, v25
	flat_store_dwordx4 v[36:37], v[16:19] offset:256
	s_waitcnt vmcnt(8) lgkmcnt(0)
	s_nop 1
	v_mov_b32_e32 v16, v228
	v_mov_b32_e32 v17, v229
	v_mov_b32_e32 v18, v230
	v_mov_b32_e32 v19, v231
	v_lshlrev_b32_e32 v22, 16, v16
	v_and_b32_e32 v23, 0xffff0000, v16
	v_lshlrev_b32_e32 v16, 16, v17
	v_and_b32_e32 v17, 0xffff0000, v17
	v_lshlrev_b32_e32 v24, 16, v18
	v_and_b32_e32 v25, 0xffff0000, v18
	v_lshlrev_b32_e32 v18, 16, v19
	v_and_b32_e32 v19, 0xffff0000, v19
	v_pk_add_f32 v[14:15], v[14:15], v[16:17]
	v_pk_add_f32 v[12:13], v[12:13], v[22:23]
	v_pk_add_f32 v[16:17], v[10:11], v[18:19]
	v_pk_add_f32 v[10:11], v[8:9], v[24:25]
	v_cvt_pk_bf16_f32 v8, v12, v13
	v_cvt_pk_bf16_f32 v9, v14, v15
	s_nop 0
	v_cvt_pk_bf16_f32 v10, v10, v11
	v_cvt_pk_bf16_f32 v11, v16, v17
	s_nop 0
	flat_store_dwordx4 v[34:35], v[8:11]
	s_waitcnt vmcnt(7) lgkmcnt(0)
	s_nop 1
	v_mov_b32_e32 v12, v232
	v_mov_b32_e32 v13, v233
	v_mov_b32_e32 v14, v234
	v_mov_b32_e32 v15, v235
	s_nop 0
	v_lshlrev_b32_e32 v8, 16, v12
	v_and_b32_e32 v9, 0xffff0000, v12
	v_lshlrev_b32_e32 v10, 16, v13
	v_and_b32_e32 v11, 0xffff0000, v13
	v_lshlrev_b32_e32 v12, 16, v14
	v_and_b32_e32 v13, 0xffff0000, v14
	v_lshlrev_b32_e32 v14, 16, v15
	v_and_b32_e32 v15, 0xffff0000, v15
	v_pk_add_f32 v[4:5], v[4:5], v[8:9]
	v_pk_add_f32 v[8:9], v[2:3], v[14:15]
	v_pk_add_f32 v[2:3], v[0:1], v[12:13]
	v_pk_add_f32 v[6:7], v[6:7], v[10:11]
	v_cvt_pk_bf16_f32 v0, v4, v5
	s_nop 0
	v_cvt_pk_bf16_f32 v1, v6, v7
	v_cvt_pk_bf16_f32 v2, v2, v3
	v_cvt_pk_bf16_f32 v3, v8, v9
	flat_store_dwordx4 v[20:21], v[0:3] offset:256

.LBB0_1291:
	s_or_b64 exec, exec, s[2:3]
	s_waitcnt lgkmcnt(0)
	s_barrier
	s_add_u32 s2, s34, 0x2aa00000
	s_mov_b32 s6, 25
	s_addc_u32 s3, s35, 0
	s_ashr_i32 s7, s6, 31
	s_lshl_b64 s[6:7], s[6:7], 3
	s_add_u32 s0, s0, s6
	s_addc_u32 s1, s1, s7
	s_load_dwordx2 s[0:1], s[0:1], 0x0
	v_and_b32_e32 v114, 63, v164
	s_and_b64 vcc, exec, s[4:5]
	v_lshlrev_b32_e32 v136, 4, v114
	v_lshlrev_b32_e32 v40, 5, v114
	s_cbranch_vccnz .LBB0_1293
	v_mov_b32_e32 v137, 0
	s_ashr_i32 s25, s24, 31
	v_lshl_add_u64 v[0:1], s[2:3], 0, v[136:137]
	s_lshl_b64 s[4:5], s[24:25], 12
	v_lshl_add_u64 v[2:3], v[0:1], 0, s[4:5]
	s_add_i32 s6, s24, s18
	flat_load_dwordx4 v[20:23], v[2:3] offset:1024 nt
	flat_load_dwordx4 v[36:39], v[2:3] offset:2048 nt
	flat_load_dwordx4 v[32:35], v[2:3] offset:3072 nt
	flat_load_dwordx4 v[44:47], v[2:3] nt
	s_ashr_i32 s7, s6, 31
	s_lshl_b64 s[4:5], s[6:7], 12
	v_lshl_add_u64 v[2:3], v[0:1], 0, s[4:5]
	flat_load_dwordx4 v[48:51], v[2:3] nt
	flat_load_dwordx4 v[52:55], v[2:3] offset:1024 nt
	flat_load_dwordx4 v[110:113], v[2:3] offset:2048 nt
	flat_load_dwordx4 v[8:11], v[2:3] offset:3072 nt
	v_readlane_b32 s14, v226, 1
	v_readlane_b32 s15, v226, 2
	s_ashr_i32 s15, s14, 31
	s_add_i32 s4, s6, s18
	s_lshl_b64 s[8:9], s[14:15], 12
	s_ashr_i32 s5, s4, 31
	v_lshl_add_u64 v[108:109], v[0:1], 0, s[8:9]
	s_lshl_b64 s[8:9], s[4:5], 12
	v_lshl_add_u64 v[42:43], v[0:1], 0, s[8:9]
	flat_load_dwordx4 v[28:31], v[108:109] nt
	flat_load_dwordx4 v[24:27], v[108:109] offset:1024 nt
	flat_load_dwordx4 v[16:19], v[42:43] nt
	flat_load_dwordx4 v[12:15], v[42:43] offset:1024 nt
	flat_load_dwordx4 v[4:7], v[42:43] offset:2048 nt
	flat_load_dwordx4 v[0:3], v[42:43] offset:3072 nt
	s_waitcnt lgkmcnt(0)
	v_add_u32_e32 v204, 0x1000, v40
	global_load_dwordx4 v[166:169], v40, s[0:1]
	global_load_dwordx4 v[170:173], v40, s[0:1] offset:16
	global_load_dwordx4 v[174:177], v40, s[0:1] offset:2048
	global_load_dwordx4 v[178:181], v40, s[0:1] offset:2064
	global_load_dwordx4 v[182:185], v204, s[0:1]
	global_load_dwordx4 v[186:189], v204, s[0:1] offset:16
	global_load_dwordx4 v[190:193], v204, s[0:1] offset:2048
	global_load_dwordx4 v[200:203], v204, s[0:1] offset:2064
	s_mov_b32 s12, 0x358637bd
	s_mov_b32 s8, 0x3a000000
	s_lshl_b64 s[10:11], s[24:25], 13
	s_add_u32 s10, s20, s10
	v_mov_b32_e32 v41, v137
	s_addc_u32 s11, s21, s11
	v_mov_b32_e32 v105, v137
	s_lshl_b64 s[6:7], s[6:7], 13
	s_add_u32 s6, s20, s6
	s_addc_u32 s7, s21, s7
	s_lshl_b64 s[4:5], s[4:5], 13
	s_add_u32 s4, s20, s4
	s_addc_u32 s5, s21, s5
	s_waitcnt vmcnt(0)
	v_mov_b32_e32 v122, v170
	v_mov_b32_e32 v123, v171
	v_mov_b32_e32 v124, v172
	v_mov_b32_e32 v125, v173
	v_mov_b32_e32 v126, v166
	v_mov_b32_e32 v127, v167
	v_mov_b32_e32 v128, v168
	v_mov_b32_e32 v129, v169
	v_lshlrev_b32_e32 v69, 16, v20
	v_lshlrev_b32_e32 v57, 16, v36
	v_and_b32_e32 v59, 0xffff0000, v36
	v_and_b32_e32 v75, 0xffff0000, v44
	v_and_b32_e32 v74, 0xffff0000, v48
	v_lshlrev_b32_e32 v67, 16, v44
	v_lshlrev_b32_e32 v71, 16, v45
	v_and_b32_e32 v79, 0xffff0000, v45
	v_and_b32_e32 v45, 0xffff0000, v37
	v_lshlrev_b32_e32 v63, 16, v37
	v_lshlrev_b32_e32 v66, 16, v48
	v_pk_mul_f32 v[36:37], v[74:75], v[74:75]
	v_lshlrev_b32_e32 v73, 16, v46
	v_and_b32_e32 v87, 0xffff0000, v46
	v_lshlrev_b32_e32 v85, 16, v47
	v_and_b32_e32 v99, 0xffff0000, v47
	v_lshlrev_b32_e32 v70, 16, v49
	v_pk_fma_f32 v[46:47], v[66:67], v[66:67], v[36:37]
	v_and_b32_e32 v78, 0xffff0000, v49
	v_pk_fma_f32 v[46:47], v[70:71], v[70:71], v[46:47]
	v_lshlrev_b32_e32 v72, 16, v50
	v_pk_fma_f32 v[46:47], v[78:79], v[78:79], v[46:47]
	v_and_b32_e32 v86, 0xffff0000, v50
	v_pk_fma_f32 v[46:47], v[72:73], v[72:73], v[46:47]
	v_lshlrev_b32_e32 v84, 16, v51
	v_pk_fma_f32 v[46:47], v[86:87], v[86:87], v[46:47]
	v_and_b32_e32 v98, 0xffff0000, v51
	v_pk_fma_f32 v[46:47], v[84:85], v[84:85], v[46:47]
	v_lshlrev_b32_e32 v68, 16, v52
	v_pk_fma_f32 v[46:47], v[98:99], v[98:99], v[46:47]
	v_and_b32_e32 v61, 0xffff0000, v20
	v_and_b32_e32 v60, 0xffff0000, v52
	v_pk_fma_f32 v[46:47], v[68:69], v[68:69], v[46:47]
	v_lshlrev_b32_e32 v77, 16, v21
	v_lshlrev_b32_e32 v76, 16, v53
	v_pk_fma_f32 v[46:47], v[60:61], v[60:61], v[46:47]
	v_and_b32_e32 v95, 0xffff0000, v21
	v_and_b32_e32 v94, 0xffff0000, v53
	v_pk_fma_f32 v[46:47], v[76:77], v[76:77], v[46:47]
	v_lshlrev_b32_e32 v81, 16, v22
	v_lshlrev_b32_e32 v80, 16, v54
	v_pk_fma_f32 v[46:47], v[94:95], v[94:95], v[46:47]
	v_and_b32_e32 v89, 0xffff0000, v22
	v_and_b32_e32 v88, 0xffff0000, v54
	v_pk_fma_f32 v[46:47], v[80:81], v[80:81], v[46:47]
	v_lshlrev_b32_e32 v91, 16, v23
	v_lshlrev_b32_e32 v90, 16, v55
	v_pk_fma_f32 v[46:47], v[88:89], v[88:89], v[46:47]
	v_and_b32_e32 v97, 0xffff0000, v23
	v_and_b32_e32 v96, 0xffff0000, v55
	v_pk_fma_f32 v[46:47], v[90:91], v[90:91], v[46:47]
	v_lshlrev_b32_e32 v56, 16, v110
	v_pk_fma_f32 v[46:47], v[96:97], v[96:97], v[46:47]
	v_and_b32_e32 v58, 0xffff0000, v110
	v_pk_fma_f32 v[46:47], v[56:57], v[56:57], v[46:47]
	v_lshlrev_b32_e32 v62, 16, v111
	v_pk_fma_f32 v[46:47], v[58:59], v[58:59], v[46:47]
	v_lshlrev_b32_e32 v43, 16, v38
	v_and_b32_e32 v65, 0xffff0000, v38
	v_and_b32_e32 v44, 0xffff0000, v111
	v_lshlrev_b32_e32 v83, 16, v39
	v_and_b32_e32 v93, 0xffff0000, v39
	v_pk_fma_f32 v[38:39], v[62:63], v[62:63], v[46:47]
	v_lshlrev_b32_e32 v42, 16, v112
	v_pk_fma_f32 v[38:39], v[44:45], v[44:45], v[38:39]
	v_and_b32_e32 v64, 0xffff0000, v112
	v_pk_fma_f32 v[38:39], v[42:43], v[42:43], v[38:39]
	v_lshlrev_b32_e32 v82, 16, v113
	v_pk_fma_f32 v[38:39], v[64:65], v[64:65], v[38:39]
	v_and_b32_e32 v92, 0xffff0000, v113
	v_pk_fma_f32 v[38:39], v[82:83], v[82:83], v[38:39]
	v_and_b32_e32 v100, 0xffff0000, v34
	v_pk_fma_f32 v[38:39], v[92:93], v[92:93], v[38:39]
	v_lshlrev_b32_e32 v47, 16, v32
	v_lshlrev_b32_e32 v46, 16, v8
	v_lshlrev_b32_e32 v103, 16, v34
	v_mov_b32_e32 v102, v100
	v_and_b32_e32 v34, 0xffff0000, v10
	v_and_b32_e32 v49, 0xffff0000, v32
	v_and_b32_e32 v48, 0xffff0000, v8
	v_lshlrev_b32_e32 v52, 16, v9
	v_and_b32_e32 v54, 0xffff0000, v9
	v_pk_fma_f32 v[8:9], v[46:47], v[46:47], v[38:39]
	v_lshlrev_b32_e32 v51, 16, v10
	v_pk_mul_f32 v[22:23], v[102:103], v[102:103]
	v_mov_b32_e32 v50, v34
	v_lshlrev_b32_e32 v53, 16, v33
	v_pk_fma_f32 v[8:9], v[48:49], v[48:49], v[8:9]
	v_and_b32_e32 v10, 64, v196
	v_and_b32_e32 v104, 0xffff0000, v35
	v_pk_mul_f32 v[36:37], v[50:51], v[50:51]
	v_and_b32_e32 v55, 0xffff0000, v33
	v_pk_fma_f32 v[8:9], v[52:53], v[52:53], v[8:9]
	v_mov_b32_e32 v33, v23
	v_and_b32_e32 v110, 0xffff0000, v11
	v_add_u32_e32 v10, 64, v10
	v_xor_b32_e32 v23, 1, v196
	v_lshlrev_b32_e32 v107, 16, v35
	v_mov_b32_e32 v106, v104
	v_pk_fma_f32 v[8:9], v[54:55], v[54:55], v[8:9]
	v_mov_b32_e32 v32, v37
	v_lshlrev_b32_e32 v113, 16, v11
	v_mov_b32_e32 v112, v110
	v_cmp_lt_i32_e32 vcc, v23, v10
	v_pk_mul_f32 v[20:21], v[106:107], v[106:107]
	v_pk_add_f32 v[8:9], v[32:33], v[8:9]
	v_pk_mul_f32 v[32:33], v[112:113], v[112:113]
	v_cndmask_b32_e32 v23, v196, v23, vcc
	v_mov_b32_e32 v37, v22
	v_lshlrev_b32_e32 v115, 2, v23
	v_pk_add_f32 v[8:9], v[36:37], v[8:9]
	v_mov_b32_e32 v22, v33
	v_mov_b32_e32 v23, v21
	v_pk_add_f32 v[8:9], v[22:23], v[8:9]
	v_mov_b32_e32 v33, v20
	v_pk_add_f32 v[8:9], v[32:33], v[8:9]
	ds_bpermute_b32 v21, v115, v9
	ds_bpermute_b32 v20, v115, v8
	v_xor_b32_e32 v22, 2, v196
	v_cmp_lt_i32_e32 vcc, v22, v10
	v_mov_b32_e32 v132, v71
	v_mov_b32_e32 v133, v79
	v_cndmask_b32_e32 v22, v196, v22, vcc
	v_lshlrev_b32_e32 v117, 2, v22
	s_waitcnt lgkmcnt(0)
	v_pk_add_f32 v[8:9], v[8:9], v[20:21]
	ds_bpermute_b32 v21, v117, v9
	ds_bpermute_b32 v20, v117, v8
	v_xor_b32_e32 v22, 4, v196
	v_cmp_lt_i32_e32 vcc, v22, v10
	v_mov_b32_e32 v134, v69
	v_mov_b32_e32 v135, v61
	v_cndmask_b32_e32 v22, v196, v22, vcc
	v_lshlrev_b32_e32 v118, 2, v22
	s_waitcnt lgkmcnt(0)
	v_pk_add_f32 v[8:9], v[8:9], v[20:21]
	ds_bpermute_b32 v21, v118, v9
	ds_bpermute_b32 v20, v118, v8
	v_xor_b32_e32 v22, 8, v196
	v_cmp_lt_i32_e32 vcc, v22, v10
	v_mov_b32_e32 v138, v91
	v_mov_b32_e32 v139, v97
	v_cndmask_b32_e32 v22, v196, v22, vcc
	v_lshlrev_b32_e32 v119, 2, v22
	s_waitcnt lgkmcnt(0)
	v_pk_add_f32 v[8:9], v[8:9], v[20:21]
	ds_bpermute_b32 v21, v119, v9
	ds_bpermute_b32 v20, v119, v8
	v_xor_b32_e32 v22, 16, v196
	v_cmp_lt_i32_e32 vcc, v22, v10
	v_mov_b32_e32 v140, v81
	v_mov_b32_e32 v141, v89
	v_cndmask_b32_e32 v22, v196, v22, vcc
	v_lshlrev_b32_e32 v120, 2, v22
	s_waitcnt lgkmcnt(0)
	v_pk_add_f32 v[8:9], v[8:9], v[20:21]
	ds_bpermute_b32 v21, v120, v9
	ds_bpermute_b32 v20, v120, v8
	v_xor_b32_e32 v22, 32, v196
	v_cmp_lt_i32_e32 vcc, v22, v10
	v_mov_b32_e32 v142, v43
	v_mov_b32_e32 v143, v65
	v_cndmask_b32_e32 v10, v196, v22, vcc
	v_lshlrev_b32_e32 v116, 2, v10
	s_waitcnt lgkmcnt(0)
	v_pk_add_f32 v[8:9], v[8:9], v[20:21]
	ds_bpermute_b32 v33, v116, v9
	ds_bpermute_b32 v32, v116, v8
	flat_load_dwordx4 v[36:39], v[108:109] offset:2048 nt
	flat_load_dwordx4 v[20:23], v[108:109] offset:3072 nt
	v_mov_b64_e32 v[108:109], s[12:13]
	v_and_b32_e32 v101, s0, v35
	v_pk_mov_b32 v[104:105], v[106:107], v[104:105] op_sel:[1,0]
	s_waitcnt lgkmcnt(0)
	v_pk_add_f32 v[8:9], v[8:9], v[32:33]
	v_mov_b32_e32 v33, v75
	v_pk_fma_f32 v[130:131], v[8:9], s[8:9], v[108:109] op_sel_hi:[1,0,0]
	s_mov_b32 s9, 0x800000
	v_mul_f32_e32 v8, 0x4b800000, v131
	v_cmp_gt_f32_e32 vcc, s9, v131
	v_pk_mov_b32 v[100:101], v[102:103], v[100:101] op_sel:[1,0]
	v_mov_b32_e32 v71, v78
	v_cndmask_b32_e32 v8, v131, v8, vcc
	v_rsq_f32_e32 v10, v8
	v_lshl_add_u64 v[8:9], s[10:11], 0, v[40:41]
	v_mov_b32_e32 v69, v60
	v_mov_b32_e32 v81, v88
	v_mul_f32_e32 v32, 0x45800000, v10
	v_cndmask_b32_e32 v10, v10, v32, vcc
	v_mov_b32_e32 v32, v67
	v_pk_mul_f32 v[32:33], v[32:33], v[10:11] op_sel_hi:[1,0]
	v_pk_mul_f32 v[132:133], v[132:133], v[10:11] op_sel_hi:[1,0]
	v_pk_mul_f32 v[126:127], v[126:127], v[32:33]
	v_pk_mul_f32 v[128:129], v[128:129], v[132:133]
	v_mov_b32_e32 v32, v73
	v_mov_b32_e32 v33, v87
	v_mov_b32_e32 v132, v85
	v_mov_b32_e32 v133, v99
	v_pk_mul_f32 v[32:33], v[32:33], v[10:11] op_sel_hi:[1,0]
	v_pk_mul_f32 v[132:133], v[132:133], v[10:11] op_sel_hi:[1,0]
	v_pk_mul_f32 v[122:123], v[122:123], v[32:33]
	v_pk_mul_f32 v[124:125], v[124:125], v[132:133]
	global_store_dwordx4 v[8:9], v[126:129], off
	s_nop 1
	global_store_dwordx4 v[8:9], v[122:125], off offset:16
	s_nop 1
	s_nop 0
	v_mov_b32_e32 v132, v77
	v_mov_b32_e32 v133, v95
	v_pk_mul_f32 v[132:133], v[132:133], v[10:11] op_sel_hi:[1,0]
	v_pk_mul_f32 v[134:135], v[134:135], v[10:11] op_sel_hi:[1,0]
	v_pk_mul_f32 v[138:139], v[138:139], v[10:11] op_sel_hi:[1,0]
	v_pk_mul_f32 v[140:141], v[140:141], v[10:11] op_sel_hi:[1,0]
	v_or_b32_e32 v32, 0x1000, v40
	v_mov_b32_e32 v33, v137
	v_pk_mul_f32 v[142:143], v[142:143], v[10:11] op_sel_hi:[1,0]
	v_cmp_gt_f32_e32 vcc, s9, v130
	v_mov_b32_e32 v67, v74
	v_mov_b32_e32 v73, v86
	v_mov_b32_e32 v85, v98
	v_mov_b32_e32 v77, v94
	v_mov_b32_e32 v91, v96
	v_lshlrev_b32_e32 v88, 16, v29
	v_and_b32_e32 v94, 0xffff0000, v29
	v_mov_b32_e32 v43, v64
	v_and_b32_e32 v96, 0xffff0000, v30
	v_and_b32_e32 v98, 0xffff0000, v31
	v_lshlrev_b32_e32 v89, 16, v17
	v_and_b32_e32 v95, 0xffff0000, v17
	v_and_b32_e32 v97, 0xffff0000, v18
	v_and_b32_e32 v99, 0xffff0000, v19
	v_mov_b32_e32 v111, v137
	v_and_b32_e32 v65, 0xffff0000, v7
	s_waitcnt vmcnt(2)
	v_mov_b32_e32 v122, v174
	v_mov_b32_e32 v123, v175
	v_mov_b32_e32 v124, v176
	v_mov_b32_e32 v125, v177
	v_mov_b32_e32 v126, v178
	v_mov_b32_e32 v127, v179
	v_mov_b32_e32 v128, v180
	v_mov_b32_e32 v129, v181
	v_and_b32_e32 v64, 0xffff0000, v39
	v_pk_mul_f32 v[122:123], v[122:123], v[134:135]
	v_pk_mul_f32 v[124:125], v[124:125], v[132:133]
	v_pk_mul_f32 v[126:127], v[126:127], v[140:141]
	v_pk_mul_f32 v[128:129], v[128:129], v[138:139]
	global_store_dwordx4 v[8:9], v[122:125], off offset:2048
	s_nop 1
	global_store_dwordx4 v[8:9], v[126:129], off offset:2064
	s_nop 1
	s_nop 0
	v_mov_b32_e32 v134, v63
	v_mov_b32_e32 v135, v45
	v_mov_b32_e32 v138, v57
	v_mov_b32_e32 v139, v59
	v_mov_b32_e32 v140, v83
	v_mov_b32_e32 v141, v93
	v_pk_mul_f32 v[134:135], v[134:135], v[10:11] op_sel_hi:[1,0]
	v_pk_mul_f32 v[138:139], v[138:139], v[10:11] op_sel_hi:[1,0]
	v_lshl_add_u64 v[132:133], s[10:11], 0, v[32:33]
	v_pk_mul_f32 v[140:141], v[140:141], v[10:11] op_sel_hi:[1,0]
	v_or_b32_e32 v8, 0x1800, v40
	v_mov_b32_e32 v9, v137
	v_mov_b32_e32 v57, v58
	v_mov_b32_e32 v63, v44
	v_mov_b32_e32 v83, v92
	v_and_b32_e32 v59, 0xffff0000, v4
	v_and_b32_e32 v58, 0xffff0000, v36
	v_and_b32_e32 v92, 0xffff0000, v2
	v_and_b32_e32 v93, s0, v3
	v_mov_b32_e32 v122, v182
	v_mov_b32_e32 v123, v183
	v_mov_b32_e32 v124, v184
	v_mov_b32_e32 v125, v185
	v_mov_b32_e32 v126, v186
	v_mov_b32_e32 v127, v187
	v_mov_b32_e32 v128, v188
	v_mov_b32_e32 v129, v189
	v_pk_mul_f32 v[122:123], v[122:123], v[138:139]
	v_pk_mul_f32 v[124:125], v[124:125], v[134:135]
	v_pk_mul_f32 v[126:127], v[126:127], v[142:143]
	v_pk_mul_f32 v[128:129], v[128:129], v[140:141]
	global_store_dwordx4 v[132:133], v[122:125], off
	s_nop 1
	global_store_dwordx4 v[132:133], v[126:129], off offset:16
	s_nop 1
	s_nop 0
	v_mov_b32_e32 v134, v53
	v_mov_b32_e32 v135, v55
	v_mov_b32_e32 v138, v47
	v_mov_b32_e32 v139, v49
	v_pk_mul_f32 v[102:103], v[134:135], v[10:11] op_sel_hi:[1,0]
	v_pk_mul_f32 v[106:107], v[138:139], v[10:11] op_sel_hi:[1,0]
	v_lshl_add_u64 v[132:133], s[10:11], 0, v[8:9]
	v_pk_mul_f32 v[134:135], v[10:11], v[104:105] op_sel_hi:[0,1]
	v_pk_mul_f32 v[104:105], v[10:11], v[100:101] op_sel_hi:[0,1]
	v_mul_f32_e32 v10, 0x4b800000, v130
	v_cndmask_b32_e32 v10, v130, v10, vcc
	v_rsq_f32_e32 v10, v10
	v_mov_b32_e32 v47, v48
	v_mov_b32_e32 v53, v54
	v_mov_b32_e32 v49, v99
	v_mul_f32_e32 v35, 0x45800000, v10
	v_cndmask_b32_e32 v130, v10, v35, vcc
	v_pk_mul_f32 v[74:75], v[70:71], v[130:131] op_sel_hi:[1,0]
	v_pk_mul_f32 v[66:67], v[66:67], v[130:131] op_sel_hi:[1,0]
	v_pk_mul_f32 v[78:79], v[84:85], v[130:131] op_sel_hi:[1,0]
	v_pk_mul_f32 v[84:85], v[72:73], v[130:131] op_sel_hi:[1,0]
	v_pk_mul_f32 v[60:61], v[76:77], v[130:131] op_sel_hi:[1,0]
	v_pk_mul_f32 v[76:77], v[80:81], v[130:131] op_sel_hi:[1,0]
	v_and_b32_e32 v80, 0xffff0000, v25
	v_pk_mul_f32 v[44:45], v[82:83], v[130:131] op_sel_hi:[1,0]
	v_pk_mul_f32 v[42:43], v[42:43], v[130:131] op_sel_hi:[1,0]
	v_and_b32_e32 v10, 0xffff0000, v22
	v_and_b32_e32 v82, 0xffff0000, v27
	v_and_b32_e32 v35, s0, v11
	v_and_b32_e32 v81, 0xffff0000, v13
	v_and_b32_e32 v83, 0xffff0000, v15
	v_mov_b32_e32 v122, v190
	v_mov_b32_e32 v123, v191
	v_mov_b32_e32 v124, v192
	v_mov_b32_e32 v125, v193
	v_mov_b32_e32 v126, v200
	v_mov_b32_e32 v127, v201
	v_mov_b32_e32 v128, v202
	v_mov_b32_e32 v129, v203
	v_pk_mul_f32 v[100:101], v[106:107], v[122:123]
	v_pk_mul_f32 v[102:103], v[102:103], v[124:125]
	v_pk_mul_f32 v[104:105], v[104:105], v[126:127]
	v_pk_mul_f32 v[106:107], v[134:135], v[128:129]
	global_store_dwordx4 v[132:133], v[100:103], off
	s_nop 1
	global_store_dwordx4 v[132:133], v[104:107], off offset:16
	s_nop 1
	s_nop 0
	v_lshl_add_u64 v[122:123], s[6:7], 0, v[40:41]
	v_lshl_add_u64 v[132:133], s[6:7], 0, v[8:9]
	v_mov_b32_e32 v100, v166
	v_mov_b32_e32 v101, v167
	v_mov_b32_e32 v102, v168
	v_mov_b32_e32 v103, v169
	v_mov_b32_e32 v104, v170
	v_mov_b32_e32 v105, v171
	v_mov_b32_e32 v106, v172
	v_mov_b32_e32 v107, v173
	v_pk_mul_f32 v[70:71], v[66:67], v[100:101]
	v_pk_mul_f32 v[72:73], v[74:75], v[102:103]
	v_pk_mul_f32 v[84:85], v[84:85], v[104:105]
	v_pk_mul_f32 v[86:87], v[78:79], v[106:107]
	global_store_dwordx4 v[122:123], v[70:73], off
	s_nop 1
	global_store_dwordx4 v[122:123], v[84:87], off offset:16
	s_nop 1
	s_nop 0
	v_pk_mul_f32 v[66:67], v[68:69], v[130:131] op_sel_hi:[1,0]
	v_pk_mul_f32 v[74:75], v[90:91], v[130:131] op_sel_hi:[1,0]
	v_and_b32_e32 v100, 0xffff0000, v28
	v_and_b32_e32 v78, 0xffff0000, v24
	v_lshl_add_u64 v[106:107], s[6:7], 0, v[32:33]
	v_lshlrev_b32_e32 v90, 16, v31
	v_and_b32_e32 v101, 0xffff0000, v16
	v_lshlrev_b32_e32 v91, 16, v19
	v_and_b32_e32 v79, 0xffff0000, v12
	v_mov_b32_e32 v48, v91
	v_mov_b32_e32 v70, v174
	v_mov_b32_e32 v71, v175
	v_mov_b32_e32 v72, v176
	v_mov_b32_e32 v73, v177
	v_mov_b32_e32 v84, v178
	v_mov_b32_e32 v85, v179
	v_mov_b32_e32 v86, v180
	v_mov_b32_e32 v87, v181
	v_pk_mul_f32 v[66:67], v[66:67], v[70:71]
	v_pk_mul_f32 v[68:69], v[60:61], v[72:73]
	v_pk_mul_f32 v[70:71], v[76:77], v[84:85]
	v_pk_mul_f32 v[72:73], v[74:75], v[86:87]
	global_store_dwordx4 v[122:123], v[66:69], off offset:2048
	s_nop 1
	global_store_dwordx4 v[122:123], v[70:73], off offset:2064
	s_nop 1
	s_nop 0
	v_lshlrev_b32_e32 v84, 16, v28
	v_lshlrev_b32_e32 v68, 16, v24
	v_lshlrev_b32_e32 v72, 16, v25
	v_pk_mul_f32 v[24:25], v[62:63], v[130:131] op_sel_hi:[1,0]
	v_pk_mul_f32 v[28:29], v[56:57], v[130:131] op_sel_hi:[1,0]
	v_lshlrev_b32_e32 v86, 16, v30
	v_lshlrev_b32_e32 v85, 16, v16
	v_and_b32_e32 v67, 0xffff0000, v5
	v_lshlrev_b32_e32 v87, 16, v18
	v_lshlrev_b32_e32 v60, 16, v38
	v_lshlrev_b32_e32 v70, 16, v26
	v_and_b32_e32 v76, 0xffff0000, v26
	v_lshlrev_b32_e32 v74, 16, v27
	v_lshlrev_b32_e32 v27, 16, v22
	v_and_b32_e32 v62, 0xffff0000, v38
	v_lshlrev_b32_e32 v56, 16, v39
	v_lshlrev_b32_e32 v39, 16, v23
	v_mov_b32_e32 v26, v10
	v_lshlrev_b32_e32 v69, 16, v12
	v_lshlrev_b32_e32 v73, 16, v13
	v_lshlrev_b32_e32 v71, 16, v14
	v_and_b32_e32 v77, 0xffff0000, v14
	v_lshlrev_b32_e32 v75, 16, v15
	v_pk_mul_f32 v[16:17], v[26:27], v[26:27]
	v_pk_mov_b32 v[12:13], v[50:51], v[34:35] op_sel:[1,0]
	v_lshlrev_b32_e32 v61, 16, v6
	v_and_b32_e32 v63, 0xffff0000, v6
	v_lshlrev_b32_e32 v57, 16, v7
	v_mov_b32_e32 v18, v17
	v_pk_mov_b32 v[6:7], v[112:113], v[110:111] op_sel:[1,0]
	v_pk_mul_f32 v[12:13], v[130:131], v[12:13] op_sel_hi:[0,1]
	v_and_b32_e32 v66, 0xffff0000, v37
	v_mov_b32_e32 v102, v182
	v_mov_b32_e32 v103, v183
	v_mov_b32_e32 v104, v184
	v_mov_b32_e32 v105, v185
	v_mov_b32_e32 v122, v186
	v_mov_b32_e32 v123, v187
	v_mov_b32_e32 v124, v188
	v_mov_b32_e32 v125, v189
	v_pk_mul_f32 v[28:29], v[28:29], v[102:103]
	v_pk_mul_f32 v[30:31], v[24:25], v[104:105]
	v_pk_mul_f32 v[42:43], v[42:43], v[122:123]
	v_pk_mul_f32 v[44:45], v[44:45], v[124:125]
	global_store_dwordx4 v[106:107], v[28:31], off
	s_nop 1
	global_store_dwordx4 v[106:107], v[42:45], off offset:16
	s_nop 1
	v_lshlrev_b32_e32 v43, 16, v4
	v_lshlrev_b32_e32 v45, 16, v5
	v_pk_mul_f32 v[4:5], v[100:101], v[100:101]
	v_lshlrev_b32_e32 v42, 16, v36
	v_pk_fma_f32 v[4:5], v[84:85], v[84:85], v[4:5]
	v_and_b32_e32 v36, 0xffff0000, v23
	v_pk_fma_f32 v[4:5], v[88:89], v[88:89], v[4:5]
	v_and_b32_e32 v104, 0xffff0000, v3
	v_pk_fma_f32 v[4:5], v[94:95], v[94:95], v[4:5]
	v_mov_b32_e32 v38, v36
	v_pk_fma_f32 v[4:5], v[86:87], v[86:87], v[4:5]
	v_lshlrev_b32_e32 v103, 16, v2
	v_pk_fma_f32 v[4:5], v[96:97], v[96:97], v[4:5]
	v_lshlrev_b32_e32 v107, 16, v3
	v_mov_b32_e32 v102, v92
	v_mov_b32_e32 v106, v104
	v_pk_fma_f32 v[4:5], v[90:91], v[90:91], v[4:5]
	v_lshlrev_b32_e32 v24, 16, v20
	v_and_b32_e32 v28, 0xffff0000, v20
	v_lshlrev_b32_e32 v20, 16, v21
	v_and_b32_e32 v30, 0xffff0000, v21
	v_lshlrev_b32_e32 v25, 16, v0
	v_and_b32_e32 v29, 0xffff0000, v0
	v_lshlrev_b32_e32 v21, 16, v1
	v_and_b32_e32 v31, 0xffff0000, v1
	v_pk_mul_f32 v[0:1], v[38:39], v[38:39]
	v_pk_mul_f32 v[14:15], v[102:103], v[102:103]
	v_pk_mul_f32 v[50:51], v[106:107], v[106:107]
	v_pk_fma_f32 v[4:5], v[98:99], v[98:99], v[4:5]
	v_mov_b32_e32 v34, v1
	v_mov_b32_e32 v19, v15
	v_mov_b32_e32 v17, v14
	v_mov_b32_e32 v35, v51
	v_mov_b32_e32 v1, v50
	v_pk_fma_f32 v[50:51], v[68:69], v[68:69], v[4:5]
	v_pk_mul_f32 v[14:15], v[52:53], v[130:131] op_sel_hi:[1,0]
	v_pk_mul_f32 v[4:5], v[46:47], v[130:131] op_sel_hi:[1,0]
	v_pk_mul_f32 v[46:47], v[130:131], v[6:7] op_sel_hi:[0,1]
	v_lshlrev_b32_e32 v44, 16, v37
	v_mov_b32_e32 v105, v137
	v_mov_b32_e32 v91, v98
	v_mov_b32_e32 v37, v137
	v_mov_b32_e32 v122, v200
	v_mov_b32_e32 v123, v201
	v_mov_b32_e32 v124, v202
	v_mov_b32_e32 v125, v203
	v_mov_b32_e32 v126, v190
	v_mov_b32_e32 v127, v191
	v_mov_b32_e32 v128, v192
	v_mov_b32_e32 v129, v193
	v_pk_mul_f32 v[12:13], v[12:13], v[122:123]
	v_pk_mul_f32 v[4:5], v[4:5], v[126:127]
	v_pk_mul_f32 v[6:7], v[14:15], v[128:129]
	v_pk_mul_f32 v[14:15], v[46:47], v[124:125]
	global_store_dwordx4 v[132:133], v[4:7], off
	s_nop 1
	global_store_dwordx4 v[132:133], v[12:15], off offset:16
	s_nop 1
	s_nop 0
	v_pk_fma_f32 v[46:47], v[78:79], v[78:79], v[50:51]
	s_nop 0
	v_pk_fma_f32 v[46:47], v[72:73], v[72:73], v[46:47]
	s_nop 0
	v_pk_fma_f32 v[46:47], v[80:81], v[80:81], v[46:47]
	s_nop 0
	v_pk_fma_f32 v[46:47], v[70:71], v[70:71], v[46:47]
	s_nop 0
	v_pk_fma_f32 v[46:47], v[76:77], v[76:77], v[46:47]
	s_nop 0
	v_pk_fma_f32 v[46:47], v[74:75], v[74:75], v[46:47]
	s_nop 0
	v_pk_fma_f32 v[46:47], v[82:83], v[82:83], v[46:47]
	s_nop 0
	v_pk_fma_f32 v[46:47], v[42:43], v[42:43], v[46:47]
	s_nop 0
	v_pk_fma_f32 v[46:47], v[58:59], v[58:59], v[46:47]
	s_nop 0
	v_pk_fma_f32 v[46:47], v[44:45], v[44:45], v[46:47]
	s_nop 0
	v_pk_fma_f32 v[46:47], v[66:67], v[66:67], v[46:47]
	s_nop 0
	v_pk_fma_f32 v[46:47], v[60:61], v[60:61], v[46:47]
	s_nop 0
	v_pk_fma_f32 v[46:47], v[62:63], v[62:63], v[46:47]
	s_nop 0
	v_pk_fma_f32 v[46:47], v[56:57], v[56:57], v[46:47]
	s_nop 0
	v_pk_fma_f32 v[46:47], v[64:65], v[64:65], v[46:47]
	s_nop 0
	v_pk_fma_f32 v[46:47], v[24:25], v[24:25], v[46:47]
	s_nop 0
	v_pk_fma_f32 v[46:47], v[28:29], v[28:29], v[46:47]
	s_nop 0
	v_pk_fma_f32 v[46:47], v[20:21], v[20:21], v[46:47]
	s_nop 0
	v_pk_fma_f32 v[46:47], v[30:31], v[30:31], v[46:47]
	s_nop 0
	v_pk_add_f32 v[18:19], v[18:19], v[46:47]
	v_mov_b32_e32 v46, v85
	v_pk_add_f32 v[16:17], v[16:17], v[18:19]
	v_mov_b32_e32 v47, v101
	v_pk_add_f32 v[16:17], v[34:35], v[16:17]
	v_mov_b32_e32 v34, v89
	v_pk_add_f32 v[0:1], v[0:1], v[16:17]
	ds_bpermute_b32 v17, v115, v1
	ds_bpermute_b32 v16, v115, v0
	v_mov_b32_e32 v35, v95
	v_lshl_add_u64 v[18:19], s[4:5], 0, v[40:41]
	v_mov_b32_e32 v85, v100
	v_mov_b32_e32 v89, v94
	s_waitcnt lgkmcnt(0)
	v_pk_add_f32 v[0:1], v[0:1], v[16:17]
	ds_bpermute_b32 v17, v117, v1
	ds_bpermute_b32 v16, v117, v0
	s_waitcnt lgkmcnt(0)
	v_pk_add_f32 v[0:1], v[0:1], v[16:17]
	ds_bpermute_b32 v17, v118, v1
	ds_bpermute_b32 v16, v118, v0
	s_waitcnt lgkmcnt(0)
	v_pk_add_f32 v[0:1], v[0:1], v[16:17]
	ds_bpermute_b32 v17, v119, v1
	ds_bpermute_b32 v16, v119, v0
	s_waitcnt lgkmcnt(0)
	v_pk_add_f32 v[0:1], v[0:1], v[16:17]
	ds_bpermute_b32 v17, v120, v1
	ds_bpermute_b32 v16, v120, v0
	s_waitcnt lgkmcnt(0)
	v_pk_add_f32 v[0:1], v[0:1], v[16:17]
	ds_bpermute_b32 v17, v116, v1
	ds_bpermute_b32 v16, v116, v0
	s_waitcnt lgkmcnt(0)
	v_pk_add_f32 v[0:1], v[0:1], v[16:17]
	s_nop 0
	v_pk_fma_f32 v[16:17], v[0:1], s[8:9], v[108:109] op_sel_hi:[1,0,0]
	v_mov_b32_e32 v1, v97
	v_mul_f32_e32 v0, 0x4b800000, v17
	v_cmp_gt_f32_e32 vcc, s9, v17
	s_nop 1
	v_cndmask_b32_e32 v0, v17, v0, vcc
	v_rsq_f32_e32 v2, v0
	v_mov_b32_e32 v0, v87
	v_mov_b32_e32 v87, v96
	v_mul_f32_e32 v11, 0x45800000, v2
	v_cndmask_b32_e32 v2, v2, v11, vcc
	v_pk_mul_f32 v[34:35], v[34:35], v[2:3] op_sel_hi:[1,0]
	v_pk_mul_f32 v[46:47], v[46:47], v[2:3] op_sel_hi:[1,0]
	v_pk_mul_f32 v[48:49], v[48:49], v[2:3] op_sel_hi:[1,0]
	v_pk_mul_f32 v[0:1], v[0:1], v[2:3] op_sel_hi:[1,0]
	v_mov_b32_e32 v4, v170
	v_mov_b32_e32 v5, v171
	v_mov_b32_e32 v6, v172
	v_mov_b32_e32 v7, v173
	v_mov_b32_e32 v12, v166
	v_mov_b32_e32 v13, v167
	v_mov_b32_e32 v14, v168
	v_mov_b32_e32 v15, v169
	v_pk_mul_f32 v[12:13], v[46:47], v[12:13]
	v_pk_mul_f32 v[14:15], v[34:35], v[14:15]
	v_pk_mul_f32 v[4:5], v[0:1], v[4:5]
	v_pk_mul_f32 v[6:7], v[48:49], v[6:7]
	global_store_dwordx4 v[18:19], v[12:15], off
	s_nop 1
	global_store_dwordx4 v[18:19], v[4:7], off offset:16
	s_nop 1
	s_nop 0
	v_mov_b32_e32 v0, v73
	v_mov_b32_e32 v1, v81
	v_mov_b32_e32 v34, v69
	v_mov_b32_e32 v35, v79
	v_mov_b32_e32 v46, v75
	v_mov_b32_e32 v47, v83
	v_mov_b32_e32 v48, v71
	v_mov_b32_e32 v49, v77
	v_pk_mul_f32 v[0:1], v[0:1], v[2:3] op_sel_hi:[1,0]
	v_pk_mul_f32 v[34:35], v[34:35], v[2:3] op_sel_hi:[1,0]
	v_pk_mul_f32 v[46:47], v[46:47], v[2:3] op_sel_hi:[1,0]
	v_pk_mul_f32 v[48:49], v[48:49], v[2:3] op_sel_hi:[1,0]
	v_mul_f32_e32 v11, 0x4b800000, v16
	v_cmp_gt_f32_e32 vcc, s9, v16
	v_mov_b32_e32 v69, v78
	v_mov_b32_e32 v73, v80
	v_cndmask_b32_e32 v11, v16, v11, vcc
	v_rsq_f32_e32 v11, v11
	v_mov_b32_e32 v71, v76
	v_mov_b32_e32 v75, v82
	v_mov_b32_e32 v4, v174
	v_mov_b32_e32 v5, v175
	v_mov_b32_e32 v6, v176
	v_mov_b32_e32 v7, v177
	v_mov_b32_e32 v12, v178
	v_mov_b32_e32 v13, v179
	v_mov_b32_e32 v14, v180
	v_mov_b32_e32 v15, v181
	v_pk_mul_f32 v[4:5], v[34:35], v[4:5]
	v_pk_mul_f32 v[6:7], v[0:1], v[6:7]
	v_pk_mul_f32 v[12:13], v[48:49], v[12:13]
	v_pk_mul_f32 v[14:15], v[46:47], v[14:15]
	global_store_dwordx4 v[18:19], v[4:7], off offset:2048
	s_nop 1
	global_store_dwordx4 v[18:19], v[12:15], off offset:2064
	s_nop 1
	s_nop 0
	v_mov_b32_e32 v18, v45
	v_mov_b32_e32 v19, v67
	v_mov_b32_e32 v34, v43
	v_mov_b32_e32 v35, v59
	v_mov_b32_e32 v46, v57
	v_mov_b32_e32 v47, v65
	v_mov_b32_e32 v48, v61
	v_mov_b32_e32 v49, v63
	v_pk_mul_f32 v[18:19], v[18:19], v[2:3] op_sel_hi:[1,0]
	v_pk_mul_f32 v[34:35], v[34:35], v[2:3] op_sel_hi:[1,0]
	v_lshl_add_u64 v[0:1], s[4:5], 0, v[32:33]
	v_pk_mul_f32 v[46:47], v[46:47], v[2:3] op_sel_hi:[1,0]
	v_pk_mul_f32 v[48:49], v[48:49], v[2:3] op_sel_hi:[1,0]
	v_mov_b32_e32 v43, v58
	v_mov_b32_e32 v45, v66
	v_mov_b32_e32 v61, v62
	v_mov_b32_e32 v57, v64
	v_mov_b32_e32 v4, v182
	v_mov_b32_e32 v5, v183
	v_mov_b32_e32 v6, v184
	v_mov_b32_e32 v7, v185
	v_mov_b32_e32 v12, v186
	v_mov_b32_e32 v13, v187
	v_mov_b32_e32 v14, v188
	v_mov_b32_e32 v15, v189
	v_pk_mul_f32 v[4:5], v[34:35], v[4:5]
	v_pk_mul_f32 v[6:7], v[18:19], v[6:7]
	v_pk_mul_f32 v[12:13], v[48:49], v[12:13]
	v_pk_mul_f32 v[14:15], v[46:47], v[14:15]
	global_store_dwordx4 v[0:1], v[4:7], off
	s_nop 1
	global_store_dwordx4 v[0:1], v[12:15], off offset:16
	s_nop 1
	s_nop 0
	v_mov_b32_e32 v0, v21
	v_mov_b32_e32 v1, v31
	v_mov_b32_e32 v34, v25
	v_mov_b32_e32 v35, v29
	v_pk_mov_b32 v[46:47], v[106:107], v[104:105] op_sel:[1,0]
	v_pk_mov_b32 v[48:49], v[102:103], v[92:93] op_sel:[1,0]
	v_pk_mul_f32 v[50:51], v[0:1], v[2:3] op_sel_hi:[1,0]
	v_pk_mul_f32 v[0:1], v[34:35], v[2:3] op_sel_hi:[1,0]
	v_lshl_add_u64 v[18:19], s[4:5], 0, v[8:9]
	v_pk_mul_f32 v[34:35], v[2:3], v[46:47] op_sel_hi:[0,1]
	v_pk_mul_f32 v[46:47], v[2:3], v[48:49] op_sel_hi:[0,1]
	s_lshl_b64 s[4:5], s[14:15], 13
	s_add_u32 s4, s20, s4
	s_addc_u32 s5, s21, s5
	v_mov_b32_e32 v25, v28
	v_mov_b32_e32 v21, v30
	s_lshl_b32 s6, s26, 5
	s_add_i32 s24, s24, s6
	v_mov_b32_e32 v4, v190
	v_mov_b32_e32 v5, v191
	v_mov_b32_e32 v6, v192
	v_mov_b32_e32 v7, v193
	v_mov_b32_e32 v12, v200
	v_mov_b32_e32 v13, v201
	v_mov_b32_e32 v14, v202
	v_mov_b32_e32 v15, v203
	v_pk_mul_f32 v[0:1], v[0:1], v[4:5]
	v_pk_mul_f32 v[2:3], v[50:51], v[6:7]
	v_pk_mul_f32 v[4:5], v[46:47], v[12:13]
	v_pk_mul_f32 v[6:7], v[34:35], v[14:15]
	global_store_dwordx4 v[18:19], v[0:3], off
	s_nop 1
	global_store_dwordx4 v[18:19], v[4:7], off offset:16
	s_nop 1
	s_nop 0
	v_mul_f32_e32 v14, 0x45800000, v11
	v_cndmask_b32_e32 v14, v11, v14, vcc
	v_pk_mul_f32 v[16:17], v[88:89], v[14:15] op_sel_hi:[1,0]
	v_pk_mul_f32 v[18:19], v[84:85], v[14:15] op_sel_hi:[1,0]
	v_lshl_add_u64 v[12:13], s[4:5], 0, v[40:41]
	v_pk_mul_f32 v[34:35], v[90:91], v[14:15] op_sel_hi:[1,0]
	v_pk_mul_f32 v[46:47], v[86:87], v[14:15] op_sel_hi:[1,0]
	v_and_b32_e32 v11, s0, v23
	v_pk_mov_b32 v[10:11], v[26:27], v[10:11] op_sel:[1,0]
	v_mov_b32_e32 v0, v166
	v_mov_b32_e32 v1, v167
	v_mov_b32_e32 v2, v168
	v_mov_b32_e32 v3, v169
	v_mov_b32_e32 v4, v170
	v_mov_b32_e32 v5, v171
	v_mov_b32_e32 v6, v172
	v_mov_b32_e32 v7, v173
	v_pk_mul_f32 v[0:1], v[18:19], v[0:1]
	v_pk_mul_f32 v[2:3], v[16:17], v[2:3]
	v_pk_mul_f32 v[4:5], v[46:47], v[4:5]
	v_pk_mul_f32 v[6:7], v[34:35], v[6:7]
	global_store_dwordx4 v[12:13], v[0:3], off
	s_nop 1
	global_store_dwordx4 v[12:13], v[4:7], off offset:16
	s_nop 1
	s_nop 0
	v_pk_mul_f32 v[16:17], v[72:73], v[14:15] op_sel_hi:[1,0]
	v_pk_mul_f32 v[18:19], v[68:69], v[14:15] op_sel_hi:[1,0]
	v_pk_mul_f32 v[34:35], v[74:75], v[14:15] op_sel_hi:[1,0]
	v_pk_mul_f32 v[46:47], v[70:71], v[14:15] op_sel_hi:[1,0]
	v_pk_mul_f32 v[10:11], v[14:15], v[10:11] op_sel_hi:[0,1]
	v_mov_b32_e32 v0, v174
	v_mov_b32_e32 v1, v175
	v_mov_b32_e32 v2, v176
	v_mov_b32_e32 v3, v177
	v_mov_b32_e32 v4, v178
	v_mov_b32_e32 v5, v179
	v_mov_b32_e32 v6, v180
	v_mov_b32_e32 v7, v181
	v_pk_mul_f32 v[0:1], v[18:19], v[0:1]
	v_pk_mul_f32 v[2:3], v[16:17], v[2:3]
	v_pk_mul_f32 v[4:5], v[46:47], v[4:5]
	v_pk_mul_f32 v[6:7], v[34:35], v[6:7]
	global_store_dwordx4 v[12:13], v[0:3], off offset:2048
	s_nop 1
	global_store_dwordx4 v[12:13], v[4:7], off offset:2064
	s_nop 1
	s_nop 0
	v_pk_mul_f32 v[16:17], v[44:45], v[14:15] op_sel_hi:[1,0]
	v_pk_mul_f32 v[18:19], v[42:43], v[14:15] op_sel_hi:[1,0]
	v_lshl_add_u64 v[12:13], s[4:5], 0, v[32:33]
	v_pk_mul_f32 v[32:33], v[56:57], v[14:15] op_sel_hi:[1,0]
	v_pk_mul_f32 v[34:35], v[60:61], v[14:15] op_sel_hi:[1,0]
	v_mov_b32_e32 v0, v182
	v_mov_b32_e32 v1, v183
	v_mov_b32_e32 v2, v184
	v_mov_b32_e32 v3, v185
	v_mov_b32_e32 v4, v186
	v_mov_b32_e32 v5, v187
	v_mov_b32_e32 v6, v188
	v_mov_b32_e32 v7, v189
	v_pk_mul_f32 v[0:1], v[18:19], v[0:1]
	v_pk_mul_f32 v[2:3], v[16:17], v[2:3]
	v_pk_mul_f32 v[4:5], v[34:35], v[4:5]
	v_pk_mul_f32 v[6:7], v[32:33], v[6:7]
	global_store_dwordx4 v[12:13], v[0:3], off
	s_nop 1
	global_store_dwordx4 v[12:13], v[4:7], off offset:16
	s_nop 1
	s_nop 0
	v_pk_mov_b32 v[12:13], v[38:39], v[36:37] op_sel:[1,0]
	v_pk_mul_f32 v[16:17], v[20:21], v[14:15] op_sel_hi:[1,0]
	v_pk_mul_f32 v[18:19], v[24:25], v[14:15] op_sel_hi:[1,0]
	v_lshl_add_u64 v[8:9], s[4:5], 0, v[8:9]
	v_pk_mul_f32 v[12:13], v[14:15], v[12:13] op_sel_hi:[0,1]
	v_mov_b32_e32 v0, v190
	v_mov_b32_e32 v1, v191
	v_mov_b32_e32 v2, v192
	v_mov_b32_e32 v3, v193
	v_mov_b32_e32 v4, v200
	v_mov_b32_e32 v5, v201
	v_mov_b32_e32 v6, v202
	v_mov_b32_e32 v7, v203
	v_pk_mul_f32 v[0:1], v[18:19], v[0:1]
	v_pk_mul_f32 v[2:3], v[16:17], v[2:3]
	v_pk_mul_f32 v[4:5], v[10:11], v[4:5]
	v_pk_mul_f32 v[6:7], v[12:13], v[6:7]
	global_store_dwordx4 v[8:9], v[0:3], off
	s_nop 1
	global_store_dwordx4 v[8:9], v[4:7], off offset:16
	s_nop 1
.LBB0_1293:
	s_cmpk_lg_i32 s26, 0x100
	s_cbranch_scc1 .Lsrow_r3_orig
	s_add_i32 s93, s24, 0xffffe000
	s_and_b32 s97, s93, 7
	s_cmp_gt_u32 s97, 3
	s_cbranch_scc1 .LBB0_1307
	s_lshr_b32 s93, s93, 3
	s_lshl_b32 s93, s93, 2
	s_add_i32 s93, s93, s97
	s_add_i32 s32, s93, 0x2000
	s_waitcnt lgkmcnt(0)
	v_and_b32_e32 v195, 63, v164
	v_lshlrev_b32_e32 v162, 4, v195
	v_lshlrev_b32_e32 v163, 5, v195
	v_lshlrev_b32_e32 v243, 2, v195
	v_add_u32_e32 v194, 0x1000, v163
	s_lshl_b32 s97, s93, 12
	s_add_u32 s98, s34, s97
	s_addc_u32 s99, s35, 0
	s_add_u32 s98, s98, 0x19600000
	s_addc_u32 s99, s99, 0
	s_lshl_b32 s97, s32, 12
	s_add_u32 s94, s34, s97
	s_addc_u32 s95, s35, 0
	s_add_u32 s94, s94, 0x2aa00000
	s_addc_u32 s95, s95, 0
	global_load_dwordx4 v[222:225], v162, s[94:95] nt
	global_load_dwordx4 v[228:231], v162, s[94:95] offset:1024 nt
	global_load_dwordx4 v[232:235], v162, s[94:95] offset:2048 nt
	global_load_dwordx4 v[236:239], v162, s[94:95] offset:3072 nt
	global_load_dwordx4 v[150:153], v162, s[98:99] nt
	global_load_dwordx4 v[154:157], v162, s[98:99] offset:1024 nt
	global_load_dwordx4 v[158:161], v162, s[98:99] offset:2048 nt
	global_load_dwordx4 v[166:169], v162, s[98:99] offset:3072 nt
	s_add_u32 s98, s98, 0x400000
	s_addc_u32 s99, s99, 0
	global_load_dwordx4 v[170:173], v162, s[98:99] nt
	global_load_dwordx4 v[174:177], v162, s[98:99] offset:1024 nt
	global_load_dwordx4 v[178:181], v162, s[98:99] offset:2048 nt
	global_load_dwordx4 v[182:185], v162, s[98:99] offset:3072 nt
	s_add_u32 s98, s98, 0x400000
	s_addc_u32 s99, s99, 0
	global_load_dwordx4 v[186:189], v162, s[98:99] nt
	global_load_dwordx4 v[190:193], v162, s[98:99] offset:1024 nt
	global_load_dwordx4 v[198:201], v162, s[98:99] offset:2048 nt
	global_load_dwordx4 v[202:205], v162, s[98:99] offset:3072 nt
	s_add_u32 s98, s98, 0x400000
	s_addc_u32 s99, s99, 0
	global_load_dwordx4 v[206:209], v162, s[98:99] nt
	global_load_dwordx4 v[210:213], v162, s[98:99] offset:1024 nt
	global_load_dwordx4 v[214:217], v162, s[98:99] offset:2048 nt
	global_load_dwordx4 v[218:221], v162, s[98:99] offset:3072 nt
	s_add_u32 s98, s98, 0x400000
	s_addc_u32 s99, s99, 0
	s_waitcnt vmcnt(16)
	v_lshlrev_b32_e32 v118, 16, v222
	v_and_b32_e32 v119, 0xffff0000, v222
	v_lshlrev_b32_e32 v120, 16, v223
	v_and_b32_e32 v121, 0xffff0000, v223
	v_lshlrev_b32_e32 v122, 16, v224
	v_and_b32_e32 v123, 0xffff0000, v224
	v_lshlrev_b32_e32 v124, 16, v225
	v_and_b32_e32 v125, 0xffff0000, v225
	v_lshlrev_b32_e32 v126, 16, v228
	v_and_b32_e32 v127, 0xffff0000, v228
	v_lshlrev_b32_e32 v128, 16, v229
	v_and_b32_e32 v129, 0xffff0000, v229
	v_lshlrev_b32_e32 v130, 16, v230
	v_and_b32_e32 v131, 0xffff0000, v230
	v_lshlrev_b32_e32 v132, 16, v231
	v_and_b32_e32 v133, 0xffff0000, v231
	v_lshlrev_b32_e32 v134, 16, v232
	v_and_b32_e32 v135, 0xffff0000, v232
	v_lshlrev_b32_e32 v136, 16, v233
	v_and_b32_e32 v137, 0xffff0000, v233
	v_lshlrev_b32_e32 v138, 16, v234
	v_and_b32_e32 v139, 0xffff0000, v234
	v_lshlrev_b32_e32 v140, 16, v235
	v_and_b32_e32 v141, 0xffff0000, v235
	v_lshlrev_b32_e32 v142, 16, v236
	v_and_b32_e32 v143, 0xffff0000, v236
	v_lshlrev_b32_e32 v144, 16, v237
	v_and_b32_e32 v145, 0xffff0000, v237
	v_lshlrev_b32_e32 v146, 16, v238
	v_and_b32_e32 v147, 0xffff0000, v238
	v_lshlrev_b32_e32 v148, 16, v239
	v_and_b32_e32 v149, 0xffff0000, v239
	s_waitcnt vmcnt(12)
	v_lshlrev_b32_e32 v195, 16, v150
	v_and_b32_e32 v197, 0xffff0000, v150
	v_add_f32_e32 v118, v118, v195
	v_add_f32_e32 v119, v119, v197
	v_lshlrev_b32_e32 v195, 16, v151
	v_and_b32_e32 v197, 0xffff0000, v151
	v_add_f32_e32 v120, v120, v195
	v_add_f32_e32 v121, v121, v197
	v_lshlrev_b32_e32 v195, 16, v152
	v_and_b32_e32 v197, 0xffff0000, v152
	v_add_f32_e32 v122, v122, v195
	v_add_f32_e32 v123, v123, v197
	v_lshlrev_b32_e32 v195, 16, v153
	v_and_b32_e32 v197, 0xffff0000, v153
	v_add_f32_e32 v124, v124, v195
	v_add_f32_e32 v125, v125, v197
	v_lshlrev_b32_e32 v195, 16, v154
	v_and_b32_e32 v197, 0xffff0000, v154
	v_add_f32_e32 v126, v126, v195
	v_add_f32_e32 v127, v127, v197
	v_lshlrev_b32_e32 v195, 16, v155
	v_and_b32_e32 v197, 0xffff0000, v155
	v_add_f32_e32 v128, v128, v195
	v_add_f32_e32 v129, v129, v197
	v_lshlrev_b32_e32 v195, 16, v156
	v_and_b32_e32 v197, 0xffff0000, v156
	v_add_f32_e32 v130, v130, v195
	v_add_f32_e32 v131, v131, v197
	v_lshlrev_b32_e32 v195, 16, v157
	v_and_b32_e32 v197, 0xffff0000, v157
	v_add_f32_e32 v132, v132, v195
	v_add_f32_e32 v133, v133, v197
	v_lshlrev_b32_e32 v195, 16, v158
	v_and_b32_e32 v197, 0xffff0000, v158
	v_add_f32_e32 v134, v134, v195
	v_add_f32_e32 v135, v135, v197
	v_lshlrev_b32_e32 v195, 16, v159
	v_and_b32_e32 v197, 0xffff0000, v159
	v_add_f32_e32 v136, v136, v195
	v_add_f32_e32 v137, v137, v197
	v_lshlrev_b32_e32 v195, 16, v160
	v_and_b32_e32 v197, 0xffff0000, v160
	v_add_f32_e32 v138, v138, v195
	v_add_f32_e32 v139, v139, v197
	v_lshlrev_b32_e32 v195, 16, v161
	v_and_b32_e32 v197, 0xffff0000, v161
	v_add_f32_e32 v140, v140, v195
	v_add_f32_e32 v141, v141, v197
	v_lshlrev_b32_e32 v195, 16, v166
	v_and_b32_e32 v197, 0xffff0000, v166
	v_add_f32_e32 v142, v142, v195
	v_add_f32_e32 v143, v143, v197
	v_lshlrev_b32_e32 v195, 16, v167
	v_and_b32_e32 v197, 0xffff0000, v167
	v_add_f32_e32 v144, v144, v195
	v_add_f32_e32 v145, v145, v197
	v_lshlrev_b32_e32 v195, 16, v168
	v_and_b32_e32 v197, 0xffff0000, v168
	v_add_f32_e32 v146, v146, v195
	v_add_f32_e32 v147, v147, v197
	v_lshlrev_b32_e32 v195, 16, v169
	v_and_b32_e32 v197, 0xffff0000, v169
	v_add_f32_e32 v148, v148, v195
	v_add_f32_e32 v149, v149, v197
	global_load_dwordx4 v[150:153], v162, s[98:99] nt
	global_load_dwordx4 v[154:157], v162, s[98:99] offset:1024 nt
	global_load_dwordx4 v[158:161], v162, s[98:99] offset:2048 nt
	global_load_dwordx4 v[166:169], v162, s[98:99] offset:3072 nt
	s_add_u32 s98, s98, 0x400000
	s_addc_u32 s99, s99, 0
	s_waitcnt vmcnt(12)
	v_lshlrev_b32_e32 v195, 16, v170
	v_and_b32_e32 v197, 0xffff0000, v170
	v_add_f32_e32 v118, v118, v195
	v_add_f32_e32 v119, v119, v197
	v_lshlrev_b32_e32 v195, 16, v171
	v_and_b32_e32 v197, 0xffff0000, v171
	v_add_f32_e32 v120, v120, v195
	v_add_f32_e32 v121, v121, v197
	v_lshlrev_b32_e32 v195, 16, v172
	v_and_b32_e32 v197, 0xffff0000, v172
	v_add_f32_e32 v122, v122, v195
	v_add_f32_e32 v123, v123, v197
	v_lshlrev_b32_e32 v195, 16, v173
	v_and_b32_e32 v197, 0xffff0000, v173
	v_add_f32_e32 v124, v124, v195
	v_add_f32_e32 v125, v125, v197
	v_lshlrev_b32_e32 v195, 16, v174
	v_and_b32_e32 v197, 0xffff0000, v174
	v_add_f32_e32 v126, v126, v195
	v_add_f32_e32 v127, v127, v197
	v_lshlrev_b32_e32 v195, 16, v175
	v_and_b32_e32 v197, 0xffff0000, v175
	v_add_f32_e32 v128, v128, v195
	v_add_f32_e32 v129, v129, v197
	v_lshlrev_b32_e32 v195, 16, v176
	v_and_b32_e32 v197, 0xffff0000, v176
	v_add_f32_e32 v130, v130, v195
	v_add_f32_e32 v131, v131, v197
	v_lshlrev_b32_e32 v195, 16, v177
	v_and_b32_e32 v197, 0xffff0000, v177
	v_add_f32_e32 v132, v132, v195
	v_add_f32_e32 v133, v133, v197
	v_lshlrev_b32_e32 v195, 16, v178
	v_and_b32_e32 v197, 0xffff0000, v178
	v_add_f32_e32 v134, v134, v195
	v_add_f32_e32 v135, v135, v197
	v_lshlrev_b32_e32 v195, 16, v179
	v_and_b32_e32 v197, 0xffff0000, v179
	v_add_f32_e32 v136, v136, v195
	v_add_f32_e32 v137, v137, v197
	v_lshlrev_b32_e32 v195, 16, v180
	v_and_b32_e32 v197, 0xffff0000, v180
	v_add_f32_e32 v138, v138, v195
	v_add_f32_e32 v139, v139, v197
	v_lshlrev_b32_e32 v195, 16, v181
	v_and_b32_e32 v197, 0xffff0000, v181
	v_add_f32_e32 v140, v140, v195
	v_add_f32_e32 v141, v141, v197
	v_lshlrev_b32_e32 v195, 16, v182
	v_and_b32_e32 v197, 0xffff0000, v182
	v_add_f32_e32 v142, v142, v195
	v_add_f32_e32 v143, v143, v197
	v_lshlrev_b32_e32 v195, 16, v183
	v_and_b32_e32 v197, 0xffff0000, v183
	v_add_f32_e32 v144, v144, v195
	v_add_f32_e32 v145, v145, v197
	v_lshlrev_b32_e32 v195, 16, v184
	v_and_b32_e32 v197, 0xffff0000, v184
	v_add_f32_e32 v146, v146, v195
	v_add_f32_e32 v147, v147, v197
	v_lshlrev_b32_e32 v195, 16, v185
	v_and_b32_e32 v197, 0xffff0000, v185
	v_add_f32_e32 v148, v148, v195
	v_add_f32_e32 v149, v149, v197
	global_load_dwordx4 v[170:173], v162, s[98:99] nt
	global_load_dwordx4 v[174:177], v162, s[98:99] offset:1024 nt
	global_load_dwordx4 v[178:181], v162, s[98:99] offset:2048 nt
	global_load_dwordx4 v[182:185], v162, s[98:99] offset:3072 nt
	s_add_u32 s98, s98, 0x400000
	s_addc_u32 s99, s99, 0
	s_waitcnt vmcnt(12)
	v_lshlrev_b32_e32 v195, 16, v186
	v_and_b32_e32 v197, 0xffff0000, v186
	v_add_f32_e32 v118, v118, v195
	v_add_f32_e32 v119, v119, v197
	v_lshlrev_b32_e32 v195, 16, v187
	v_and_b32_e32 v197, 0xffff0000, v187
	v_add_f32_e32 v120, v120, v195
	v_add_f32_e32 v121, v121, v197
	v_lshlrev_b32_e32 v195, 16, v188
	v_and_b32_e32 v197, 0xffff0000, v188
	v_add_f32_e32 v122, v122, v195
	v_add_f32_e32 v123, v123, v197
	v_lshlrev_b32_e32 v195, 16, v189
	v_and_b32_e32 v197, 0xffff0000, v189
	v_add_f32_e32 v124, v124, v195
	v_add_f32_e32 v125, v125, v197
	v_lshlrev_b32_e32 v195, 16, v190
	v_and_b32_e32 v197, 0xffff0000, v190
	v_add_f32_e32 v126, v126, v195
	v_add_f32_e32 v127, v127, v197
	v_lshlrev_b32_e32 v195, 16, v191
	v_and_b32_e32 v197, 0xffff0000, v191
	v_add_f32_e32 v128, v128, v195
	v_add_f32_e32 v129, v129, v197
	v_lshlrev_b32_e32 v195, 16, v192
	v_and_b32_e32 v197, 0xffff0000, v192
	v_add_f32_e32 v130, v130, v195
	v_add_f32_e32 v131, v131, v197
	v_lshlrev_b32_e32 v195, 16, v193
	v_and_b32_e32 v197, 0xffff0000, v193
	v_add_f32_e32 v132, v132, v195
	v_add_f32_e32 v133, v133, v197
	v_lshlrev_b32_e32 v195, 16, v198
	v_and_b32_e32 v197, 0xffff0000, v198
	v_add_f32_e32 v134, v134, v195
	v_add_f32_e32 v135, v135, v197
	v_lshlrev_b32_e32 v195, 16, v199
	v_and_b32_e32 v197, 0xffff0000, v199
	v_add_f32_e32 v136, v136, v195
	v_add_f32_e32 v137, v137, v197
	v_lshlrev_b32_e32 v195, 16, v200
	v_and_b32_e32 v197, 0xffff0000, v200
	v_add_f32_e32 v138, v138, v195
	v_add_f32_e32 v139, v139, v197
	v_lshlrev_b32_e32 v195, 16, v201
	v_and_b32_e32 v197, 0xffff0000, v201
	v_add_f32_e32 v140, v140, v195
	v_add_f32_e32 v141, v141, v197
	v_lshlrev_b32_e32 v195, 16, v202
	v_and_b32_e32 v197, 0xffff0000, v202
	v_add_f32_e32 v142, v142, v195
	v_add_f32_e32 v143, v143, v197
	v_lshlrev_b32_e32 v195, 16, v203
	v_and_b32_e32 v197, 0xffff0000, v203
	v_add_f32_e32 v144, v144, v195
	v_add_f32_e32 v145, v145, v197
	v_lshlrev_b32_e32 v195, 16, v204
	v_and_b32_e32 v197, 0xffff0000, v204
	v_add_f32_e32 v146, v146, v195
	v_add_f32_e32 v147, v147, v197
	v_lshlrev_b32_e32 v195, 16, v205
	v_and_b32_e32 v197, 0xffff0000, v205
	v_add_f32_e32 v148, v148, v195
	v_add_f32_e32 v149, v149, v197
	global_load_dwordx4 v[186:189], v162, s[98:99] nt
	global_load_dwordx4 v[190:193], v162, s[98:99] offset:1024 nt
	global_load_dwordx4 v[198:201], v162, s[98:99] offset:2048 nt
	global_load_dwordx4 v[202:205], v162, s[98:99] offset:3072 nt
	s_add_u32 s98, s98, 0x400000
	s_addc_u32 s99, s99, 0
	s_waitcnt vmcnt(12)
	v_lshlrev_b32_e32 v195, 16, v206
	v_and_b32_e32 v197, 0xffff0000, v206
	v_add_f32_e32 v118, v118, v195
	v_add_f32_e32 v119, v119, v197
	v_lshlrev_b32_e32 v195, 16, v207
	v_and_b32_e32 v197, 0xffff0000, v207
	v_add_f32_e32 v120, v120, v195
	v_add_f32_e32 v121, v121, v197
	v_lshlrev_b32_e32 v195, 16, v208
	v_and_b32_e32 v197, 0xffff0000, v208
	v_add_f32_e32 v122, v122, v195
	v_add_f32_e32 v123, v123, v197
	v_lshlrev_b32_e32 v195, 16, v209
	v_and_b32_e32 v197, 0xffff0000, v209
	v_add_f32_e32 v124, v124, v195
	v_add_f32_e32 v125, v125, v197
	v_lshlrev_b32_e32 v195, 16, v210
	v_and_b32_e32 v197, 0xffff0000, v210
	v_add_f32_e32 v126, v126, v195
	v_add_f32_e32 v127, v127, v197
	v_lshlrev_b32_e32 v195, 16, v211
	v_and_b32_e32 v197, 0xffff0000, v211
	v_add_f32_e32 v128, v128, v195
	v_add_f32_e32 v129, v129, v197
	v_lshlrev_b32_e32 v195, 16, v212
	v_and_b32_e32 v197, 0xffff0000, v212
	v_add_f32_e32 v130, v130, v195
	v_add_f32_e32 v131, v131, v197
	v_lshlrev_b32_e32 v195, 16, v213
	v_and_b32_e32 v197, 0xffff0000, v213
	v_add_f32_e32 v132, v132, v195
	v_add_f32_e32 v133, v133, v197
	v_lshlrev_b32_e32 v195, 16, v214
	v_and_b32_e32 v197, 0xffff0000, v214
	v_add_f32_e32 v134, v134, v195
	v_add_f32_e32 v135, v135, v197
	v_lshlrev_b32_e32 v195, 16, v215
	v_and_b32_e32 v197, 0xffff0000, v215
	v_add_f32_e32 v136, v136, v195
	v_add_f32_e32 v137, v137, v197
	v_lshlrev_b32_e32 v195, 16, v216
	v_and_b32_e32 v197, 0xffff0000, v216
	v_add_f32_e32 v138, v138, v195
	v_add_f32_e32 v139, v139, v197
	v_lshlrev_b32_e32 v195, 16, v217
	v_and_b32_e32 v197, 0xffff0000, v217
	v_add_f32_e32 v140, v140, v195
	v_add_f32_e32 v141, v141, v197
	v_lshlrev_b32_e32 v195, 16, v218
	v_and_b32_e32 v197, 0xffff0000, v218
	v_add_f32_e32 v142, v142, v195
	v_add_f32_e32 v143, v143, v197
	v_lshlrev_b32_e32 v195, 16, v219
	v_and_b32_e32 v197, 0xffff0000, v219
	v_add_f32_e32 v144, v144, v195
	v_add_f32_e32 v145, v145, v197
	v_lshlrev_b32_e32 v195, 16, v220
	v_and_b32_e32 v197, 0xffff0000, v220
	v_add_f32_e32 v146, v146, v195
	v_add_f32_e32 v147, v147, v197
	v_lshlrev_b32_e32 v195, 16, v221
	v_and_b32_e32 v197, 0xffff0000, v221
	v_add_f32_e32 v148, v148, v195
	v_add_f32_e32 v149, v149, v197
	global_load_dwordx4 v[206:209], v162, s[98:99] nt
	global_load_dwordx4 v[210:213], v162, s[98:99] offset:1024 nt
	global_load_dwordx4 v[214:217], v162, s[98:99] offset:2048 nt
	global_load_dwordx4 v[218:221], v162, s[98:99] offset:3072 nt
	s_add_u32 s98, s98, 0x400000
	s_addc_u32 s99, s99, 0
	s_waitcnt vmcnt(12)
	v_lshlrev_b32_e32 v195, 16, v150
	v_and_b32_e32 v197, 0xffff0000, v150
	v_add_f32_e32 v118, v118, v195
	v_add_f32_e32 v119, v119, v197
	v_lshlrev_b32_e32 v195, 16, v151
	v_and_b32_e32 v197, 0xffff0000, v151
	v_add_f32_e32 v120, v120, v195
	v_add_f32_e32 v121, v121, v197
	v_lshlrev_b32_e32 v195, 16, v152
	v_and_b32_e32 v197, 0xffff0000, v152
	v_add_f32_e32 v122, v122, v195
	v_add_f32_e32 v123, v123, v197
	v_lshlrev_b32_e32 v195, 16, v153
	v_and_b32_e32 v197, 0xffff0000, v153
	v_add_f32_e32 v124, v124, v195
	v_add_f32_e32 v125, v125, v197
	v_lshlrev_b32_e32 v195, 16, v154
	v_and_b32_e32 v197, 0xffff0000, v154
	v_add_f32_e32 v126, v126, v195
	v_add_f32_e32 v127, v127, v197
	v_lshlrev_b32_e32 v195, 16, v155
	v_and_b32_e32 v197, 0xffff0000, v155
	v_add_f32_e32 v128, v128, v195
	v_add_f32_e32 v129, v129, v197
	v_lshlrev_b32_e32 v195, 16, v156
	v_and_b32_e32 v197, 0xffff0000, v156
	v_add_f32_e32 v130, v130, v195
	v_add_f32_e32 v131, v131, v197
	v_lshlrev_b32_e32 v195, 16, v157
	v_and_b32_e32 v197, 0xffff0000, v157
	v_add_f32_e32 v132, v132, v195
	v_add_f32_e32 v133, v133, v197
	v_lshlrev_b32_e32 v195, 16, v158
	v_and_b32_e32 v197, 0xffff0000, v158
	v_add_f32_e32 v134, v134, v195
	v_add_f32_e32 v135, v135, v197
	v_lshlrev_b32_e32 v195, 16, v159
	v_and_b32_e32 v197, 0xffff0000, v159
	v_add_f32_e32 v136, v136, v195
	v_add_f32_e32 v137, v137, v197
	v_lshlrev_b32_e32 v195, 16, v160
	v_and_b32_e32 v197, 0xffff0000, v160
	v_add_f32_e32 v138, v138, v195
	v_add_f32_e32 v139, v139, v197
	v_lshlrev_b32_e32 v195, 16, v161
	v_and_b32_e32 v197, 0xffff0000, v161
	v_add_f32_e32 v140, v140, v195
	v_add_f32_e32 v141, v141, v197
	v_lshlrev_b32_e32 v195, 16, v166
	v_and_b32_e32 v197, 0xffff0000, v166
	v_add_f32_e32 v142, v142, v195
	v_add_f32_e32 v143, v143, v197
	v_lshlrev_b32_e32 v195, 16, v167
	v_and_b32_e32 v197, 0xffff0000, v167
	v_add_f32_e32 v144, v144, v195
	v_add_f32_e32 v145, v145, v197
	v_lshlrev_b32_e32 v195, 16, v168
	v_and_b32_e32 v197, 0xffff0000, v168
	v_add_f32_e32 v146, v146, v195
	v_add_f32_e32 v147, v147, v197
	v_lshlrev_b32_e32 v195, 16, v169
	v_and_b32_e32 v197, 0xffff0000, v169
	v_add_f32_e32 v148, v148, v195
	v_add_f32_e32 v149, v149, v197
	global_load_dwordx4 v[150:153], v163, s[0:1]
	global_load_dwordx4 v[154:157], v163, s[0:1] offset:16
	global_load_dwordx4 v[158:161], v163, s[0:1] offset:2048
	global_load_dwordx4 v[166:169], v163, s[0:1] offset:2064
	s_waitcnt vmcnt(12)
	v_lshlrev_b32_e32 v195, 16, v170
	v_and_b32_e32 v197, 0xffff0000, v170
	v_add_f32_e32 v118, v118, v195
	v_add_f32_e32 v119, v119, v197
	v_lshlrev_b32_e32 v195, 16, v171
	v_and_b32_e32 v197, 0xffff0000, v171
	v_add_f32_e32 v120, v120, v195
	v_add_f32_e32 v121, v121, v197
	v_lshlrev_b32_e32 v195, 16, v172
	v_and_b32_e32 v197, 0xffff0000, v172
	v_add_f32_e32 v122, v122, v195
	v_add_f32_e32 v123, v123, v197
	v_lshlrev_b32_e32 v195, 16, v173
	v_and_b32_e32 v197, 0xffff0000, v173
	v_add_f32_e32 v124, v124, v195
	v_add_f32_e32 v125, v125, v197
	v_lshlrev_b32_e32 v195, 16, v174
	v_and_b32_e32 v197, 0xffff0000, v174
	v_add_f32_e32 v126, v126, v195
	v_add_f32_e32 v127, v127, v197
	v_lshlrev_b32_e32 v195, 16, v175
	v_and_b32_e32 v197, 0xffff0000, v175
	v_add_f32_e32 v128, v128, v195
	v_add_f32_e32 v129, v129, v197
	v_lshlrev_b32_e32 v195, 16, v176
	v_and_b32_e32 v197, 0xffff0000, v176
	v_add_f32_e32 v130, v130, v195
	v_add_f32_e32 v131, v131, v197
	v_lshlrev_b32_e32 v195, 16, v177
	v_and_b32_e32 v197, 0xffff0000, v177
	v_add_f32_e32 v132, v132, v195
	v_add_f32_e32 v133, v133, v197
	v_lshlrev_b32_e32 v195, 16, v178
	v_and_b32_e32 v197, 0xffff0000, v178
	v_add_f32_e32 v134, v134, v195
	v_add_f32_e32 v135, v135, v197
	v_lshlrev_b32_e32 v195, 16, v179
	v_and_b32_e32 v197, 0xffff0000, v179
	v_add_f32_e32 v136, v136, v195
	v_add_f32_e32 v137, v137, v197
	v_lshlrev_b32_e32 v195, 16, v180
	v_and_b32_e32 v197, 0xffff0000, v180
	v_add_f32_e32 v138, v138, v195
	v_add_f32_e32 v139, v139, v197
	v_lshlrev_b32_e32 v195, 16, v181
	v_and_b32_e32 v197, 0xffff0000, v181
	v_add_f32_e32 v140, v140, v195
	v_add_f32_e32 v141, v141, v197
	v_lshlrev_b32_e32 v195, 16, v182
	v_and_b32_e32 v197, 0xffff0000, v182
	v_add_f32_e32 v142, v142, v195
	v_add_f32_e32 v143, v143, v197
	v_lshlrev_b32_e32 v195, 16, v183
	v_and_b32_e32 v197, 0xffff0000, v183
	v_add_f32_e32 v144, v144, v195
	v_add_f32_e32 v145, v145, v197
	v_lshlrev_b32_e32 v195, 16, v184
	v_and_b32_e32 v197, 0xffff0000, v184
	v_add_f32_e32 v146, v146, v195
	v_add_f32_e32 v147, v147, v197
	v_lshlrev_b32_e32 v195, 16, v185
	v_and_b32_e32 v197, 0xffff0000, v185
	v_add_f32_e32 v148, v148, v195
	v_add_f32_e32 v149, v149, v197
	global_load_dwordx4 v[170:173], v194, s[0:1]
	global_load_dwordx4 v[174:177], v194, s[0:1] offset:16
	global_load_dwordx4 v[178:181], v194, s[0:1] offset:2048
	global_load_dwordx4 v[182:185], v194, s[0:1] offset:2064
	s_waitcnt vmcnt(12)
	v_lshlrev_b32_e32 v195, 16, v186
	v_and_b32_e32 v197, 0xffff0000, v186
	v_add_f32_e32 v118, v118, v195
	v_add_f32_e32 v119, v119, v197
	v_lshlrev_b32_e32 v195, 16, v187
	v_and_b32_e32 v197, 0xffff0000, v187
	v_add_f32_e32 v120, v120, v195
	v_add_f32_e32 v121, v121, v197
	v_lshlrev_b32_e32 v195, 16, v188
	v_and_b32_e32 v197, 0xffff0000, v188
	v_add_f32_e32 v122, v122, v195
	v_add_f32_e32 v123, v123, v197
	v_lshlrev_b32_e32 v195, 16, v189
	v_and_b32_e32 v197, 0xffff0000, v189
	v_add_f32_e32 v124, v124, v195
	v_add_f32_e32 v125, v125, v197
	v_lshlrev_b32_e32 v195, 16, v190
	v_and_b32_e32 v197, 0xffff0000, v190
	v_add_f32_e32 v126, v126, v195
	v_add_f32_e32 v127, v127, v197
	v_lshlrev_b32_e32 v195, 16, v191
	v_and_b32_e32 v197, 0xffff0000, v191
	v_add_f32_e32 v128, v128, v195
	v_add_f32_e32 v129, v129, v197
	v_lshlrev_b32_e32 v195, 16, v192
	v_and_b32_e32 v197, 0xffff0000, v192
	v_add_f32_e32 v130, v130, v195
	v_add_f32_e32 v131, v131, v197
	v_lshlrev_b32_e32 v195, 16, v193
	v_and_b32_e32 v197, 0xffff0000, v193
	v_add_f32_e32 v132, v132, v195
	v_add_f32_e32 v133, v133, v197
	v_lshlrev_b32_e32 v195, 16, v198
	v_and_b32_e32 v197, 0xffff0000, v198
	v_add_f32_e32 v134, v134, v195
	v_add_f32_e32 v135, v135, v197
	v_lshlrev_b32_e32 v195, 16, v199
	v_and_b32_e32 v197, 0xffff0000, v199
	v_add_f32_e32 v136, v136, v195
	v_add_f32_e32 v137, v137, v197
	v_lshlrev_b32_e32 v195, 16, v200
	v_and_b32_e32 v197, 0xffff0000, v200
	v_add_f32_e32 v138, v138, v195
	v_add_f32_e32 v139, v139, v197
	v_lshlrev_b32_e32 v195, 16, v201
	v_and_b32_e32 v197, 0xffff0000, v201
	v_add_f32_e32 v140, v140, v195
	v_add_f32_e32 v141, v141, v197
	v_lshlrev_b32_e32 v195, 16, v202
	v_and_b32_e32 v197, 0xffff0000, v202
	v_add_f32_e32 v142, v142, v195
	v_add_f32_e32 v143, v143, v197
	v_lshlrev_b32_e32 v195, 16, v203
	v_and_b32_e32 v197, 0xffff0000, v203
	v_add_f32_e32 v144, v144, v195
	v_add_f32_e32 v145, v145, v197
	v_lshlrev_b32_e32 v195, 16, v204
	v_and_b32_e32 v197, 0xffff0000, v204
	v_add_f32_e32 v146, v146, v195
	v_add_f32_e32 v147, v147, v197
	v_lshlrev_b32_e32 v195, 16, v205
	v_and_b32_e32 v197, 0xffff0000, v205
	v_add_f32_e32 v148, v148, v195
	v_add_f32_e32 v149, v149, v197
	s_waitcnt vmcnt(8)
	v_lshlrev_b32_e32 v195, 16, v206
	v_and_b32_e32 v197, 0xffff0000, v206
	v_add_f32_e32 v118, v118, v195
	v_add_f32_e32 v119, v119, v197
	v_lshlrev_b32_e32 v195, 16, v207
	v_and_b32_e32 v197, 0xffff0000, v207
	v_add_f32_e32 v120, v120, v195
	v_add_f32_e32 v121, v121, v197
	v_lshlrev_b32_e32 v195, 16, v208
	v_and_b32_e32 v197, 0xffff0000, v208
	v_add_f32_e32 v122, v122, v195
	v_add_f32_e32 v123, v123, v197
	v_lshlrev_b32_e32 v195, 16, v209
	v_and_b32_e32 v197, 0xffff0000, v209
	v_add_f32_e32 v124, v124, v195
	v_add_f32_e32 v125, v125, v197
	v_lshlrev_b32_e32 v195, 16, v210
	v_and_b32_e32 v197, 0xffff0000, v210
	v_add_f32_e32 v126, v126, v195
	v_add_f32_e32 v127, v127, v197
	v_lshlrev_b32_e32 v195, 16, v211
	v_and_b32_e32 v197, 0xffff0000, v211
	v_add_f32_e32 v128, v128, v195
	v_add_f32_e32 v129, v129, v197
	v_lshlrev_b32_e32 v195, 16, v212
	v_and_b32_e32 v197, 0xffff0000, v212
	v_add_f32_e32 v130, v130, v195
	v_add_f32_e32 v131, v131, v197
	v_lshlrev_b32_e32 v195, 16, v213
	v_and_b32_e32 v197, 0xffff0000, v213
	v_add_f32_e32 v132, v132, v195
	v_add_f32_e32 v133, v133, v197
	v_lshlrev_b32_e32 v195, 16, v214
	v_and_b32_e32 v197, 0xffff0000, v214
	v_add_f32_e32 v134, v134, v195
	v_add_f32_e32 v135, v135, v197
	v_lshlrev_b32_e32 v195, 16, v215
	v_and_b32_e32 v197, 0xffff0000, v215
	v_add_f32_e32 v136, v136, v195
	v_add_f32_e32 v137, v137, v197
	v_lshlrev_b32_e32 v195, 16, v216
	v_and_b32_e32 v197, 0xffff0000, v216
	v_add_f32_e32 v138, v138, v195
	v_add_f32_e32 v139, v139, v197
	v_lshlrev_b32_e32 v195, 16, v217
	v_and_b32_e32 v197, 0xffff0000, v217
	v_add_f32_e32 v140, v140, v195
	v_add_f32_e32 v141, v141, v197
	v_lshlrev_b32_e32 v195, 16, v218
	v_and_b32_e32 v197, 0xffff0000, v218
	v_add_f32_e32 v142, v142, v195
	v_add_f32_e32 v143, v143, v197
	v_lshlrev_b32_e32 v195, 16, v219
	v_and_b32_e32 v197, 0xffff0000, v219
	v_add_f32_e32 v144, v144, v195
	v_add_f32_e32 v145, v145, v197
	v_lshlrev_b32_e32 v195, 16, v220
	v_and_b32_e32 v197, 0xffff0000, v220
	v_add_f32_e32 v146, v146, v195
	v_add_f32_e32 v147, v147, v197
	v_lshlrev_b32_e32 v195, 16, v221
	v_and_b32_e32 v197, 0xffff0000, v221
	v_add_f32_e32 v148, v148, v195
	v_add_f32_e32 v149, v149, v197
	v_mul_f32_e32 v227, v118, v118
	v_fmac_f32_e32 v227, v119, v119
	v_fmac_f32_e32 v227, v120, v120
	v_fmac_f32_e32 v227, v121, v121
	v_fmac_f32_e32 v227, v122, v122
	v_fmac_f32_e32 v227, v123, v123
	v_fmac_f32_e32 v227, v124, v124
	v_fmac_f32_e32 v227, v125, v125
	v_fmac_f32_e32 v227, v126, v126
	v_fmac_f32_e32 v227, v127, v127
	v_fmac_f32_e32 v227, v128, v128
	v_fmac_f32_e32 v227, v129, v129
	v_fmac_f32_e32 v227, v130, v130
	v_fmac_f32_e32 v227, v131, v131
	v_fmac_f32_e32 v227, v132, v132
	v_fmac_f32_e32 v227, v133, v133
	v_fmac_f32_e32 v227, v134, v134
	v_fmac_f32_e32 v227, v135, v135
	v_fmac_f32_e32 v227, v136, v136
	v_fmac_f32_e32 v227, v137, v137
	v_fmac_f32_e32 v227, v138, v138
	v_fmac_f32_e32 v227, v139, v139
	v_fmac_f32_e32 v227, v140, v140
	v_fmac_f32_e32 v227, v141, v141
	v_fmac_f32_e32 v227, v142, v142
	v_fmac_f32_e32 v227, v143, v143
	v_fmac_f32_e32 v227, v144, v144
	v_fmac_f32_e32 v227, v145, v145
	v_fmac_f32_e32 v227, v146, v146
	v_fmac_f32_e32 v227, v147, v147
	v_fmac_f32_e32 v227, v148, v148
	v_fmac_f32_e32 v227, v149, v149
	v_xor_b32_e32 v195, 4, v243
	ds_bpermute_b32 v242, v195, v227
	s_waitcnt lgkmcnt(0)
	v_add_f32_e32 v227, v227, v242
	v_xor_b32_e32 v195, 8, v243
	ds_bpermute_b32 v242, v195, v227
	s_waitcnt lgkmcnt(0)
	v_add_f32_e32 v227, v227, v242
	v_xor_b32_e32 v195, 16, v243
	ds_bpermute_b32 v242, v195, v227
	s_waitcnt lgkmcnt(0)
	v_add_f32_e32 v227, v227, v242
	v_xor_b32_e32 v195, 32, v243
	ds_bpermute_b32 v242, v195, v227
	s_waitcnt lgkmcnt(0)
	v_add_f32_e32 v227, v227, v242
	v_xor_b32_e32 v195, 64, v243
	ds_bpermute_b32 v242, v195, v227
	s_waitcnt lgkmcnt(0)
	v_add_f32_e32 v227, v227, v242
	v_xor_b32_e32 v195, 128, v243
	ds_bpermute_b32 v242, v195, v227
	s_waitcnt lgkmcnt(0)
	v_add_f32_e32 v227, v227, v242
	v_mov_b32_e32 v240, 0x3a000000
	v_mov_b32_e32 v241, 0x358637bd
	v_fma_f32 v227, v227, v240, v241
	v_rsq_f32_e32 v227, v227
	s_lshl_b32 s97, s32, 13
	s_add_u32 s100, s20, s97
	s_addc_u32 s101, s21, 0
	s_waitcnt vmcnt(0)
	v_mul_f32_e32 v118, v118, v227
	v_mul_f32_e32 v118, v118, v150
	v_mul_f32_e32 v119, v119, v227
	v_mul_f32_e32 v119, v119, v151
	v_mul_f32_e32 v120, v120, v227
	v_mul_f32_e32 v120, v120, v152
	v_mul_f32_e32 v121, v121, v227
	v_mul_f32_e32 v121, v121, v153
	v_mul_f32_e32 v122, v122, v227
	v_mul_f32_e32 v122, v122, v154
	v_mul_f32_e32 v123, v123, v227
	v_mul_f32_e32 v123, v123, v155
	v_mul_f32_e32 v124, v124, v227
	v_mul_f32_e32 v124, v124, v156
	v_mul_f32_e32 v125, v125, v227
	v_mul_f32_e32 v125, v125, v157
	v_mul_f32_e32 v126, v126, v227
	v_mul_f32_e32 v126, v126, v158
	v_mul_f32_e32 v127, v127, v227
	v_mul_f32_e32 v127, v127, v159
	v_mul_f32_e32 v128, v128, v227
	v_mul_f32_e32 v128, v128, v160
	v_mul_f32_e32 v129, v129, v227
	v_mul_f32_e32 v129, v129, v161
	v_mul_f32_e32 v130, v130, v227
	v_mul_f32_e32 v130, v130, v166
	v_mul_f32_e32 v131, v131, v227
	v_mul_f32_e32 v131, v131, v167
	v_mul_f32_e32 v132, v132, v227
	v_mul_f32_e32 v132, v132, v168
	v_mul_f32_e32 v133, v133, v227
	v_mul_f32_e32 v133, v133, v169
	v_mul_f32_e32 v134, v134, v227
	v_mul_f32_e32 v134, v134, v170
	v_mul_f32_e32 v135, v135, v227
	v_mul_f32_e32 v135, v135, v171
	v_mul_f32_e32 v136, v136, v227
	v_mul_f32_e32 v136, v136, v172
	v_mul_f32_e32 v137, v137, v227
	v_mul_f32_e32 v137, v137, v173
	v_mul_f32_e32 v138, v138, v227
	v_mul_f32_e32 v138, v138, v174
	v_mul_f32_e32 v139, v139, v227
	v_mul_f32_e32 v139, v139, v175
	v_mul_f32_e32 v140, v140, v227
	v_mul_f32_e32 v140, v140, v176
	v_mul_f32_e32 v141, v141, v227
	v_mul_f32_e32 v141, v141, v177
	v_mul_f32_e32 v142, v142, v227
	v_mul_f32_e32 v142, v142, v178
	v_mul_f32_e32 v143, v143, v227
	v_mul_f32_e32 v143, v143, v179
	v_mul_f32_e32 v144, v144, v227
	v_mul_f32_e32 v144, v144, v180
	v_mul_f32_e32 v145, v145, v227
	v_mul_f32_e32 v145, v145, v181
	v_mul_f32_e32 v146, v146, v227
	v_mul_f32_e32 v146, v146, v182
	v_mul_f32_e32 v147, v147, v227
	v_mul_f32_e32 v147, v147, v183
	v_mul_f32_e32 v148, v148, v227
	v_mul_f32_e32 v148, v148, v184
	v_mul_f32_e32 v149, v149, v227
	v_mul_f32_e32 v149, v149, v185
	global_store_dwordx4 v163, v[118:121], s[100:101]
	global_store_dwordx4 v163, v[122:125], s[100:101] offset:16
	global_store_dwordx4 v163, v[126:129], s[100:101] offset:2048
	global_store_dwordx4 v163, v[130:133], s[100:101] offset:2064
	global_store_dwordx4 v194, v[134:137], s[100:101]
	global_store_dwordx4 v194, v[138:141], s[100:101] offset:16
	global_store_dwordx4 v194, v[142:145], s[100:101] offset:2048
	global_store_dwordx4 v194, v[146:149], s[100:101] offset:2064
	s_branch .LBB0_1307
